# GEMM main loops: SP1 load segments issue the A-fragment LDS reads first (ahead of the scalar bookkeeping and B-address VALU)
# speedup vs baseline: 1.0101x; 1.0048x over previous
; #define PG8_STAGE(bufoff, gbase, voff) do { _Pragma("unroll") for (int _i = 0; _i < 2; ++_i) \
;         __builtin_amdgcn_global_load_lds((const unsigned*)((const char*)(gbase) + (voff)[_i]), (LAS unsigned*)(lds + (bufoff) + ldsw + _i * 8192), 16, 0, 0); } while (0)
; #define PG8_LDA(dst, b, h) do { _Pragma("unroll") for (int m = 0; m < 4; ++m) _Pragma("unroll") for (int k = 0; k < 2; ++k) dst[m][k] = *(const LAS bf16x8*)(lds + PG8_SA(b, h) + aoff + m * 2048 + k * 1024); } while (0)
; #define PG8_LDB(dst, b, h) do { _Pragma("unroll") for (int n = 0; n < 2; ++n) _Pragma("unroll") for (int k = 0; k < 2; ++k) dst[n][k] = *(const LAS bf16x8*)(lds + PG8_SB(b, h) + boff + n * 2048 + k * 1024); } while (0)
; #define PG8_MMA(ai, bj, At, Bt) do { __builtin_amdgcn_s_setprio(1); _Pragma("unroll") for (int m = 0; m < 4; ++m) _Pragma("unroll") for (int n = 0; n < 2; ++n) _Pragma("unroll") for (int k = 0; k < 2; ++k) \
;         acc[ai][bj][m][n] = __builtin_amdgcn_mfma_f32_16x16x32_bf16(Bt[n][k], At[m][k], acc[ai][bj][m][n], 0, 0, 0); __builtin_amdgcn_s_setprio(0); } while (0)
; #define PG8_WAIT_V(n) asm volatile("s_waitcnt vmcnt(" #n ")" ::: "memory")
; #define PG8_WAIT_L(n) asm volatile("s_waitcnt lgkmcnt(" #n ")" ::: "memory")
; #define PG8_BAR __builtin_amdgcn_s_barrier()
; #define PG8_SCHED __builtin_amdgcn_sched_barrier(0)
; template <class Epi, class Sched, int LDA, int LDB, bool ALIGN_EPI = true>
; __device__ __forceinline__ void gemm_phase(LAS unsigned char* lds, const Gemm g, const Sched& S, const Epi& E, int wave) {
;     ...
;             const bool last = (t == nt - 2);
;             const char* a1 = cA + (size_t)(t + 1) * kstep;
;             const char* a2 = last ? nA : cA + (size_t)(t + 2) * kstep; const char* b2 = last ? nB : cB + (size_t)(t + 2) * kstep;
;             const char* a3 = a2 + kstep; const char* b3 = b2 + kstep;
;             PG8_LDB(B0, 0, 0); PG8_LDB(B1, 0, 1); PG8_SCHED; PG8_LDA(At, 0, 0); PG8_STAGE(PG8_SA(1, 1), a1 + hstepA, voffA);
;             PG8_WAIT_V(8); PG8_WAIT_L(0); PG8_BAR; PG8_MMA(0, 0, At, B0); PG8_MMA(0, 1, At, B1); PG8_BAR; PG8_SCHED;
;             PG8_LDA(At, 0, 1); PG8_STAGE(PG8_SB(0, 0), b2, voffB); PG8_STAGE(PG8_SB(0, 1), b2 + hstepB, voffB); PG8_STAGE(PG8_SA(0, 0), a2, voffA);
;             PG8_WAIT_V(8); PG8_WAIT_L(0); PG8_BAR; PG8_MMA(1, 0, At, B0); PG8_MMA(1, 1, At, B1); PG8_BAR; PG8_SCHED;
.LBB0_485:
	ds_read_b128 v[184:187], v145
	ds_read_b128 v[188:191], v145 offset:1024
	ds_read_b128 v[192:195], v145 offset:2048
	ds_read_b128 v[196:199], v145 offset:3072
	ds_read_b128 v[200:203], v145 offset:4096
	ds_read_b128 v[204:207], v145 offset:5120
	ds_read_b128 v[208:211], v145 offset:6144
	ds_read_b128 v[212:215], v145 offset:7168
	s_add_u32 s24, s18, 0x100
	s_addc_u32 s25, s19, 0
	s_add_i32 s54, 0, 0x10000
	s_cmp_eq_u32 s53, 28
	s_cselect_b32 s35, s3, s25
	s_cselect_b32 s34, s2, s24
	v_add_u32_e32 v140, s54, v143
	s_cselect_b32 s29, s1, s45
	s_cselect_b32 s28, s17, s44
	s_add_i32 s55, 0, 0x14000
	ds_read_b128 v[146:149], v140
	ds_read_b128 v[150:153], v140 offset:1024
	ds_read_b128 v[154:157], v140 offset:2048
	ds_read_b128 v[158:161], v140 offset:3072
	v_add_u32_e32 v140, s55, v143
	ds_read_b128 v[162:165], v140
	ds_read_b128 v[166:169], v140 offset:1024
	ds_read_b128 v[170:173], v140 offset:2048
	ds_read_b128 v[180:183], v140 offset:3072
	v_lshl_add_u64 v[140:141], s[18:19], 0, v[136:137]
	s_add_i32 m0, s38, 0xc000
	s_nop 0
	global_load_lds_dwordx4 v[140:141], off
	v_lshl_add_u64 v[140:141], s[18:19], 0, v[138:139]
	s_add_i32 m0, s38, 0xe000
	s_nop 0
	global_load_lds_dwordx4 v[140:141], off
	s_waitcnt vmcnt(8)
	s_waitcnt lgkmcnt(0)
	s_setprio 1
	s_barrier
	v_mfma_f32_16x16x32_bf16 v[126:129], v[146:149], v[184:187], v[126:129]
	v_mfma_f32_16x16x32_bf16 v[118:121], v[154:157], v[184:187], v[118:121]
	v_mfma_f32_16x16x32_bf16 v[110:113], v[146:149], v[192:195], v[110:113]
	v_mfma_f32_16x16x32_bf16 v[102:105], v[154:157], v[192:195], v[102:105]
	v_mfma_f32_16x16x32_bf16 v[94:97], v[146:149], v[200:203], v[94:97]
	v_mfma_f32_16x16x32_bf16 v[86:89], v[154:157], v[200:203], v[86:89]
	v_mfma_f32_16x16x32_bf16 v[78:81], v[146:149], v[208:211], v[78:81]
	v_mfma_f32_16x16x32_bf16 v[70:73], v[154:157], v[208:211], v[70:73]
	v_mfma_f32_16x16x32_bf16 v[126:129], v[150:153], v[188:191], v[126:129]
	v_mfma_f32_16x16x32_bf16 v[118:121], v[158:161], v[188:191], v[118:121]
	v_mfma_f32_16x16x32_bf16 v[110:113], v[150:153], v[196:199], v[110:113]
	v_mfma_f32_16x16x32_bf16 v[102:105], v[158:161], v[196:199], v[102:105]
	v_mfma_f32_16x16x32_bf16 v[94:97], v[150:153], v[204:207], v[94:97]
	v_mfma_f32_16x16x32_bf16 v[86:89], v[158:161], v[204:207], v[86:89]
	v_mfma_f32_16x16x32_bf16 v[78:81], v[150:153], v[212:215], v[78:81]
	v_mfma_f32_16x16x32_bf16 v[70:73], v[158:161], v[212:215], v[70:73]
	v_mfma_f32_16x16x32_bf16 v[122:125], v[162:165], v[184:187], v[122:125]
	v_mfma_f32_16x16x32_bf16 v[114:117], v[170:173], v[184:187], v[114:117]
	v_mfma_f32_16x16x32_bf16 v[106:109], v[162:165], v[192:195], v[106:109]
	v_mfma_f32_16x16x32_bf16 v[98:101], v[170:173], v[192:195], v[98:101]
	v_mfma_f32_16x16x32_bf16 v[90:93], v[162:165], v[200:203], v[90:93]
	v_mfma_f32_16x16x32_bf16 v[82:85], v[170:173], v[200:203], v[82:85]
	v_mfma_f32_16x16x32_bf16 v[74:77], v[162:165], v[208:211], v[74:77]
	v_mfma_f32_16x16x32_bf16 v[66:69], v[170:173], v[208:211], v[66:69]
	v_mfma_f32_16x16x32_bf16 v[122:125], v[166:169], v[188:191], v[122:125]
	v_mfma_f32_16x16x32_bf16 v[114:117], v[180:183], v[188:191], v[114:117]
	v_mfma_f32_16x16x32_bf16 v[106:109], v[166:169], v[196:199], v[106:109]
	v_mfma_f32_16x16x32_bf16 v[98:101], v[180:183], v[196:199], v[98:101]
	v_mfma_f32_16x16x32_bf16 v[90:93], v[166:169], v[204:207], v[90:93]
	v_mfma_f32_16x16x32_bf16 v[82:85], v[180:183], v[204:207], v[82:85]
	v_mfma_f32_16x16x32_bf16 v[74:77], v[166:169], v[212:215], v[74:77]
	v_mfma_f32_16x16x32_bf16 v[66:69], v[180:183], v[212:215], v[66:69]
	s_barrier
	s_setprio 0
	s_add_i32 s18, s54, s5
	v_lshl_add_u64 v[140:141], s[28:29], 0, v[0:1]
	s_mov_b32 m0, s18
	ds_read_b128 v[184:187], v145 offset:16384
	ds_read_b128 v[188:191], v145 offset:17408
	ds_read_b128 v[192:195], v145 offset:18432
	ds_read_b128 v[196:199], v145 offset:19456
	ds_read_b128 v[200:203], v145 offset:20480
	ds_read_b128 v[204:207], v145 offset:21504
	ds_read_b128 v[208:211], v145 offset:22528
	ds_read_b128 v[212:215], v145 offset:23552
	global_load_lds_dwordx4 v[140:141], off
	s_add_i32 m0, s18, 0x2000
	s_add_u32 s18, s28, 0x80000
	v_lshl_add_u64 v[174:175], s[28:29], 0, v[130:131]
	s_addc_u32 s19, s29, 0
	s_add_i32 s54, s55, s5
	global_load_lds_dwordx4 v[174:175], off
	v_lshl_add_u64 v[216:217], s[18:19], 0, v[0:1]
	s_mov_b32 m0, s54
	v_lshl_add_u64 v[218:219], s[34:35], 0, v[132:133]
	global_load_lds_dwordx4 v[216:217], off
	v_lshl_add_u64 v[216:217], s[18:19], 0, v[130:131]
	s_add_i32 m0, s54, 0x2000
	s_nop 0
	global_load_lds_dwordx4 v[216:217], off
	v_lshl_add_u64 v[216:217], s[34:35], 0, v[134:135]
	s_mov_b32 m0, s38
	s_nop 0
	global_load_lds_dwordx4 v[216:217], off
	s_mov_b32 m0, s39
	s_nop 0
	global_load_lds_dwordx4 v[218:219], off
	s_waitcnt vmcnt(8)
	s_waitcnt lgkmcnt(0)
	s_setprio 1
	s_barrier
; #define PG8_STAGE(bufoff, gbase, voff) do { _Pragma("unroll") for (int _i = 0; _i < 2; ++_i) \
;         __builtin_amdgcn_global_load_lds((const unsigned*)((const char*)(gbase) + (voff)[_i]), (LAS unsigned*)(lds + (bufoff) + ldsw + _i * 8192), 16, 0, 0); } while (0)
; #define PG8_LDA(dst, b, h) do { _Pragma("unroll") for (int m = 0; m < 4; ++m) _Pragma("unroll") for (int k = 0; k < 2; ++k) dst[m][k] = *(const LAS bf16x8*)(lds + PG8_SA(b, h) + aoff + m * 2048 + k * 1024); } while (0)
; #define PG8_LDB(dst, b, h) do { _Pragma("unroll") for (int n = 0; n < 2; ++n) _Pragma("unroll") for (int k = 0; k < 2; ++k) dst[n][k] = *(const LAS bf16x8*)(lds + PG8_SB(b, h) + boff + n * 2048 + k * 1024); } while (0)
; #define PG8_MMA(ai, bj, At, Bt) do { __builtin_amdgcn_s_setprio(1); _Pragma("unroll") for (int m = 0; m < 4; ++m) _Pragma("unroll") for (int n = 0; n < 2; ++n) _Pragma("unroll") for (int k = 0; k < 2; ++k) \
;         acc[ai][bj][m][n] = __builtin_amdgcn_mfma_f32_16x16x32_bf16(Bt[n][k], At[m][k], acc[ai][bj][m][n], 0, 0, 0); __builtin_amdgcn_s_setprio(0); } while (0)
; #define PG8_WAIT_V(n) asm volatile("s_waitcnt vmcnt(" #n ")" ::: "memory")
; #define PG8_WAIT_L(n) asm volatile("s_waitcnt lgkmcnt(" #n ")" ::: "memory")
; #define PG8_BAR __builtin_amdgcn_s_barrier()
; #define PG8_SCHED __builtin_amdgcn_sched_barrier(0)
; template <class Epi, class Sched, int LDA, int LDB, bool ALIGN_EPI = true>
; __device__ __forceinline__ void gemm_phase(LAS unsigned char* lds, const Gemm g, const Sched& S, const Epi& E, int wave) {
;     ...
;             PG8_WAIT_V(8); PG8_WAIT_L(0); PG8_BAR; PG8_MMA(1, 0, At, B0); PG8_MMA(1, 1, At, B1); PG8_BAR; PG8_SCHED;
;             PG8_LDB(B0, 1, 0); PG8_LDB(B1, 1, 1); PG8_SCHED; PG8_LDA(At, 1, 0); PG8_STAGE(PG8_SA(0, 1), a2 + hstepA, voffA);
;             PG8_WAIT_V(8); PG8_WAIT_L(0); PG8_BAR; PG8_MMA(0, 0, At, B0); PG8_MMA(0, 1, At, B1); PG8_BAR; PG8_SCHED;
	v_mfma_f32_16x16x32_bf16 v[62:65], v[146:149], v[184:187], v[62:65]
	v_mfma_f32_16x16x32_bf16 v[54:57], v[154:157], v[184:187], v[54:57]
	v_mfma_f32_16x16x32_bf16 v[46:49], v[146:149], v[192:195], v[46:49]
	v_mfma_f32_16x16x32_bf16 v[38:41], v[154:157], v[192:195], v[38:41]
	v_mfma_f32_16x16x32_bf16 v[30:33], v[146:149], v[200:203], v[30:33]
	v_mfma_f32_16x16x32_bf16 v[22:25], v[154:157], v[200:203], v[22:25]
	v_mfma_f32_16x16x32_bf16 v[14:17], v[146:149], v[208:211], v[14:17]
	v_mfma_f32_16x16x32_bf16 v[6:9], v[154:157], v[208:211], v[6:9]
	v_mfma_f32_16x16x32_bf16 v[62:65], v[150:153], v[188:191], v[62:65]
	v_mfma_f32_16x16x32_bf16 v[54:57], v[158:161], v[188:191], v[54:57]
	v_mfma_f32_16x16x32_bf16 v[46:49], v[150:153], v[196:199], v[46:49]
	v_mfma_f32_16x16x32_bf16 v[38:41], v[158:161], v[196:199], v[38:41]
	v_mfma_f32_16x16x32_bf16 v[30:33], v[150:153], v[204:207], v[30:33]
	v_mfma_f32_16x16x32_bf16 v[22:25], v[158:161], v[204:207], v[22:25]
	v_mfma_f32_16x16x32_bf16 v[14:17], v[150:153], v[212:215], v[14:17]
	v_mfma_f32_16x16x32_bf16 v[6:9], v[158:161], v[212:215], v[6:9]
	v_mfma_f32_16x16x32_bf16 v[58:61], v[162:165], v[184:187], v[58:61]
	v_mfma_f32_16x16x32_bf16 v[50:53], v[170:173], v[184:187], v[50:53]
	v_mfma_f32_16x16x32_bf16 v[42:45], v[162:165], v[192:195], v[42:45]
	v_mfma_f32_16x16x32_bf16 v[34:37], v[170:173], v[192:195], v[34:37]
	v_mfma_f32_16x16x32_bf16 v[26:29], v[162:165], v[200:203], v[26:29]
	v_mfma_f32_16x16x32_bf16 v[18:21], v[170:173], v[200:203], v[18:21]
	v_mfma_f32_16x16x32_bf16 v[10:13], v[162:165], v[208:211], v[10:13]
	v_mfma_f32_16x16x32_bf16 v[2:5], v[170:173], v[208:211], v[2:5]
	v_mfma_f32_16x16x32_bf16 v[58:61], v[166:169], v[188:191], v[58:61]
	v_mfma_f32_16x16x32_bf16 v[50:53], v[180:183], v[188:191], v[50:53]
	v_mfma_f32_16x16x32_bf16 v[42:45], v[166:169], v[196:199], v[42:45]
	v_mfma_f32_16x16x32_bf16 v[34:37], v[180:183], v[196:199], v[34:37]
	v_mfma_f32_16x16x32_bf16 v[26:29], v[166:169], v[204:207], v[26:29]
	v_mfma_f32_16x16x32_bf16 v[18:21], v[180:183], v[204:207], v[18:21]
	v_mfma_f32_16x16x32_bf16 v[10:13], v[166:169], v[212:215], v[10:13]
	v_mfma_f32_16x16x32_bf16 v[2:5], v[180:183], v[212:215], v[2:5]
	s_barrier
	s_setprio 0
	ds_read_b128 v[184:187], v145 offset:32768
	ds_read_b128 v[188:191], v145 offset:33792
	ds_read_b128 v[192:195], v145 offset:34816
	ds_read_b128 v[196:199], v145 offset:35840
	ds_read_b128 v[200:203], v145 offset:36864
	ds_read_b128 v[204:207], v145 offset:37888
	ds_read_b128 v[208:211], v145 offset:38912
	ds_read_b128 v[212:215], v145 offset:39936
	s_add_i32 s54, 0, 0x18000
	s_add_i32 s55, 0, 0x1c000
	v_add_u32_e32 v158, s54, v143
	v_add_u32_e32 v180, s55, v143
	ds_read_b128 v[146:149], v158
	ds_read_b128 v[150:153], v158 offset:1024
	ds_read_b128 v[154:157], v158 offset:2048
	ds_read_b128 v[158:161], v158 offset:3072
	ds_read_b128 v[162:165], v180
	ds_read_b128 v[166:169], v180 offset:1024
	ds_read_b128 v[170:173], v180 offset:2048
	ds_read_b128 v[180:183], v180 offset:3072
	s_add_u32 s18, s34, 0x84000
	s_addc_u32 s19, s35, 0
	s_mov_b32 m0, s46
	v_lshl_add_u64 v[220:221], s[18:19], 0, v[134:135]
	global_load_lds_dwordx4 v[220:221], off
	v_lshl_add_u64 v[220:221], s[18:19], 0, v[132:133]
	s_mov_b32 m0, s47
	s_nop 0
	global_load_lds_dwordx4 v[220:221], off
	s_waitcnt vmcnt(8)
	s_waitcnt lgkmcnt(0)
	s_setprio 1
	s_barrier
	v_mfma_f32_16x16x32_bf16 v[126:129], v[146:149], v[184:187], v[126:129]
	v_mfma_f32_16x16x32_bf16 v[118:121], v[154:157], v[184:187], v[118:121]
	v_mfma_f32_16x16x32_bf16 v[110:113], v[146:149], v[192:195], v[110:113]
	v_mfma_f32_16x16x32_bf16 v[102:105], v[154:157], v[192:195], v[102:105]
	v_mfma_f32_16x16x32_bf16 v[94:97], v[146:149], v[200:203], v[94:97]
	v_mfma_f32_16x16x32_bf16 v[86:89], v[154:157], v[200:203], v[86:89]
	v_mfma_f32_16x16x32_bf16 v[78:81], v[146:149], v[208:211], v[78:81]
	v_mfma_f32_16x16x32_bf16 v[70:73], v[154:157], v[208:211], v[70:73]
	v_mfma_f32_16x16x32_bf16 v[126:129], v[150:153], v[188:191], v[126:129]
	v_mfma_f32_16x16x32_bf16 v[118:121], v[158:161], v[188:191], v[118:121]
	v_mfma_f32_16x16x32_bf16 v[110:113], v[150:153], v[196:199], v[110:113]
	v_mfma_f32_16x16x32_bf16 v[102:105], v[158:161], v[196:199], v[102:105]
	v_mfma_f32_16x16x32_bf16 v[94:97], v[150:153], v[204:207], v[94:97]
	v_mfma_f32_16x16x32_bf16 v[86:89], v[158:161], v[204:207], v[86:89]
	v_mfma_f32_16x16x32_bf16 v[78:81], v[150:153], v[212:215], v[78:81]
	v_mfma_f32_16x16x32_bf16 v[70:73], v[158:161], v[212:215], v[70:73]
	v_mfma_f32_16x16x32_bf16 v[122:125], v[162:165], v[184:187], v[122:125]
	v_mfma_f32_16x16x32_bf16 v[114:117], v[170:173], v[184:187], v[114:117]
	v_mfma_f32_16x16x32_bf16 v[106:109], v[162:165], v[192:195], v[106:109]
	v_mfma_f32_16x16x32_bf16 v[98:101], v[170:173], v[192:195], v[98:101]
	v_mfma_f32_16x16x32_bf16 v[90:93], v[162:165], v[200:203], v[90:93]
	v_mfma_f32_16x16x32_bf16 v[82:85], v[170:173], v[200:203], v[82:85]
	v_mfma_f32_16x16x32_bf16 v[74:77], v[162:165], v[208:211], v[74:77]
	v_mfma_f32_16x16x32_bf16 v[66:69], v[170:173], v[208:211], v[66:69]
	v_mfma_f32_16x16x32_bf16 v[122:125], v[166:169], v[188:191], v[122:125]
	v_mfma_f32_16x16x32_bf16 v[114:117], v[180:183], v[188:191], v[114:117]
	v_mfma_f32_16x16x32_bf16 v[106:109], v[166:169], v[196:199], v[106:109]
	v_mfma_f32_16x16x32_bf16 v[98:101], v[180:183], v[196:199], v[98:101]
	v_mfma_f32_16x16x32_bf16 v[90:93], v[166:169], v[204:207], v[90:93]
	v_mfma_f32_16x16x32_bf16 v[82:85], v[180:183], v[204:207], v[82:85]
	v_mfma_f32_16x16x32_bf16 v[74:77], v[166:169], v[212:215], v[74:77]
	v_mfma_f32_16x16x32_bf16 v[66:69], v[180:183], v[212:215], v[66:69]
	s_barrier
; #define PG8_STAGE(bufoff, gbase, voff) do { _Pragma("unroll") for (int _i = 0; _i < 2; ++_i) \
;         __builtin_amdgcn_global_load_lds((const unsigned*)((const char*)(gbase) + (voff)[_i]), (LAS unsigned*)(lds + (bufoff) + ldsw + _i * 8192), 16, 0, 0); } while (0)
; #define PG8_LDA(dst, b, h) do { _Pragma("unroll") for (int m = 0; m < 4; ++m) _Pragma("unroll") for (int k = 0; k < 2; ++k) dst[m][k] = *(const LAS bf16x8*)(lds + PG8_SA(b, h) + aoff + m * 2048 + k * 1024); } while (0)
; #define PG8_MMA(ai, bj, At, Bt) do { __builtin_amdgcn_s_setprio(1); _Pragma("unroll") for (int m = 0; m < 4; ++m) _Pragma("unroll") for (int n = 0; n < 2; ++n) _Pragma("unroll") for (int k = 0; k < 2; ++k) \
;         acc[ai][bj][m][n] = __builtin_amdgcn_mfma_f32_16x16x32_bf16(Bt[n][k], At[m][k], acc[ai][bj][m][n], 0, 0, 0); __builtin_amdgcn_s_setprio(0); } while (0)
; #define PG8_WAIT_V(n) asm volatile("s_waitcnt vmcnt(" #n ")" ::: "memory")
; #define PG8_WAIT_L(n) asm volatile("s_waitcnt lgkmcnt(" #n ")" ::: "memory")
; #define PG8_BAR __builtin_amdgcn_s_barrier()
; #define PG8_SCHED __builtin_amdgcn_sched_barrier(0)
; template <class Epi, class Sched, int LDA, int LDB, bool ALIGN_EPI = true>
; __device__ __forceinline__ void gemm_phase(LAS unsigned char* lds, const Gemm g, const Sched& S, const Epi& E, int wave) {
;     ...
;             PG8_LDA(At, 1, 1); PG8_STAGE(PG8_SB(1, 0), b3, voffB); PG8_STAGE(PG8_SB(1, 1), b3 + hstepB, voffB); PG8_STAGE(PG8_SA(1, 0), a3, voffA);
;             PG8_WAIT_V(8); PG8_WAIT_L(0); PG8_BAR; PG8_MMA(1, 0, At, B0); PG8_MMA(1, 1, At, B1); PG8_BAR; PG8_SCHED;
;         }
	s_setprio 0
	s_add_i32 s18, s54, s5
	v_lshl_add_u64 v[140:141], v[140:141], 0, s[6:7]
	s_mov_b32 m0, s18
	ds_read_b128 v[184:187], v145 offset:49152
	ds_read_b128 v[188:191], v145 offset:50176
	ds_read_b128 v[192:195], v145 offset:51200
	ds_read_b128 v[196:199], v145 offset:52224
	ds_read_b128 v[200:203], v145 offset:53248
	ds_read_b128 v[204:207], v145 offset:54272
	ds_read_b128 v[208:211], v145 offset:55296
	ds_read_b128 v[212:215], v145 offset:56320
	global_load_lds_dwordx4 v[140:141], off
	s_add_i32 m0, s18, 0x2000
	s_add_u32 s18, s28, 0x80080
	v_lshl_add_u64 v[140:141], v[174:175], 0, s[6:7]
	s_addc_u32 s19, s29, 0
	s_add_i32 s28, s55, s5
	global_load_lds_dwordx4 v[140:141], off
	v_lshl_add_u64 v[140:141], s[18:19], 0, v[0:1]
	s_mov_b32 m0, s28
	s_nop 0
	global_load_lds_dwordx4 v[140:141], off
	v_lshl_add_u64 v[140:141], s[18:19], 0, v[130:131]
	s_add_i32 m0, s28, 0x2000
	s_nop 0
	global_load_lds_dwordx4 v[140:141], off
	v_lshl_add_u64 v[140:141], v[216:217], 0, s[6:7]
	s_mov_b32 m0, s48
	s_nop 0
	global_load_lds_dwordx4 v[140:141], off
	v_lshl_add_u64 v[140:141], v[218:219], 0, s[6:7]
	s_mov_b32 m0, s49
	s_nop 0
	global_load_lds_dwordx4 v[140:141], off
	s_waitcnt vmcnt(8)
	s_waitcnt lgkmcnt(0)
	s_setprio 1
	s_barrier
	v_mfma_f32_16x16x32_bf16 v[62:65], v[146:149], v[184:187], v[62:65]
	v_mfma_f32_16x16x32_bf16 v[54:57], v[154:157], v[184:187], v[54:57]
	v_mfma_f32_16x16x32_bf16 v[46:49], v[146:149], v[192:195], v[46:49]
	v_mfma_f32_16x16x32_bf16 v[38:41], v[154:157], v[192:195], v[38:41]
	v_mfma_f32_16x16x32_bf16 v[30:33], v[146:149], v[200:203], v[30:33]
	v_mfma_f32_16x16x32_bf16 v[22:25], v[154:157], v[200:203], v[22:25]
	v_mfma_f32_16x16x32_bf16 v[14:17], v[146:149], v[208:211], v[14:17]
	v_mfma_f32_16x16x32_bf16 v[6:9], v[154:157], v[208:211], v[6:9]
	v_mfma_f32_16x16x32_bf16 v[62:65], v[150:153], v[188:191], v[62:65]
	v_mfma_f32_16x16x32_bf16 v[54:57], v[158:161], v[188:191], v[54:57]
	v_mfma_f32_16x16x32_bf16 v[46:49], v[150:153], v[196:199], v[46:49]
	v_mfma_f32_16x16x32_bf16 v[38:41], v[158:161], v[196:199], v[38:41]
	v_mfma_f32_16x16x32_bf16 v[30:33], v[150:153], v[204:207], v[30:33]
	v_mfma_f32_16x16x32_bf16 v[22:25], v[158:161], v[204:207], v[22:25]
	v_mfma_f32_16x16x32_bf16 v[14:17], v[150:153], v[212:215], v[14:17]
	v_mfma_f32_16x16x32_bf16 v[6:9], v[158:161], v[212:215], v[6:9]
	v_mfma_f32_16x16x32_bf16 v[58:61], v[162:165], v[184:187], v[58:61]
	v_mfma_f32_16x16x32_bf16 v[50:53], v[170:173], v[184:187], v[50:53]
	v_mfma_f32_16x16x32_bf16 v[42:45], v[162:165], v[192:195], v[42:45]
	v_mfma_f32_16x16x32_bf16 v[34:37], v[170:173], v[192:195], v[34:37]
	v_mfma_f32_16x16x32_bf16 v[26:29], v[162:165], v[200:203], v[26:29]
	v_mfma_f32_16x16x32_bf16 v[18:21], v[170:173], v[200:203], v[18:21]
	v_mfma_f32_16x16x32_bf16 v[10:13], v[162:165], v[208:211], v[10:13]
	v_mfma_f32_16x16x32_bf16 v[2:5], v[170:173], v[208:211], v[2:5]
	v_mfma_f32_16x16x32_bf16 v[58:61], v[166:169], v[188:191], v[58:61]
	v_mfma_f32_16x16x32_bf16 v[50:53], v[180:183], v[188:191], v[50:53]
	v_mfma_f32_16x16x32_bf16 v[42:45], v[166:169], v[196:199], v[42:45]
	v_mfma_f32_16x16x32_bf16 v[34:37], v[180:183], v[196:199], v[34:37]
	v_mfma_f32_16x16x32_bf16 v[26:29], v[166:169], v[204:207], v[26:29]
	v_mfma_f32_16x16x32_bf16 v[18:21], v[180:183], v[204:207], v[18:21]
	v_mfma_f32_16x16x32_bf16 v[10:13], v[166:169], v[212:215], v[10:13]
	v_mfma_f32_16x16x32_bf16 v[2:5], v[180:183], v[212:215], v[2:5]
	s_barrier
	s_setprio 0
	s_add_i32 s53, s53, 2
	s_add_u32 s44, s44, 0x100
	s_addc_u32 s45, s45, 0
	s_cmp_gt_u32 s53, 29
	s_mov_b64 s[18:19], s[24:25]
	s_cbranch_scc0 .LBB0_485
	v_readlane_b32 s6, v252, 14
	v_readlane_b32 s7, v252, 15
	s_and_b64 vcc, exec, s[6:7]
	s_cbranch_vccz .LBB0_488
	s_barrier

; #define PG8_STAGE(bufoff, gbase, voff) do { _Pragma("unroll") for (int _i = 0; _i < 2; ++_i) \
;         __builtin_amdgcn_global_load_lds((const unsigned*)((const char*)(gbase) + (voff)[_i]), (LAS unsigned*)(lds + (bufoff) + ldsw + _i * 8192), 16, 0, 0); } while (0)
; #define PG8_LDA(dst, b, h) do { _Pragma("unroll") for (int m = 0; m < 4; ++m) _Pragma("unroll") for (int k = 0; k < 2; ++k) dst[m][k] = *(const LAS bf16x8*)(lds + PG8_SA(b, h) + aoff + m * 2048 + k * 1024); } while (0)
; #define PG8_LDB(dst, b, h) do { _Pragma("unroll") for (int n = 0; n < 2; ++n) _Pragma("unroll") for (int k = 0; k < 2; ++k) dst[n][k] = *(const LAS bf16x8*)(lds + PG8_SB(b, h) + boff + n * 2048 + k * 1024); } while (0)
; #define PG8_MMA(ai, bj, At, Bt) do { __builtin_amdgcn_s_setprio(1); _Pragma("unroll") for (int m = 0; m < 4; ++m) _Pragma("unroll") for (int n = 0; n < 2; ++n) _Pragma("unroll") for (int k = 0; k < 2; ++k) \
;         acc[ai][bj][m][n] = __builtin_amdgcn_mfma_f32_16x16x32_bf16(Bt[n][k], At[m][k], acc[ai][bj][m][n], 0, 0, 0); __builtin_amdgcn_s_setprio(0); } while (0)
; #define PG8_WAIT_V(n) asm volatile("s_waitcnt vmcnt(" #n ")" ::: "memory")
; #define PG8_WAIT_L(n) asm volatile("s_waitcnt lgkmcnt(" #n ")" ::: "memory")
; #define PG8_BAR __builtin_amdgcn_s_barrier()
; #define PG8_SCHED __builtin_amdgcn_sched_barrier(0)
; template <class Epi, class Sched, int LDA, int LDB, bool ALIGN_EPI = true>
; __device__ __forceinline__ void gemm_phase(LAS unsigned char* lds, const Gemm g, const Sched& S, const Epi& E, int wave) {
;     ...
;             const bool last = (t == nt - 2);
;             const char* a1 = cA + (size_t)(t + 1) * kstep;
;             const char* a2 = last ? nA : cA + (size_t)(t + 2) * kstep; const char* b2 = last ? nB : cB + (size_t)(t + 2) * kstep;
;             const char* a3 = a2 + kstep; const char* b3 = b2 + kstep;
;             PG8_LDB(B0, 0, 0); PG8_LDB(B1, 0, 1); PG8_SCHED; PG8_LDA(At, 0, 0); PG8_STAGE(PG8_SA(1, 1), a1 + hstepA, voffA);
;             PG8_WAIT_V(8); PG8_WAIT_L(0); PG8_BAR; PG8_MMA(0, 0, At, B0); PG8_MMA(0, 1, At, B1); PG8_BAR; PG8_SCHED;
;             PG8_LDA(At, 0, 1); PG8_STAGE(PG8_SB(0, 0), b2, voffB); PG8_STAGE(PG8_SB(0, 1), b2 + hstepB, voffB); PG8_STAGE(PG8_SA(0, 0), a2, voffA);
;             PG8_WAIT_V(8); PG8_WAIT_L(0); PG8_BAR; PG8_MMA(1, 0, At, B0); PG8_MMA(1, 1, At, B1); PG8_BAR; PG8_SCHED;
.LBB0_1893:
	ds_read_b128 v[172:175], v236
	ds_read_b128 v[180:183], v236 offset:1024
	ds_read_b128 v[184:187], v236 offset:2048
	ds_read_b128 v[188:191], v236 offset:3072
	ds_read_b128 v[192:195], v236 offset:4096
	ds_read_b128 v[196:199], v236 offset:5120
	ds_read_b128 v[200:203], v236 offset:6144
	ds_read_b128 v[204:207], v236 offset:7168
	s_add_i32 s79, s46, 2
	s_add_u32 s38, s36, 0x100
	s_addc_u32 s39, s37, 0
	s_add_i32 s82, 0, 0x10000
	s_cmp_eq_u32 s25, s46
	s_cselect_b32 s49, s29, s39
	s_cselect_b32 s48, s28, s38
	s_cselect_b32 s47, s35, s78
	s_cselect_b32 s46, s34, s77
	s_add_i32 s85, 0, 0x14000
	v_add_u32_e32 v152, s82, v249
	v_add_u32_e32 v168, s85, v249
	ds_read_b128 v[130:133], v152
	ds_read_b128 v[134:137], v152 offset:1024
	ds_read_b128 v[148:151], v152 offset:2048
	ds_read_b128 v[152:155], v152 offset:3072
	ds_read_b128 v[156:159], v168
	ds_read_b128 v[160:163], v168 offset:1024
	ds_read_b128 v[164:167], v168 offset:2048
	ds_read_b128 v[168:171], v168 offset:3072
	v_lshl_add_u64 v[208:209], s[36:37], 0, v[144:145]
	s_add_i32 m0, s50, 0xc000
	s_nop 0
	global_load_lds_dwordx4 v[208:209], off
	v_lshl_add_u64 v[208:209], s[36:37], 0, v[146:147]
	s_add_i32 m0, s50, 0xe000
	s_nop 0
	global_load_lds_dwordx4 v[208:209], off
	s_waitcnt vmcnt(8)
	s_waitcnt lgkmcnt(0)
	s_setprio 1
	s_barrier
	v_mfma_f32_16x16x32_bf16 v[126:129], v[130:133], v[172:175], v[126:129]
	v_mfma_f32_16x16x32_bf16 v[122:125], v[148:151], v[172:175], v[122:125]
	v_mfma_f32_16x16x32_bf16 v[110:113], v[130:133], v[184:187], v[110:113]
	v_mfma_f32_16x16x32_bf16 v[106:109], v[148:151], v[184:187], v[106:109]
	v_mfma_f32_16x16x32_bf16 v[94:97], v[130:133], v[192:195], v[94:97]
	v_mfma_f32_16x16x32_bf16 v[90:93], v[148:151], v[192:195], v[90:93]
	v_mfma_f32_16x16x32_bf16 v[78:81], v[130:133], v[200:203], v[78:81]
	v_mfma_f32_16x16x32_bf16 v[74:77], v[148:151], v[200:203], v[74:77]
	v_mfma_f32_16x16x32_bf16 v[126:129], v[134:137], v[180:183], v[126:129]
	v_mfma_f32_16x16x32_bf16 v[122:125], v[152:155], v[180:183], v[122:125]
	v_mfma_f32_16x16x32_bf16 v[110:113], v[134:137], v[188:191], v[110:113]
	v_mfma_f32_16x16x32_bf16 v[106:109], v[152:155], v[188:191], v[106:109]
	v_mfma_f32_16x16x32_bf16 v[94:97], v[134:137], v[196:199], v[94:97]
	v_mfma_f32_16x16x32_bf16 v[90:93], v[152:155], v[196:199], v[90:93]
	v_mfma_f32_16x16x32_bf16 v[78:81], v[134:137], v[204:207], v[78:81]
	v_mfma_f32_16x16x32_bf16 v[74:77], v[152:155], v[204:207], v[74:77]
	v_mfma_f32_16x16x32_bf16 v[118:121], v[156:159], v[172:175], v[118:121]
	v_mfma_f32_16x16x32_bf16 v[114:117], v[164:167], v[172:175], v[114:117]
	v_mfma_f32_16x16x32_bf16 v[102:105], v[156:159], v[184:187], v[102:105]
	v_mfma_f32_16x16x32_bf16 v[98:101], v[164:167], v[184:187], v[98:101]
	v_mfma_f32_16x16x32_bf16 v[86:89], v[156:159], v[192:195], v[86:89]
	v_mfma_f32_16x16x32_bf16 v[82:85], v[164:167], v[192:195], v[82:85]
	v_mfma_f32_16x16x32_bf16 v[70:73], v[156:159], v[200:203], v[70:73]
	v_mfma_f32_16x16x32_bf16 v[66:69], v[164:167], v[200:203], v[66:69]
	v_mfma_f32_16x16x32_bf16 v[118:121], v[160:163], v[180:183], v[118:121]
	v_mfma_f32_16x16x32_bf16 v[114:117], v[168:171], v[180:183], v[114:117]
	v_mfma_f32_16x16x32_bf16 v[102:105], v[160:163], v[188:191], v[102:105]
	v_mfma_f32_16x16x32_bf16 v[98:101], v[168:171], v[188:191], v[98:101]
	v_mfma_f32_16x16x32_bf16 v[86:89], v[160:163], v[196:199], v[86:89]
	v_mfma_f32_16x16x32_bf16 v[82:85], v[168:171], v[196:199], v[82:85]
	v_mfma_f32_16x16x32_bf16 v[70:73], v[160:163], v[204:207], v[70:73]
	v_mfma_f32_16x16x32_bf16 v[66:69], v[168:171], v[204:207], v[66:69]
	s_barrier
	s_setprio 0
	s_add_i32 s36, s82, s2
	v_lshl_add_u64 v[208:209], s[46:47], 0, v[0:1]
	s_mov_b32 m0, s36
	ds_read_b128 v[172:175], v236 offset:16384
	ds_read_b128 v[180:183], v236 offset:17408
	ds_read_b128 v[184:187], v236 offset:18432
	ds_read_b128 v[188:191], v236 offset:19456
	ds_read_b128 v[192:195], v236 offset:20480
	ds_read_b128 v[196:199], v236 offset:21504
	ds_read_b128 v[200:203], v236 offset:22528
	ds_read_b128 v[204:207], v236 offset:23552
	global_load_lds_dwordx4 v[208:209], off
	s_add_i32 m0, s36, 0x2000
	s_add_u32 s36, s46, 0x160000
	v_lshl_add_u64 v[210:211], s[46:47], 0, v[142:143]
	s_addc_u32 s37, s47, 0
	s_add_i32 s82, s85, s2
	global_load_lds_dwordx4 v[210:211], off
	v_lshl_add_u64 v[212:213], s[36:37], 0, v[0:1]
	s_mov_b32 m0, s82
	v_lshl_add_u64 v[214:215], s[48:49], 0, v[140:141]
	global_load_lds_dwordx4 v[212:213], off
	v_lshl_add_u64 v[212:213], s[36:37], 0, v[142:143]
	s_add_i32 m0, s82, 0x2000
	s_nop 0
	global_load_lds_dwordx4 v[212:213], off
	v_lshl_add_u64 v[212:213], s[48:49], 0, v[138:139]
	s_mov_b32 m0, s50
	s_nop 0
	global_load_lds_dwordx4 v[212:213], off
	s_mov_b32 m0, s51
	s_nop 0
	global_load_lds_dwordx4 v[214:215], off
	s_waitcnt vmcnt(8)
	s_waitcnt lgkmcnt(0)
	s_setprio 1
	s_barrier
; #define PG8_STAGE(bufoff, gbase, voff) do { _Pragma("unroll") for (int _i = 0; _i < 2; ++_i) \
;         __builtin_amdgcn_global_load_lds((const unsigned*)((const char*)(gbase) + (voff)[_i]), (LAS unsigned*)(lds + (bufoff) + ldsw + _i * 8192), 16, 0, 0); } while (0)
; #define PG8_LDA(dst, b, h) do { _Pragma("unroll") for (int m = 0; m < 4; ++m) _Pragma("unroll") for (int k = 0; k < 2; ++k) dst[m][k] = *(const LAS bf16x8*)(lds + PG8_SA(b, h) + aoff + m * 2048 + k * 1024); } while (0)
; #define PG8_LDB(dst, b, h) do { _Pragma("unroll") for (int n = 0; n < 2; ++n) _Pragma("unroll") for (int k = 0; k < 2; ++k) dst[n][k] = *(const LAS bf16x8*)(lds + PG8_SB(b, h) + boff + n * 2048 + k * 1024); } while (0)
; #define PG8_MMA(ai, bj, At, Bt) do { __builtin_amdgcn_s_setprio(1); _Pragma("unroll") for (int m = 0; m < 4; ++m) _Pragma("unroll") for (int n = 0; n < 2; ++n) _Pragma("unroll") for (int k = 0; k < 2; ++k) \
;         acc[ai][bj][m][n] = __builtin_amdgcn_mfma_f32_16x16x32_bf16(Bt[n][k], At[m][k], acc[ai][bj][m][n], 0, 0, 0); __builtin_amdgcn_s_setprio(0); } while (0)
; #define PG8_WAIT_V(n) asm volatile("s_waitcnt vmcnt(" #n ")" ::: "memory")
; #define PG8_WAIT_L(n) asm volatile("s_waitcnt lgkmcnt(" #n ")" ::: "memory")
; #define PG8_BAR __builtin_amdgcn_s_barrier()
; #define PG8_SCHED __builtin_amdgcn_sched_barrier(0)
; template <class Epi, class Sched, int LDA, int LDB, bool ALIGN_EPI = true>
; __device__ __forceinline__ void gemm_phase(LAS unsigned char* lds, const Gemm g, const Sched& S, const Epi& E, int wave) {
;     ...
;             PG8_WAIT_V(8); PG8_WAIT_L(0); PG8_BAR; PG8_MMA(1, 0, At, B0); PG8_MMA(1, 1, At, B1); PG8_BAR; PG8_SCHED;
;             PG8_LDB(B0, 1, 0); PG8_LDB(B1, 1, 1); PG8_SCHED; PG8_LDA(At, 1, 0); PG8_STAGE(PG8_SA(0, 1), a2 + hstepA, voffA);
;             PG8_WAIT_V(8); PG8_WAIT_L(0); PG8_BAR; PG8_MMA(0, 0, At, B0); PG8_MMA(0, 1, At, B1); PG8_BAR; PG8_SCHED;
	v_mfma_f32_16x16x32_bf16 v[62:65], v[130:133], v[172:175], v[62:65]
	v_mfma_f32_16x16x32_bf16 v[58:61], v[148:151], v[172:175], v[58:61]
	v_mfma_f32_16x16x32_bf16 v[46:49], v[130:133], v[184:187], v[46:49]
	v_mfma_f32_16x16x32_bf16 v[42:45], v[148:151], v[184:187], v[42:45]
	v_mfma_f32_16x16x32_bf16 v[30:33], v[130:133], v[192:195], v[30:33]
	v_mfma_f32_16x16x32_bf16 v[26:29], v[148:151], v[192:195], v[26:29]
	v_mfma_f32_16x16x32_bf16 v[14:17], v[130:133], v[200:203], v[14:17]
	v_mfma_f32_16x16x32_bf16 v[10:13], v[148:151], v[200:203], v[10:13]
	v_mfma_f32_16x16x32_bf16 v[62:65], v[134:137], v[180:183], v[62:65]
	v_mfma_f32_16x16x32_bf16 v[58:61], v[152:155], v[180:183], v[58:61]
	v_mfma_f32_16x16x32_bf16 v[46:49], v[134:137], v[188:191], v[46:49]
	v_mfma_f32_16x16x32_bf16 v[42:45], v[152:155], v[188:191], v[42:45]
	v_mfma_f32_16x16x32_bf16 v[30:33], v[134:137], v[196:199], v[30:33]
	v_mfma_f32_16x16x32_bf16 v[26:29], v[152:155], v[196:199], v[26:29]
	v_mfma_f32_16x16x32_bf16 v[14:17], v[134:137], v[204:207], v[14:17]
	v_mfma_f32_16x16x32_bf16 v[10:13], v[152:155], v[204:207], v[10:13]
	v_mfma_f32_16x16x32_bf16 v[54:57], v[156:159], v[172:175], v[54:57]
	v_mfma_f32_16x16x32_bf16 v[50:53], v[164:167], v[172:175], v[50:53]
	v_mfma_f32_16x16x32_bf16 v[38:41], v[156:159], v[184:187], v[38:41]
	v_mfma_f32_16x16x32_bf16 v[34:37], v[164:167], v[184:187], v[34:37]
	v_mfma_f32_16x16x32_bf16 v[22:25], v[156:159], v[192:195], v[22:25]
	v_mfma_f32_16x16x32_bf16 v[18:21], v[164:167], v[192:195], v[18:21]
	v_mfma_f32_16x16x32_bf16 v[6:9], v[156:159], v[200:203], v[6:9]
	v_mfma_f32_16x16x32_bf16 v[2:5], v[164:167], v[200:203], v[2:5]
	v_mfma_f32_16x16x32_bf16 v[54:57], v[160:163], v[180:183], v[54:57]
	v_mfma_f32_16x16x32_bf16 v[50:53], v[168:171], v[180:183], v[50:53]
	v_mfma_f32_16x16x32_bf16 v[38:41], v[160:163], v[188:191], v[38:41]
	v_mfma_f32_16x16x32_bf16 v[34:37], v[168:171], v[188:191], v[34:37]
	v_mfma_f32_16x16x32_bf16 v[22:25], v[160:163], v[196:199], v[22:25]
	v_mfma_f32_16x16x32_bf16 v[18:21], v[168:171], v[196:199], v[18:21]
	v_mfma_f32_16x16x32_bf16 v[6:9], v[160:163], v[204:207], v[6:9]
	v_mfma_f32_16x16x32_bf16 v[2:5], v[168:171], v[204:207], v[2:5]
	s_barrier
	s_setprio 0
	ds_read_b128 v[172:175], v236 offset:32768
	ds_read_b128 v[180:183], v236 offset:33792
	ds_read_b128 v[184:187], v236 offset:34816
	ds_read_b128 v[188:191], v236 offset:35840
	ds_read_b128 v[192:195], v236 offset:36864
	ds_read_b128 v[196:199], v236 offset:37888
	ds_read_b128 v[200:203], v236 offset:38912
	ds_read_b128 v[204:207], v236 offset:39936
	s_add_i32 s82, 0, 0x18000
	s_add_i32 s85, 0, 0x1c000
	v_add_u32_e32 v152, s82, v249
	v_add_u32_e32 v168, s85, v249
	ds_read_b128 v[130:133], v152
	ds_read_b128 v[134:137], v152 offset:1024
	ds_read_b128 v[148:151], v152 offset:2048
	ds_read_b128 v[152:155], v152 offset:3072
	ds_read_b128 v[156:159], v168
	ds_read_b128 v[160:163], v168 offset:1024
	ds_read_b128 v[164:167], v168 offset:2048
	ds_read_b128 v[168:171], v168 offset:3072
	s_add_u32 s36, s48, 0x160000
	s_addc_u32 s37, s49, 0
	s_mov_b32 m0, s52
	v_lshl_add_u64 v[216:217], s[36:37], 0, v[138:139]
	global_load_lds_dwordx4 v[216:217], off
	v_lshl_add_u64 v[216:217], s[36:37], 0, v[140:141]
	s_mov_b32 m0, s53
	s_nop 0
	global_load_lds_dwordx4 v[216:217], off
	s_waitcnt vmcnt(8)
	s_waitcnt lgkmcnt(0)
	s_setprio 1
	s_barrier
	v_mfma_f32_16x16x32_bf16 v[126:129], v[130:133], v[172:175], v[126:129]
	v_mfma_f32_16x16x32_bf16 v[122:125], v[148:151], v[172:175], v[122:125]
	v_mfma_f32_16x16x32_bf16 v[110:113], v[130:133], v[184:187], v[110:113]
	v_mfma_f32_16x16x32_bf16 v[106:109], v[148:151], v[184:187], v[106:109]
	v_mfma_f32_16x16x32_bf16 v[94:97], v[130:133], v[192:195], v[94:97]
	v_mfma_f32_16x16x32_bf16 v[90:93], v[148:151], v[192:195], v[90:93]
	v_mfma_f32_16x16x32_bf16 v[78:81], v[130:133], v[200:203], v[78:81]
	v_mfma_f32_16x16x32_bf16 v[74:77], v[148:151], v[200:203], v[74:77]
	v_mfma_f32_16x16x32_bf16 v[126:129], v[134:137], v[180:183], v[126:129]
	v_mfma_f32_16x16x32_bf16 v[122:125], v[152:155], v[180:183], v[122:125]
	v_mfma_f32_16x16x32_bf16 v[110:113], v[134:137], v[188:191], v[110:113]
	v_mfma_f32_16x16x32_bf16 v[106:109], v[152:155], v[188:191], v[106:109]
	v_mfma_f32_16x16x32_bf16 v[94:97], v[134:137], v[196:199], v[94:97]
	v_mfma_f32_16x16x32_bf16 v[90:93], v[152:155], v[196:199], v[90:93]
	v_mfma_f32_16x16x32_bf16 v[78:81], v[134:137], v[204:207], v[78:81]
	v_mfma_f32_16x16x32_bf16 v[74:77], v[152:155], v[204:207], v[74:77]
	v_mfma_f32_16x16x32_bf16 v[118:121], v[156:159], v[172:175], v[118:121]
	v_mfma_f32_16x16x32_bf16 v[114:117], v[164:167], v[172:175], v[114:117]
	v_mfma_f32_16x16x32_bf16 v[102:105], v[156:159], v[184:187], v[102:105]
	v_mfma_f32_16x16x32_bf16 v[98:101], v[164:167], v[184:187], v[98:101]
	v_mfma_f32_16x16x32_bf16 v[86:89], v[156:159], v[192:195], v[86:89]
	v_mfma_f32_16x16x32_bf16 v[82:85], v[164:167], v[192:195], v[82:85]
	v_mfma_f32_16x16x32_bf16 v[70:73], v[156:159], v[200:203], v[70:73]
	v_mfma_f32_16x16x32_bf16 v[66:69], v[164:167], v[200:203], v[66:69]
	v_mfma_f32_16x16x32_bf16 v[118:121], v[160:163], v[180:183], v[118:121]
	v_mfma_f32_16x16x32_bf16 v[114:117], v[168:171], v[180:183], v[114:117]
	v_mfma_f32_16x16x32_bf16 v[102:105], v[160:163], v[188:191], v[102:105]
	v_mfma_f32_16x16x32_bf16 v[98:101], v[168:171], v[188:191], v[98:101]
	v_mfma_f32_16x16x32_bf16 v[86:89], v[160:163], v[196:199], v[86:89]
	v_mfma_f32_16x16x32_bf16 v[82:85], v[168:171], v[196:199], v[82:85]
	v_mfma_f32_16x16x32_bf16 v[70:73], v[160:163], v[204:207], v[70:73]
	v_mfma_f32_16x16x32_bf16 v[66:69], v[168:171], v[204:207], v[66:69]
	s_barrier
; #define PG8_STAGE(bufoff, gbase, voff) do { _Pragma("unroll") for (int _i = 0; _i < 2; ++_i) \
;         __builtin_amdgcn_global_load_lds((const unsigned*)((const char*)(gbase) + (voff)[_i]), (LAS unsigned*)(lds + (bufoff) + ldsw + _i * 8192), 16, 0, 0); } while (0)
; #define PG8_LDA(dst, b, h) do { _Pragma("unroll") for (int m = 0; m < 4; ++m) _Pragma("unroll") for (int k = 0; k < 2; ++k) dst[m][k] = *(const LAS bf16x8*)(lds + PG8_SA(b, h) + aoff + m * 2048 + k * 1024); } while (0)
; #define PG8_MMA(ai, bj, At, Bt) do { __builtin_amdgcn_s_setprio(1); _Pragma("unroll") for (int m = 0; m < 4; ++m) _Pragma("unroll") for (int n = 0; n < 2; ++n) _Pragma("unroll") for (int k = 0; k < 2; ++k) \
;         acc[ai][bj][m][n] = __builtin_amdgcn_mfma_f32_16x16x32_bf16(Bt[n][k], At[m][k], acc[ai][bj][m][n], 0, 0, 0); __builtin_amdgcn_s_setprio(0); } while (0)
; #define PG8_WAIT_V(n) asm volatile("s_waitcnt vmcnt(" #n ")" ::: "memory")
; #define PG8_WAIT_L(n) asm volatile("s_waitcnt lgkmcnt(" #n ")" ::: "memory")
; #define PG8_BAR __builtin_amdgcn_s_barrier()
; #define PG8_SCHED __builtin_amdgcn_sched_barrier(0)
; template <class Epi, class Sched, int LDA, int LDB, bool ALIGN_EPI = true>
; __device__ __forceinline__ void gemm_phase(LAS unsigned char* lds, const Gemm g, const Sched& S, const Epi& E, int wave) {
;     ...
;             PG8_LDA(At, 1, 1); PG8_STAGE(PG8_SB(1, 0), b3, voffB); PG8_STAGE(PG8_SB(1, 1), b3 + hstepB, voffB); PG8_STAGE(PG8_SA(1, 0), a3, voffA);
;             PG8_WAIT_V(8); PG8_WAIT_L(0); PG8_BAR; PG8_MMA(1, 0, At, B0); PG8_MMA(1, 1, At, B1); PG8_BAR; PG8_SCHED;
;         }
	s_setprio 0
	s_add_i32 s36, s82, s2
	v_lshl_add_u64 v[208:209], v[208:209], 0, s[8:9]
	s_mov_b32 m0, s36
	ds_read_b128 v[172:175], v236 offset:49152
	ds_read_b128 v[180:183], v236 offset:50176
	ds_read_b128 v[184:187], v236 offset:51200
	ds_read_b128 v[188:191], v236 offset:52224
	ds_read_b128 v[192:195], v236 offset:53248
	ds_read_b128 v[196:199], v236 offset:54272
	ds_read_b128 v[200:203], v236 offset:55296
	ds_read_b128 v[204:207], v236 offset:56320
	global_load_lds_dwordx4 v[208:209], off
	s_add_i32 m0, s36, 0x2000
	s_add_u32 s36, s46, 0x160080
	v_lshl_add_u64 v[208:209], v[210:211], 0, s[8:9]
	s_addc_u32 s37, s47, 0
	s_add_i32 s46, s85, s2
	global_load_lds_dwordx4 v[208:209], off
	v_lshl_add_u64 v[208:209], s[36:37], 0, v[0:1]
	s_mov_b32 m0, s46
	s_nop 0
	global_load_lds_dwordx4 v[208:209], off
	v_lshl_add_u64 v[208:209], s[36:37], 0, v[142:143]
	s_add_i32 m0, s46, 0x2000
	s_nop 0
	global_load_lds_dwordx4 v[208:209], off
	v_lshl_add_u64 v[208:209], v[212:213], 0, s[8:9]
	s_mov_b32 m0, s5
	s_nop 0
	global_load_lds_dwordx4 v[208:209], off
	v_lshl_add_u64 v[208:209], v[214:215], 0, s[8:9]
	s_mov_b32 m0, s59
	s_nop 0
	global_load_lds_dwordx4 v[208:209], off
	s_waitcnt vmcnt(8)
	s_waitcnt lgkmcnt(0)
	s_setprio 1
	s_barrier
	v_mfma_f32_16x16x32_bf16 v[62:65], v[130:133], v[172:175], v[62:65]
	v_mfma_f32_16x16x32_bf16 v[58:61], v[148:151], v[172:175], v[58:61]
	v_mfma_f32_16x16x32_bf16 v[46:49], v[130:133], v[184:187], v[46:49]
	v_mfma_f32_16x16x32_bf16 v[42:45], v[148:151], v[184:187], v[42:45]
	v_mfma_f32_16x16x32_bf16 v[30:33], v[130:133], v[192:195], v[30:33]
	v_mfma_f32_16x16x32_bf16 v[26:29], v[148:151], v[192:195], v[26:29]
	v_mfma_f32_16x16x32_bf16 v[14:17], v[130:133], v[200:203], v[14:17]
	v_mfma_f32_16x16x32_bf16 v[10:13], v[148:151], v[200:203], v[10:13]
	v_mfma_f32_16x16x32_bf16 v[62:65], v[134:137], v[180:183], v[62:65]
	v_mfma_f32_16x16x32_bf16 v[58:61], v[152:155], v[180:183], v[58:61]
	v_mfma_f32_16x16x32_bf16 v[46:49], v[134:137], v[188:191], v[46:49]
	v_mfma_f32_16x16x32_bf16 v[42:45], v[152:155], v[188:191], v[42:45]
	v_mfma_f32_16x16x32_bf16 v[30:33], v[134:137], v[196:199], v[30:33]
	v_mfma_f32_16x16x32_bf16 v[26:29], v[152:155], v[196:199], v[26:29]
	v_mfma_f32_16x16x32_bf16 v[14:17], v[134:137], v[204:207], v[14:17]
	v_mfma_f32_16x16x32_bf16 v[10:13], v[152:155], v[204:207], v[10:13]
	v_mfma_f32_16x16x32_bf16 v[54:57], v[156:159], v[172:175], v[54:57]
	v_mfma_f32_16x16x32_bf16 v[50:53], v[164:167], v[172:175], v[50:53]
	v_mfma_f32_16x16x32_bf16 v[38:41], v[156:159], v[184:187], v[38:41]
	v_mfma_f32_16x16x32_bf16 v[34:37], v[164:167], v[184:187], v[34:37]
	v_mfma_f32_16x16x32_bf16 v[22:25], v[156:159], v[192:195], v[22:25]
	v_mfma_f32_16x16x32_bf16 v[18:21], v[164:167], v[192:195], v[18:21]
	v_mfma_f32_16x16x32_bf16 v[6:9], v[156:159], v[200:203], v[6:9]
	v_mfma_f32_16x16x32_bf16 v[2:5], v[164:167], v[200:203], v[2:5]
	v_mfma_f32_16x16x32_bf16 v[54:57], v[160:163], v[180:183], v[54:57]
	v_mfma_f32_16x16x32_bf16 v[50:53], v[168:171], v[180:183], v[50:53]
	v_mfma_f32_16x16x32_bf16 v[38:41], v[160:163], v[188:191], v[38:41]
	v_mfma_f32_16x16x32_bf16 v[34:37], v[168:171], v[188:191], v[34:37]
	v_mfma_f32_16x16x32_bf16 v[22:25], v[160:163], v[196:199], v[22:25]
	v_mfma_f32_16x16x32_bf16 v[18:21], v[168:171], v[196:199], v[18:21]
	v_mfma_f32_16x16x32_bf16 v[6:9], v[160:163], v[204:207], v[6:9]
	v_mfma_f32_16x16x32_bf16 v[2:5], v[168:171], v[204:207], v[2:5]
	s_barrier
	s_setprio 0
	s_add_u32 s77, s77, 0x100
	s_addc_u32 s78, s78, 0
	s_cmp_ge_i32 s79, s75
	s_mov_b64 s[36:37], s[38:39]
	s_mov_b32 s46, s79
	s_cbranch_scc0 .LBB0_1893
	v_readlane_b32 s2, v252, 14
	v_readlane_b32 s3, v252, 15
	s_and_b64 vcc, exec, s[2:3]
	s_cbranch_vccz .LBB0_1896
	s_barrier

; #define PG8_STAGE(bufoff, gbase, voff) do { _Pragma("unroll") for (int _i = 0; _i < 2; ++_i) \
;         __builtin_amdgcn_global_load_lds((const unsigned*)((const char*)(gbase) + (voff)[_i]), (LAS unsigned*)(lds + (bufoff) + ldsw + _i * 8192), 16, 0, 0); } while (0)
; #define PG8_LDA(dst, b, h) do { _Pragma("unroll") for (int m = 0; m < 4; ++m) _Pragma("unroll") for (int k = 0; k < 2; ++k) dst[m][k] = *(const LAS bf16x8*)(lds + PG8_SA(b, h) + aoff + m * 2048 + k * 1024); } while (0)
; #define PG8_LDB(dst, b, h) do { _Pragma("unroll") for (int n = 0; n < 2; ++n) _Pragma("unroll") for (int k = 0; k < 2; ++k) dst[n][k] = *(const LAS bf16x8*)(lds + PG8_SB(b, h) + boff + n * 2048 + k * 1024); } while (0)
; #define PG8_MMA(ai, bj, At, Bt) do { __builtin_amdgcn_s_setprio(1); _Pragma("unroll") for (int m = 0; m < 4; ++m) _Pragma("unroll") for (int n = 0; n < 2; ++n) _Pragma("unroll") for (int k = 0; k < 2; ++k) \
;         acc[ai][bj][m][n] = __builtin_amdgcn_mfma_f32_16x16x32_bf16(Bt[n][k], At[m][k], acc[ai][bj][m][n], 0, 0, 0); __builtin_amdgcn_s_setprio(0); } while (0)
; #define PG8_WAIT_V(n) asm volatile("s_waitcnt vmcnt(" #n ")" ::: "memory")
; #define PG8_WAIT_L(n) asm volatile("s_waitcnt lgkmcnt(" #n ")" ::: "memory")
; #define PG8_BAR __builtin_amdgcn_s_barrier()
; #define PG8_SCHED __builtin_amdgcn_sched_barrier(0)
; template <class Epi, class Sched, int LDA, int LDB, bool ALIGN_EPI = true>
; __device__ __forceinline__ void gemm_phase(LAS unsigned char* lds, const Gemm g, const Sched& S, const Epi& E, int wave) {
;     ...
;             const bool last = (t == nt - 2);
;             const char* a1 = cA + (size_t)(t + 1) * kstep;
;             const char* a2 = last ? nA : cA + (size_t)(t + 2) * kstep; const char* b2 = last ? nB : cB + (size_t)(t + 2) * kstep;
;             const char* a3 = a2 + kstep; const char* b3 = b2 + kstep;
;             PG8_LDB(B0, 0, 0); PG8_LDB(B1, 0, 1); PG8_SCHED; PG8_LDA(At, 0, 0); PG8_STAGE(PG8_SA(1, 1), a1 + hstepA, voffA);
;             PG8_WAIT_V(8); PG8_WAIT_L(0); PG8_BAR; PG8_MMA(0, 0, At, B0); PG8_MMA(0, 1, At, B1); PG8_BAR; PG8_SCHED;
;             PG8_LDA(At, 0, 1); PG8_STAGE(PG8_SB(0, 0), b2, voffB); PG8_STAGE(PG8_SB(0, 1), b2 + hstepB, voffB); PG8_STAGE(PG8_SA(0, 0), a2, voffA);
;             PG8_WAIT_V(8); PG8_WAIT_L(0); PG8_BAR; PG8_MMA(1, 0, At, B0); PG8_MMA(1, 1, At, B1); PG8_BAR; PG8_SCHED;
.LBB0_2254:
	ds_read_b128 v[184:187], v163
	ds_read_b128 v[188:191], v163 offset:1024
	ds_read_b128 v[192:195], v163 offset:2048
	ds_read_b128 v[196:199], v163 offset:3072
	ds_read_b128 v[200:203], v163 offset:4096
	ds_read_b128 v[204:207], v163 offset:5120
	ds_read_b128 v[208:211], v163 offset:6144
	ds_read_b128 v[212:215], v163 offset:7168
	s_add_u32 s2, s0, 0x100
	s_addc_u32 s3, s1, 0
	s_add_i32 s64, 0, 0x10000
	s_cmp_eq_u32 s59, 28
	s_cselect_b32 s29, s15, s3
	s_cselect_b32 s28, s14, s2
	v_add_u32_e32 v0, s64, v161
	s_cselect_b32 s25, s13, s58
	s_cselect_b32 s24, s48, s49
	s_add_i32 s65, 0, 0x14000
	ds_read_b128 v[144:147], v0
	ds_read_b128 v[148:151], v0 offset:1024
	ds_read_b128 v[152:155], v0 offset:2048
	ds_read_b128 v[156:159], v0 offset:3072
	v_add_u32_e32 v0, s65, v161
	ds_read_b128 v[164:167], v0
	ds_read_b128 v[168:171], v0 offset:1024
	ds_read_b128 v[172:175], v0 offset:2048
	ds_read_b128 v[180:183], v0 offset:3072
	v_lshl_add_u64 v[216:217], s[0:1], 0, v[140:141]
	s_add_i32 m0, s19, 0xc000
	s_nop 0
	global_load_lds_dwordx4 v[216:217], off
	v_lshl_add_u64 v[216:217], s[0:1], 0, v[142:143]
	s_add_i32 m0, s19, 0xe000
	s_nop 0
	global_load_lds_dwordx4 v[216:217], off
	s_waitcnt vmcnt(8)
	s_waitcnt lgkmcnt(0)
	s_setprio 1
	s_barrier
	v_mfma_f32_16x16x32_bf16 v[126:129], v[144:147], v[184:187], v[126:129]
	v_mfma_f32_16x16x32_bf16 v[122:125], v[152:155], v[184:187], v[122:125]
	v_mfma_f32_16x16x32_bf16 v[118:121], v[144:147], v[192:195], v[118:121]
	v_mfma_f32_16x16x32_bf16 v[114:117], v[152:155], v[192:195], v[114:117]
	v_mfma_f32_16x16x32_bf16 v[110:113], v[144:147], v[200:203], v[110:113]
	v_mfma_f32_16x16x32_bf16 v[106:109], v[152:155], v[200:203], v[106:109]
	v_mfma_f32_16x16x32_bf16 v[102:105], v[144:147], v[208:211], v[102:105]
	v_mfma_f32_16x16x32_bf16 v[98:101], v[152:155], v[208:211], v[98:101]
	v_mfma_f32_16x16x32_bf16 v[126:129], v[148:151], v[188:191], v[126:129]
	v_mfma_f32_16x16x32_bf16 v[122:125], v[156:159], v[188:191], v[122:125]
	v_mfma_f32_16x16x32_bf16 v[118:121], v[148:151], v[196:199], v[118:121]
	v_mfma_f32_16x16x32_bf16 v[114:117], v[156:159], v[196:199], v[114:117]
	v_mfma_f32_16x16x32_bf16 v[110:113], v[148:151], v[204:207], v[110:113]
	v_mfma_f32_16x16x32_bf16 v[106:109], v[156:159], v[204:207], v[106:109]
	v_mfma_f32_16x16x32_bf16 v[102:105], v[148:151], v[212:215], v[102:105]
	v_mfma_f32_16x16x32_bf16 v[98:101], v[156:159], v[212:215], v[98:101]
	v_mfma_f32_16x16x32_bf16 v[62:65], v[164:167], v[184:187], v[62:65]
	v_mfma_f32_16x16x32_bf16 v[58:61], v[172:175], v[184:187], v[58:61]
	v_mfma_f32_16x16x32_bf16 v[54:57], v[164:167], v[192:195], v[54:57]
	v_mfma_f32_16x16x32_bf16 v[50:53], v[172:175], v[192:195], v[50:53]
	v_mfma_f32_16x16x32_bf16 v[46:49], v[164:167], v[200:203], v[46:49]
	v_mfma_f32_16x16x32_bf16 v[42:45], v[172:175], v[200:203], v[42:45]
	v_mfma_f32_16x16x32_bf16 v[38:41], v[164:167], v[208:211], v[38:41]
	v_mfma_f32_16x16x32_bf16 v[34:37], v[172:175], v[208:211], v[34:37]
	v_mfma_f32_16x16x32_bf16 v[62:65], v[168:171], v[188:191], v[62:65]
	v_mfma_f32_16x16x32_bf16 v[58:61], v[180:183], v[188:191], v[58:61]
	v_mfma_f32_16x16x32_bf16 v[54:57], v[168:171], v[196:199], v[54:57]
	v_mfma_f32_16x16x32_bf16 v[50:53], v[180:183], v[196:199], v[50:53]
	v_mfma_f32_16x16x32_bf16 v[46:49], v[168:171], v[204:207], v[46:49]
	v_mfma_f32_16x16x32_bf16 v[42:45], v[180:183], v[204:207], v[42:45]
	v_mfma_f32_16x16x32_bf16 v[38:41], v[168:171], v[212:215], v[38:41]
	v_mfma_f32_16x16x32_bf16 v[34:37], v[180:183], v[212:215], v[34:37]
	s_barrier
	s_setprio 0
	s_add_i32 s0, s64, s61
	v_lshl_add_u64 v[216:217], s[24:25], 0, v[132:133]
	s_mov_b32 m0, s0
	ds_read_b128 v[184:187], v163 offset:16384
	ds_read_b128 v[188:191], v163 offset:17408
	ds_read_b128 v[192:195], v163 offset:18432
	ds_read_b128 v[196:199], v163 offset:19456
	ds_read_b128 v[200:203], v163 offset:20480
	ds_read_b128 v[204:207], v163 offset:21504
	ds_read_b128 v[208:211], v163 offset:22528
	ds_read_b128 v[212:215], v163 offset:23552
	global_load_lds_dwordx4 v[216:217], off
	s_add_i32 m0, s0, 0x2000
	s_add_u32 s0, s24, 0x80000
	v_lshl_add_u64 v[218:219], s[24:25], 0, v[136:137]
	s_addc_u32 s1, s25, 0
	s_add_i32 s64, s65, s61
	global_load_lds_dwordx4 v[218:219], off
	v_lshl_add_u64 v[220:221], s[0:1], 0, v[132:133]
	s_mov_b32 m0, s64
	v_lshl_add_u64 v[222:223], s[28:29], 0, v[134:135]
	global_load_lds_dwordx4 v[220:221], off
	v_lshl_add_u64 v[220:221], s[0:1], 0, v[136:137]
	s_add_i32 m0, s64, 0x2000
	s_nop 0
	global_load_lds_dwordx4 v[220:221], off
	v_lshl_add_u64 v[220:221], s[28:29], 0, v[130:131]
	s_mov_b32 m0, s19
	s_nop 0
	global_load_lds_dwordx4 v[220:221], off
	s_mov_b32 m0, s35
	s_nop 0
	global_load_lds_dwordx4 v[222:223], off
	s_waitcnt vmcnt(8)
	s_waitcnt lgkmcnt(0)
	s_setprio 1
	s_barrier
; #define PG8_STAGE(bufoff, gbase, voff) do { _Pragma("unroll") for (int _i = 0; _i < 2; ++_i) \
;         __builtin_amdgcn_global_load_lds((const unsigned*)((const char*)(gbase) + (voff)[_i]), (LAS unsigned*)(lds + (bufoff) + ldsw + _i * 8192), 16, 0, 0); } while (0)
; #define PG8_LDA(dst, b, h) do { _Pragma("unroll") for (int m = 0; m < 4; ++m) _Pragma("unroll") for (int k = 0; k < 2; ++k) dst[m][k] = *(const LAS bf16x8*)(lds + PG8_SA(b, h) + aoff + m * 2048 + k * 1024); } while (0)
; #define PG8_LDB(dst, b, h) do { _Pragma("unroll") for (int n = 0; n < 2; ++n) _Pragma("unroll") for (int k = 0; k < 2; ++k) dst[n][k] = *(const LAS bf16x8*)(lds + PG8_SB(b, h) + boff + n * 2048 + k * 1024); } while (0)
; #define PG8_MMA(ai, bj, At, Bt) do { __builtin_amdgcn_s_setprio(1); _Pragma("unroll") for (int m = 0; m < 4; ++m) _Pragma("unroll") for (int n = 0; n < 2; ++n) _Pragma("unroll") for (int k = 0; k < 2; ++k) \
;         acc[ai][bj][m][n] = __builtin_amdgcn_mfma_f32_16x16x32_bf16(Bt[n][k], At[m][k], acc[ai][bj][m][n], 0, 0, 0); __builtin_amdgcn_s_setprio(0); } while (0)
; #define PG8_WAIT_V(n) asm volatile("s_waitcnt vmcnt(" #n ")" ::: "memory")
; #define PG8_WAIT_L(n) asm volatile("s_waitcnt lgkmcnt(" #n ")" ::: "memory")
; #define PG8_BAR __builtin_amdgcn_s_barrier()
; #define PG8_SCHED __builtin_amdgcn_sched_barrier(0)
; template <class Epi, class Sched, int LDA, int LDB, bool ALIGN_EPI = true>
; __device__ __forceinline__ void gemm_phase(LAS unsigned char* lds, const Gemm g, const Sched& S, const Epi& E, int wave) {
;     ...
;             PG8_WAIT_V(8); PG8_WAIT_L(0); PG8_BAR; PG8_MMA(1, 0, At, B0); PG8_MMA(1, 1, At, B1); PG8_BAR; PG8_SCHED;
;             PG8_LDB(B0, 1, 0); PG8_LDB(B1, 1, 1); PG8_SCHED; PG8_LDA(At, 1, 0); PG8_STAGE(PG8_SA(0, 1), a2 + hstepA, voffA);
;             PG8_WAIT_V(8); PG8_WAIT_L(0); PG8_BAR; PG8_MMA(0, 0, At, B0); PG8_MMA(0, 1, At, B1); PG8_BAR; PG8_SCHED;
	v_mfma_f32_16x16x32_bf16 v[94:97], v[144:147], v[184:187], v[94:97]
	v_mfma_f32_16x16x32_bf16 v[90:93], v[152:155], v[184:187], v[90:93]
	v_mfma_f32_16x16x32_bf16 v[86:89], v[144:147], v[192:195], v[86:89]
	v_mfma_f32_16x16x32_bf16 v[82:85], v[152:155], v[192:195], v[82:85]
	v_mfma_f32_16x16x32_bf16 v[78:81], v[144:147], v[200:203], v[78:81]
	v_mfma_f32_16x16x32_bf16 v[74:77], v[152:155], v[200:203], v[74:77]
	v_mfma_f32_16x16x32_bf16 v[70:73], v[144:147], v[208:211], v[70:73]
	v_mfma_f32_16x16x32_bf16 v[66:69], v[152:155], v[208:211], v[66:69]
	v_mfma_f32_16x16x32_bf16 v[94:97], v[148:151], v[188:191], v[94:97]
	v_mfma_f32_16x16x32_bf16 v[90:93], v[156:159], v[188:191], v[90:93]
	v_mfma_f32_16x16x32_bf16 v[86:89], v[148:151], v[196:199], v[86:89]
	v_mfma_f32_16x16x32_bf16 v[82:85], v[156:159], v[196:199], v[82:85]
	v_mfma_f32_16x16x32_bf16 v[78:81], v[148:151], v[204:207], v[78:81]
	v_mfma_f32_16x16x32_bf16 v[74:77], v[156:159], v[204:207], v[74:77]
	v_mfma_f32_16x16x32_bf16 v[70:73], v[148:151], v[212:215], v[70:73]
	v_mfma_f32_16x16x32_bf16 v[66:69], v[156:159], v[212:215], v[66:69]
	v_mfma_f32_16x16x32_bf16 v[30:33], v[164:167], v[184:187], v[30:33]
	v_mfma_f32_16x16x32_bf16 v[26:29], v[172:175], v[184:187], v[26:29]
	v_mfma_f32_16x16x32_bf16 v[22:25], v[164:167], v[192:195], v[22:25]
	v_mfma_f32_16x16x32_bf16 v[18:21], v[172:175], v[192:195], v[18:21]
	v_mfma_f32_16x16x32_bf16 v[14:17], v[164:167], v[200:203], v[14:17]
	v_mfma_f32_16x16x32_bf16 v[10:13], v[172:175], v[200:203], v[10:13]
	v_mfma_f32_16x16x32_bf16 v[6:9], v[164:167], v[208:211], v[6:9]
	v_mfma_f32_16x16x32_bf16 v[2:5], v[172:175], v[208:211], v[2:5]
	v_mfma_f32_16x16x32_bf16 v[30:33], v[168:171], v[188:191], v[30:33]
	v_mfma_f32_16x16x32_bf16 v[26:29], v[180:183], v[188:191], v[26:29]
	v_mfma_f32_16x16x32_bf16 v[22:25], v[168:171], v[196:199], v[22:25]
	v_mfma_f32_16x16x32_bf16 v[18:21], v[180:183], v[196:199], v[18:21]
	v_mfma_f32_16x16x32_bf16 v[14:17], v[168:171], v[204:207], v[14:17]
	v_mfma_f32_16x16x32_bf16 v[10:13], v[180:183], v[204:207], v[10:13]
	v_mfma_f32_16x16x32_bf16 v[6:9], v[168:171], v[212:215], v[6:9]
	v_mfma_f32_16x16x32_bf16 v[2:5], v[180:183], v[212:215], v[2:5]
	s_barrier
	s_setprio 0
	ds_read_b128 v[184:187], v163 offset:32768
	ds_read_b128 v[188:191], v163 offset:33792
	ds_read_b128 v[192:195], v163 offset:34816
	ds_read_b128 v[196:199], v163 offset:35840
	ds_read_b128 v[200:203], v163 offset:36864
	ds_read_b128 v[204:207], v163 offset:37888
	ds_read_b128 v[208:211], v163 offset:38912
	ds_read_b128 v[212:215], v163 offset:39936
	s_add_i32 s64, 0, 0x18000
	v_add_u32_e32 v0, s64, v161
	s_add_i32 s65, 0, 0x1c000
	ds_read_b128 v[144:147], v0
	ds_read_b128 v[148:151], v0 offset:1024
	ds_read_b128 v[152:155], v0 offset:2048
	ds_read_b128 v[156:159], v0 offset:3072
	v_add_u32_e32 v0, s65, v161
	ds_read_b128 v[164:167], v0
	ds_read_b128 v[168:171], v0 offset:1024
	ds_read_b128 v[172:175], v0 offset:2048
	ds_read_b128 v[180:183], v0 offset:3072
	s_add_u32 s0, s28, 0x84000
	s_addc_u32 s1, s29, 0
	s_mov_b32 m0, s36
	v_lshl_add_u64 v[224:225], s[0:1], 0, v[130:131]
	global_load_lds_dwordx4 v[224:225], off
	v_lshl_add_u64 v[224:225], s[0:1], 0, v[134:135]
	s_mov_b32 m0, s37
	s_nop 0
	global_load_lds_dwordx4 v[224:225], off
	s_waitcnt vmcnt(8)
	s_waitcnt lgkmcnt(0)
	s_setprio 1
	s_barrier
	v_mfma_f32_16x16x32_bf16 v[126:129], v[144:147], v[184:187], v[126:129]
	v_mfma_f32_16x16x32_bf16 v[122:125], v[152:155], v[184:187], v[122:125]
	v_mfma_f32_16x16x32_bf16 v[118:121], v[144:147], v[192:195], v[118:121]
	v_mfma_f32_16x16x32_bf16 v[114:117], v[152:155], v[192:195], v[114:117]
	v_mfma_f32_16x16x32_bf16 v[110:113], v[144:147], v[200:203], v[110:113]
	v_mfma_f32_16x16x32_bf16 v[106:109], v[152:155], v[200:203], v[106:109]
	v_mfma_f32_16x16x32_bf16 v[102:105], v[144:147], v[208:211], v[102:105]
	v_mfma_f32_16x16x32_bf16 v[98:101], v[152:155], v[208:211], v[98:101]
	v_mfma_f32_16x16x32_bf16 v[126:129], v[148:151], v[188:191], v[126:129]
	v_mfma_f32_16x16x32_bf16 v[122:125], v[156:159], v[188:191], v[122:125]
	v_mfma_f32_16x16x32_bf16 v[118:121], v[148:151], v[196:199], v[118:121]
	v_mfma_f32_16x16x32_bf16 v[114:117], v[156:159], v[196:199], v[114:117]
	v_mfma_f32_16x16x32_bf16 v[110:113], v[148:151], v[204:207], v[110:113]
	v_mfma_f32_16x16x32_bf16 v[106:109], v[156:159], v[204:207], v[106:109]
	v_mfma_f32_16x16x32_bf16 v[102:105], v[148:151], v[212:215], v[102:105]
	v_mfma_f32_16x16x32_bf16 v[98:101], v[156:159], v[212:215], v[98:101]
	v_mfma_f32_16x16x32_bf16 v[62:65], v[164:167], v[184:187], v[62:65]
	v_mfma_f32_16x16x32_bf16 v[58:61], v[172:175], v[184:187], v[58:61]
	v_mfma_f32_16x16x32_bf16 v[54:57], v[164:167], v[192:195], v[54:57]
	v_mfma_f32_16x16x32_bf16 v[50:53], v[172:175], v[192:195], v[50:53]
	v_mfma_f32_16x16x32_bf16 v[46:49], v[164:167], v[200:203], v[46:49]
	v_mfma_f32_16x16x32_bf16 v[42:45], v[172:175], v[200:203], v[42:45]
	v_mfma_f32_16x16x32_bf16 v[38:41], v[164:167], v[208:211], v[38:41]
	v_mfma_f32_16x16x32_bf16 v[34:37], v[172:175], v[208:211], v[34:37]
	v_mfma_f32_16x16x32_bf16 v[62:65], v[168:171], v[188:191], v[62:65]
	v_mfma_f32_16x16x32_bf16 v[58:61], v[180:183], v[188:191], v[58:61]
	v_mfma_f32_16x16x32_bf16 v[54:57], v[168:171], v[196:199], v[54:57]
	v_mfma_f32_16x16x32_bf16 v[50:53], v[180:183], v[196:199], v[50:53]
	v_mfma_f32_16x16x32_bf16 v[46:49], v[168:171], v[204:207], v[46:49]
	v_mfma_f32_16x16x32_bf16 v[42:45], v[180:183], v[204:207], v[42:45]
	v_mfma_f32_16x16x32_bf16 v[38:41], v[168:171], v[212:215], v[38:41]
	v_mfma_f32_16x16x32_bf16 v[34:37], v[180:183], v[212:215], v[34:37]
	s_barrier
; #define PG8_STAGE(bufoff, gbase, voff) do { _Pragma("unroll") for (int _i = 0; _i < 2; ++_i) \
;         __builtin_amdgcn_global_load_lds((const unsigned*)((const char*)(gbase) + (voff)[_i]), (LAS unsigned*)(lds + (bufoff) + ldsw + _i * 8192), 16, 0, 0); } while (0)
; #define PG8_LDA(dst, b, h) do { _Pragma("unroll") for (int m = 0; m < 4; ++m) _Pragma("unroll") for (int k = 0; k < 2; ++k) dst[m][k] = *(const LAS bf16x8*)(lds + PG8_SA(b, h) + aoff + m * 2048 + k * 1024); } while (0)
; #define PG8_MMA(ai, bj, At, Bt) do { __builtin_amdgcn_s_setprio(1); _Pragma("unroll") for (int m = 0; m < 4; ++m) _Pragma("unroll") for (int n = 0; n < 2; ++n) _Pragma("unroll") for (int k = 0; k < 2; ++k) \
;         acc[ai][bj][m][n] = __builtin_amdgcn_mfma_f32_16x16x32_bf16(Bt[n][k], At[m][k], acc[ai][bj][m][n], 0, 0, 0); __builtin_amdgcn_s_setprio(0); } while (0)
; #define PG8_WAIT_V(n) asm volatile("s_waitcnt vmcnt(" #n ")" ::: "memory")
; #define PG8_WAIT_L(n) asm volatile("s_waitcnt lgkmcnt(" #n ")" ::: "memory")
; #define PG8_BAR __builtin_amdgcn_s_barrier()
; #define PG8_SCHED __builtin_amdgcn_sched_barrier(0)
; template <class Epi, class Sched, int LDA, int LDB, bool ALIGN_EPI = true>
; __device__ __forceinline__ void gemm_phase(LAS unsigned char* lds, const Gemm g, const Sched& S, const Epi& E, int wave) {
;     ...
;             PG8_LDA(At, 1, 1); PG8_STAGE(PG8_SB(1, 0), b3, voffB); PG8_STAGE(PG8_SB(1, 1), b3 + hstepB, voffB); PG8_STAGE(PG8_SA(1, 0), a3, voffA);
;             PG8_WAIT_V(8); PG8_WAIT_L(0); PG8_BAR; PG8_MMA(1, 0, At, B0); PG8_MMA(1, 1, At, B1); PG8_BAR; PG8_SCHED;
;         }
	s_setprio 0
	s_add_i32 s0, s64, s61
	v_lshl_add_u64 v[216:217], v[216:217], 0, s[70:71]
	s_mov_b32 m0, s0
	ds_read_b128 v[184:187], v163 offset:49152
	ds_read_b128 v[188:191], v163 offset:50176
	ds_read_b128 v[192:195], v163 offset:51200
	ds_read_b128 v[196:199], v163 offset:52224
	ds_read_b128 v[200:203], v163 offset:53248
	ds_read_b128 v[204:207], v163 offset:54272
	ds_read_b128 v[208:211], v163 offset:55296
	ds_read_b128 v[212:215], v163 offset:56320
	global_load_lds_dwordx4 v[216:217], off
	s_add_i32 m0, s0, 0x2000
	s_add_u32 s0, s24, 0x80080
	v_lshl_add_u64 v[216:217], v[218:219], 0, s[70:71]
	s_addc_u32 s1, s25, 0
	s_add_i32 s24, s65, s61
	global_load_lds_dwordx4 v[216:217], off
	v_lshl_add_u64 v[216:217], s[0:1], 0, v[132:133]
	s_mov_b32 m0, s24
	s_nop 0
	global_load_lds_dwordx4 v[216:217], off
	v_lshl_add_u64 v[216:217], s[0:1], 0, v[136:137]
	s_add_i32 m0, s24, 0x2000
	s_nop 0
	global_load_lds_dwordx4 v[216:217], off
	v_lshl_add_u64 v[216:217], v[220:221], 0, s[70:71]
	s_mov_b32 m0, s38
	s_nop 0
	global_load_lds_dwordx4 v[216:217], off
	v_lshl_add_u64 v[216:217], v[222:223], 0, s[70:71]
	s_mov_b32 m0, s39
	s_nop 0
	global_load_lds_dwordx4 v[216:217], off
	s_waitcnt vmcnt(8)
	s_waitcnt lgkmcnt(0)
	s_setprio 1
	s_barrier
	v_mfma_f32_16x16x32_bf16 v[94:97], v[144:147], v[184:187], v[94:97]
	v_mfma_f32_16x16x32_bf16 v[90:93], v[152:155], v[184:187], v[90:93]
	v_mfma_f32_16x16x32_bf16 v[86:89], v[144:147], v[192:195], v[86:89]
	v_mfma_f32_16x16x32_bf16 v[82:85], v[152:155], v[192:195], v[82:85]
	v_mfma_f32_16x16x32_bf16 v[78:81], v[144:147], v[200:203], v[78:81]
	v_mfma_f32_16x16x32_bf16 v[74:77], v[152:155], v[200:203], v[74:77]
	v_mfma_f32_16x16x32_bf16 v[70:73], v[144:147], v[208:211], v[70:73]
	v_mfma_f32_16x16x32_bf16 v[66:69], v[152:155], v[208:211], v[66:69]
	v_mfma_f32_16x16x32_bf16 v[94:97], v[148:151], v[188:191], v[94:97]
	v_mfma_f32_16x16x32_bf16 v[90:93], v[156:159], v[188:191], v[90:93]
	v_mfma_f32_16x16x32_bf16 v[86:89], v[148:151], v[196:199], v[86:89]
	v_mfma_f32_16x16x32_bf16 v[82:85], v[156:159], v[196:199], v[82:85]
	v_mfma_f32_16x16x32_bf16 v[78:81], v[148:151], v[204:207], v[78:81]
	v_mfma_f32_16x16x32_bf16 v[74:77], v[156:159], v[204:207], v[74:77]
	v_mfma_f32_16x16x32_bf16 v[70:73], v[148:151], v[212:215], v[70:73]
	v_mfma_f32_16x16x32_bf16 v[66:69], v[156:159], v[212:215], v[66:69]
	v_mfma_f32_16x16x32_bf16 v[30:33], v[164:167], v[184:187], v[30:33]
	v_mfma_f32_16x16x32_bf16 v[26:29], v[172:175], v[184:187], v[26:29]
	v_mfma_f32_16x16x32_bf16 v[22:25], v[164:167], v[192:195], v[22:25]
	v_mfma_f32_16x16x32_bf16 v[18:21], v[172:175], v[192:195], v[18:21]
	v_mfma_f32_16x16x32_bf16 v[14:17], v[164:167], v[200:203], v[14:17]
	v_mfma_f32_16x16x32_bf16 v[10:13], v[172:175], v[200:203], v[10:13]
	v_mfma_f32_16x16x32_bf16 v[6:9], v[164:167], v[208:211], v[6:9]
	v_mfma_f32_16x16x32_bf16 v[2:5], v[172:175], v[208:211], v[2:5]
	v_mfma_f32_16x16x32_bf16 v[30:33], v[168:171], v[188:191], v[30:33]
	v_mfma_f32_16x16x32_bf16 v[26:29], v[180:183], v[188:191], v[26:29]
	v_mfma_f32_16x16x32_bf16 v[22:25], v[168:171], v[196:199], v[22:25]
	v_mfma_f32_16x16x32_bf16 v[18:21], v[180:183], v[196:199], v[18:21]
	v_mfma_f32_16x16x32_bf16 v[14:17], v[168:171], v[204:207], v[14:17]
	v_mfma_f32_16x16x32_bf16 v[10:13], v[180:183], v[204:207], v[10:13]
	v_mfma_f32_16x16x32_bf16 v[6:9], v[168:171], v[212:215], v[6:9]
	v_mfma_f32_16x16x32_bf16 v[2:5], v[180:183], v[212:215], v[2:5]
	s_barrier
	s_setprio 0
	s_add_i32 s59, s59, 2
	s_add_u32 s49, s49, 0x100
	s_addc_u32 s58, s58, 0
	s_cmp_gt_u32 s59, 29
	s_mov_b64 s[0:1], s[2:3]
	s_cbranch_scc0 .LBB0_2254
	v_readlane_b32 s0, v252, 14
	v_readlane_b32 s1, v252, 15
	s_and_b64 vcc, exec, s[0:1]
	s_cbranch_vccz .LBB0_2257
	s_barrier

; #define PG8_STAGE(bufoff, gbase, voff) do { _Pragma("unroll") for (int _i = 0; _i < 2; ++_i) \
;         __builtin_amdgcn_global_load_lds((const unsigned*)((const char*)(gbase) + (voff)[_i]), (LAS unsigned*)(lds + (bufoff) + ldsw + _i * 8192), 16, 0, 0); } while (0)
; #define PG8_LDA(dst, b, h) do { _Pragma("unroll") for (int m = 0; m < 4; ++m) _Pragma("unroll") for (int k = 0; k < 2; ++k) dst[m][k] = *(const LAS bf16x8*)(lds + PG8_SA(b, h) + aoff + m * 2048 + k * 1024); } while (0)
; #define PG8_LDB(dst, b, h) do { _Pragma("unroll") for (int n = 0; n < 2; ++n) _Pragma("unroll") for (int k = 0; k < 2; ++k) dst[n][k] = *(const LAS bf16x8*)(lds + PG8_SB(b, h) + boff + n * 2048 + k * 1024); } while (0)
; #define PG8_MMA(ai, bj, At, Bt) do { __builtin_amdgcn_s_setprio(1); _Pragma("unroll") for (int m = 0; m < 4; ++m) _Pragma("unroll") for (int n = 0; n < 2; ++n) _Pragma("unroll") for (int k = 0; k < 2; ++k) \
;         acc[ai][bj][m][n] = __builtin_amdgcn_mfma_f32_16x16x32_bf16(Bt[n][k], At[m][k], acc[ai][bj][m][n], 0, 0, 0); __builtin_amdgcn_s_setprio(0); } while (0)
; #define PG8_WAIT_V(n) asm volatile("s_waitcnt vmcnt(" #n ")" ::: "memory")
; #define PG8_WAIT_L(n) asm volatile("s_waitcnt lgkmcnt(" #n ")" ::: "memory")
; #define PG8_BAR __builtin_amdgcn_s_barrier()
; #define PG8_SCHED __builtin_amdgcn_sched_barrier(0)
; template <class Epi, class Sched, int LDA, int LDB, bool ALIGN_EPI = true>
; __device__ __forceinline__ void gemm_phase(LAS unsigned char* lds, const Gemm g, const Sched& S, const Epi& E, int wave) {
;     ...
;             const bool last = (t == nt - 2);
;             const char* a1 = cA + (size_t)(t + 1) * kstep;
;             const char* a2 = last ? nA : cA + (size_t)(t + 2) * kstep; const char* b2 = last ? nB : cB + (size_t)(t + 2) * kstep;
;             const char* a3 = a2 + kstep; const char* b3 = b2 + kstep;
;             PG8_LDB(B0, 0, 0); PG8_LDB(B1, 0, 1); PG8_SCHED; PG8_LDA(At, 0, 0); PG8_STAGE(PG8_SA(1, 1), a1 + hstepA, voffA);
;             PG8_WAIT_V(8); PG8_WAIT_L(0); PG8_BAR; PG8_MMA(0, 0, At, B0); PG8_MMA(0, 1, At, B1); PG8_BAR; PG8_SCHED;
;             PG8_LDA(At, 0, 1); PG8_STAGE(PG8_SB(0, 0), b2, voffB); PG8_STAGE(PG8_SB(0, 1), b2 + hstepB, voffB); PG8_STAGE(PG8_SA(0, 0), a2, voffA);
;             PG8_WAIT_V(8); PG8_WAIT_L(0); PG8_BAR; PG8_MMA(1, 0, At, B0); PG8_MMA(1, 1, At, B1); PG8_BAR; PG8_SCHED;
.LBB0_2415:
	ds_read_b128 v[184:187], v145
	ds_read_b128 v[188:191], v145 offset:1024
	ds_read_b128 v[192:195], v145 offset:2048
	ds_read_b128 v[196:199], v145 offset:3072
	ds_read_b128 v[200:203], v145 offset:4096
	ds_read_b128 v[204:207], v145 offset:5120
	ds_read_b128 v[208:211], v145 offset:6144
	ds_read_b128 v[212:215], v145 offset:7168
	s_add_u32 s12, s10, 0xfff80080
	s_addc_u32 s13, s11, -1
	s_add_i32 s39, 0, 0x10000
	s_cmp_eq_u32 s38, 28
	s_cselect_b32 s15, s1, s13
	s_cselect_b32 s14, s3, s12
	v_add_u32_e32 v140, s39, v143
	s_cselect_b32 s13, s7, s37
	s_cselect_b32 s12, s6, s36
	s_add_i32 s46, 0, 0x14000
	ds_read_b128 v[146:149], v140
	ds_read_b128 v[150:153], v140 offset:1024
	ds_read_b128 v[154:157], v140 offset:2048
	ds_read_b128 v[158:161], v140 offset:3072
	v_add_u32_e32 v140, s46, v143
	ds_read_b128 v[162:165], v140
	ds_read_b128 v[166:169], v140 offset:1024
	ds_read_b128 v[170:173], v140 offset:2048
	ds_read_b128 v[180:183], v140 offset:3072
	v_lshl_add_u64 v[140:141], s[10:11], 0, v[136:137]
	s_add_i32 m0, s18, 0xc000
	s_nop 0
	global_load_lds_dwordx4 v[140:141], off
	v_lshl_add_u64 v[140:141], s[10:11], 0, v[138:139]
	s_add_i32 m0, s18, 0xe000
	s_nop 0
	global_load_lds_dwordx4 v[140:141], off
	s_waitcnt vmcnt(8)
	s_waitcnt lgkmcnt(0)
	s_setprio 1
	s_barrier
	v_mfma_f32_16x16x32_bf16 v[126:129], v[146:149], v[184:187], v[126:129]
	v_mfma_f32_16x16x32_bf16 v[122:125], v[154:157], v[184:187], v[122:125]
	v_mfma_f32_16x16x32_bf16 v[114:117], v[146:149], v[192:195], v[114:117]
	v_mfma_f32_16x16x32_bf16 v[106:109], v[154:157], v[192:195], v[106:109]
	v_mfma_f32_16x16x32_bf16 v[98:101], v[146:149], v[200:203], v[98:101]
	v_mfma_f32_16x16x32_bf16 v[90:93], v[154:157], v[200:203], v[90:93]
	v_mfma_f32_16x16x32_bf16 v[82:85], v[146:149], v[208:211], v[82:85]
	v_mfma_f32_16x16x32_bf16 v[74:77], v[154:157], v[208:211], v[74:77]
	v_mfma_f32_16x16x32_bf16 v[126:129], v[150:153], v[188:191], v[126:129]
	v_mfma_f32_16x16x32_bf16 v[122:125], v[158:161], v[188:191], v[122:125]
	v_mfma_f32_16x16x32_bf16 v[114:117], v[150:153], v[196:199], v[114:117]
	v_mfma_f32_16x16x32_bf16 v[106:109], v[158:161], v[196:199], v[106:109]
	v_mfma_f32_16x16x32_bf16 v[98:101], v[150:153], v[204:207], v[98:101]
	v_mfma_f32_16x16x32_bf16 v[90:93], v[158:161], v[204:207], v[90:93]
	v_mfma_f32_16x16x32_bf16 v[82:85], v[150:153], v[212:215], v[82:85]
	v_mfma_f32_16x16x32_bf16 v[74:77], v[158:161], v[212:215], v[74:77]
	v_mfma_f32_16x16x32_bf16 v[118:121], v[162:165], v[184:187], v[118:121]
	v_mfma_f32_16x16x32_bf16 v[110:113], v[170:173], v[184:187], v[110:113]
	v_mfma_f32_16x16x32_bf16 v[102:105], v[162:165], v[192:195], v[102:105]
	v_mfma_f32_16x16x32_bf16 v[94:97], v[170:173], v[192:195], v[94:97]
	v_mfma_f32_16x16x32_bf16 v[86:89], v[162:165], v[200:203], v[86:89]
	v_mfma_f32_16x16x32_bf16 v[78:81], v[170:173], v[200:203], v[78:81]
	v_mfma_f32_16x16x32_bf16 v[70:73], v[162:165], v[208:211], v[70:73]
	v_mfma_f32_16x16x32_bf16 v[66:69], v[170:173], v[208:211], v[66:69]
	v_mfma_f32_16x16x32_bf16 v[118:121], v[166:169], v[188:191], v[118:121]
	v_mfma_f32_16x16x32_bf16 v[110:113], v[180:183], v[188:191], v[110:113]
	v_mfma_f32_16x16x32_bf16 v[102:105], v[166:169], v[196:199], v[102:105]
	v_mfma_f32_16x16x32_bf16 v[94:97], v[180:183], v[196:199], v[94:97]
	v_mfma_f32_16x16x32_bf16 v[86:89], v[166:169], v[204:207], v[86:89]
	v_mfma_f32_16x16x32_bf16 v[78:81], v[180:183], v[204:207], v[78:81]
	v_mfma_f32_16x16x32_bf16 v[70:73], v[166:169], v[212:215], v[70:73]
	v_mfma_f32_16x16x32_bf16 v[66:69], v[180:183], v[212:215], v[66:69]
	s_barrier
	s_setprio 0
	s_add_i32 s39, s39, s47
	v_lshl_add_u64 v[140:141], s[12:13], 0, v[0:1]
	s_mov_b32 m0, s39
	ds_read_b128 v[184:187], v145 offset:16384
	ds_read_b128 v[188:191], v145 offset:17408
	ds_read_b128 v[192:195], v145 offset:18432
	ds_read_b128 v[196:199], v145 offset:19456
	ds_read_b128 v[200:203], v145 offset:20480
	ds_read_b128 v[204:207], v145 offset:21504
	ds_read_b128 v[208:211], v145 offset:22528
	ds_read_b128 v[212:215], v145 offset:23552
	global_load_lds_dwordx4 v[140:141], off
	s_add_i32 m0, s39, 0x2000
	s_add_u32 s44, s12, 0x84000
	v_lshl_add_u64 v[174:175], s[12:13], 0, v[134:135]
	s_addc_u32 s45, s13, 0
	s_add_i32 s39, s46, s47
	global_load_lds_dwordx4 v[174:175], off
	v_lshl_add_u64 v[216:217], s[44:45], 0, v[0:1]
	s_mov_b32 m0, s39
	v_lshl_add_u64 v[218:219], s[14:15], 0, v[132:133]
	global_load_lds_dwordx4 v[216:217], off
	v_lshl_add_u64 v[216:217], s[44:45], 0, v[134:135]
	s_add_i32 m0, s39, 0x2000
	s_nop 0
	global_load_lds_dwordx4 v[216:217], off
	v_lshl_add_u64 v[216:217], s[14:15], 0, v[130:131]
	s_mov_b32 m0, s18
	s_nop 0
	global_load_lds_dwordx4 v[216:217], off
	s_mov_b32 m0, s19
	s_nop 0
	global_load_lds_dwordx4 v[218:219], off
	s_waitcnt vmcnt(8)
	s_waitcnt lgkmcnt(0)
	s_setprio 1
	s_barrier
; #define PG8_STAGE(bufoff, gbase, voff) do { _Pragma("unroll") for (int _i = 0; _i < 2; ++_i) \
;         __builtin_amdgcn_global_load_lds((const unsigned*)((const char*)(gbase) + (voff)[_i]), (LAS unsigned*)(lds + (bufoff) + ldsw + _i * 8192), 16, 0, 0); } while (0)
; #define PG8_LDA(dst, b, h) do { _Pragma("unroll") for (int m = 0; m < 4; ++m) _Pragma("unroll") for (int k = 0; k < 2; ++k) dst[m][k] = *(const LAS bf16x8*)(lds + PG8_SA(b, h) + aoff + m * 2048 + k * 1024); } while (0)
; #define PG8_LDB(dst, b, h) do { _Pragma("unroll") for (int n = 0; n < 2; ++n) _Pragma("unroll") for (int k = 0; k < 2; ++k) dst[n][k] = *(const LAS bf16x8*)(lds + PG8_SB(b, h) + boff + n * 2048 + k * 1024); } while (0)
; #define PG8_MMA(ai, bj, At, Bt) do { __builtin_amdgcn_s_setprio(1); _Pragma("unroll") for (int m = 0; m < 4; ++m) _Pragma("unroll") for (int n = 0; n < 2; ++n) _Pragma("unroll") for (int k = 0; k < 2; ++k) \
;         acc[ai][bj][m][n] = __builtin_amdgcn_mfma_f32_16x16x32_bf16(Bt[n][k], At[m][k], acc[ai][bj][m][n], 0, 0, 0); __builtin_amdgcn_s_setprio(0); } while (0)
; #define PG8_WAIT_V(n) asm volatile("s_waitcnt vmcnt(" #n ")" ::: "memory")
; #define PG8_WAIT_L(n) asm volatile("s_waitcnt lgkmcnt(" #n ")" ::: "memory")
; #define PG8_BAR __builtin_amdgcn_s_barrier()
; #define PG8_SCHED __builtin_amdgcn_sched_barrier(0)
; template <class Epi, class Sched, int LDA, int LDB, bool ALIGN_EPI = true>
; __device__ __forceinline__ void gemm_phase(LAS unsigned char* lds, const Gemm g, const Sched& S, const Epi& E, int wave) {
;     ...
;             PG8_WAIT_V(8); PG8_WAIT_L(0); PG8_BAR; PG8_MMA(1, 0, At, B0); PG8_MMA(1, 1, At, B1); PG8_BAR; PG8_SCHED;
;             PG8_LDB(B0, 1, 0); PG8_LDB(B1, 1, 1); PG8_SCHED; PG8_LDA(At, 1, 0); PG8_STAGE(PG8_SA(0, 1), a2 + hstepA, voffA);
;             PG8_WAIT_V(8); PG8_WAIT_L(0); PG8_BAR; PG8_MMA(0, 0, At, B0); PG8_MMA(0, 1, At, B1); PG8_BAR; PG8_SCHED;
	v_mfma_f32_16x16x32_bf16 v[62:65], v[146:149], v[184:187], v[62:65]
	v_mfma_f32_16x16x32_bf16 v[58:61], v[154:157], v[184:187], v[58:61]
	v_mfma_f32_16x16x32_bf16 v[50:53], v[146:149], v[192:195], v[50:53]
	v_mfma_f32_16x16x32_bf16 v[42:45], v[154:157], v[192:195], v[42:45]
	v_mfma_f32_16x16x32_bf16 v[34:37], v[146:149], v[200:203], v[34:37]
	v_mfma_f32_16x16x32_bf16 v[26:29], v[154:157], v[200:203], v[26:29]
	v_mfma_f32_16x16x32_bf16 v[18:21], v[146:149], v[208:211], v[18:21]
	v_mfma_f32_16x16x32_bf16 v[10:13], v[154:157], v[208:211], v[10:13]
	v_mfma_f32_16x16x32_bf16 v[62:65], v[150:153], v[188:191], v[62:65]
	v_mfma_f32_16x16x32_bf16 v[58:61], v[158:161], v[188:191], v[58:61]
	v_mfma_f32_16x16x32_bf16 v[50:53], v[150:153], v[196:199], v[50:53]
	v_mfma_f32_16x16x32_bf16 v[42:45], v[158:161], v[196:199], v[42:45]
	v_mfma_f32_16x16x32_bf16 v[34:37], v[150:153], v[204:207], v[34:37]
	v_mfma_f32_16x16x32_bf16 v[26:29], v[158:161], v[204:207], v[26:29]
	v_mfma_f32_16x16x32_bf16 v[18:21], v[150:153], v[212:215], v[18:21]
	v_mfma_f32_16x16x32_bf16 v[10:13], v[158:161], v[212:215], v[10:13]
	v_mfma_f32_16x16x32_bf16 v[54:57], v[162:165], v[184:187], v[54:57]
	v_mfma_f32_16x16x32_bf16 v[46:49], v[170:173], v[184:187], v[46:49]
	v_mfma_f32_16x16x32_bf16 v[38:41], v[162:165], v[192:195], v[38:41]
	v_mfma_f32_16x16x32_bf16 v[30:33], v[170:173], v[192:195], v[30:33]
	v_mfma_f32_16x16x32_bf16 v[22:25], v[162:165], v[200:203], v[22:25]
	v_mfma_f32_16x16x32_bf16 v[14:17], v[170:173], v[200:203], v[14:17]
	v_mfma_f32_16x16x32_bf16 v[6:9], v[162:165], v[208:211], v[6:9]
	v_mfma_f32_16x16x32_bf16 v[2:5], v[170:173], v[208:211], v[2:5]
	v_mfma_f32_16x16x32_bf16 v[54:57], v[166:169], v[188:191], v[54:57]
	v_mfma_f32_16x16x32_bf16 v[46:49], v[180:183], v[188:191], v[46:49]
	v_mfma_f32_16x16x32_bf16 v[38:41], v[166:169], v[196:199], v[38:41]
	v_mfma_f32_16x16x32_bf16 v[30:33], v[180:183], v[196:199], v[30:33]
	v_mfma_f32_16x16x32_bf16 v[22:25], v[166:169], v[204:207], v[22:25]
	v_mfma_f32_16x16x32_bf16 v[14:17], v[180:183], v[204:207], v[14:17]
	v_mfma_f32_16x16x32_bf16 v[6:9], v[166:169], v[212:215], v[6:9]
	v_mfma_f32_16x16x32_bf16 v[2:5], v[180:183], v[212:215], v[2:5]
	s_barrier
	s_setprio 0
	ds_read_b128 v[184:187], v145 offset:32768
	ds_read_b128 v[188:191], v145 offset:33792
	ds_read_b128 v[192:195], v145 offset:34816
	ds_read_b128 v[196:199], v145 offset:35840
	ds_read_b128 v[200:203], v145 offset:36864
	ds_read_b128 v[204:207], v145 offset:37888
	ds_read_b128 v[208:211], v145 offset:38912
	ds_read_b128 v[212:215], v145 offset:39936
	s_add_i32 s39, 0, 0x18000
	s_add_i32 s44, 0, 0x1c000
	v_add_u32_e32 v158, s39, v143
	v_add_u32_e32 v180, s44, v143
	ds_read_b128 v[146:149], v158
	ds_read_b128 v[150:153], v158 offset:1024
	ds_read_b128 v[154:157], v158 offset:2048
	ds_read_b128 v[158:161], v158 offset:3072
	ds_read_b128 v[162:165], v180
	ds_read_b128 v[166:169], v180 offset:1024
	ds_read_b128 v[170:173], v180 offset:2048
	ds_read_b128 v[180:183], v180 offset:3072
	s_add_u32 s14, s14, 0x80000
	s_addc_u32 s15, s15, 0
	s_mov_b32 m0, s24
	v_lshl_add_u64 v[220:221], s[14:15], 0, v[130:131]
	global_load_lds_dwordx4 v[220:221], off
	v_lshl_add_u64 v[220:221], s[14:15], 0, v[132:133]
	s_mov_b32 m0, s25
	s_nop 0
	global_load_lds_dwordx4 v[220:221], off
	s_waitcnt vmcnt(8)
	s_waitcnt lgkmcnt(0)
	s_setprio 1
	s_barrier
	v_mfma_f32_16x16x32_bf16 v[126:129], v[146:149], v[184:187], v[126:129]
	v_mfma_f32_16x16x32_bf16 v[122:125], v[154:157], v[184:187], v[122:125]
	v_mfma_f32_16x16x32_bf16 v[114:117], v[146:149], v[192:195], v[114:117]
	v_mfma_f32_16x16x32_bf16 v[106:109], v[154:157], v[192:195], v[106:109]
	v_mfma_f32_16x16x32_bf16 v[98:101], v[146:149], v[200:203], v[98:101]
	v_mfma_f32_16x16x32_bf16 v[90:93], v[154:157], v[200:203], v[90:93]
	v_mfma_f32_16x16x32_bf16 v[82:85], v[146:149], v[208:211], v[82:85]
	v_mfma_f32_16x16x32_bf16 v[74:77], v[154:157], v[208:211], v[74:77]
	v_mfma_f32_16x16x32_bf16 v[126:129], v[150:153], v[188:191], v[126:129]
	v_mfma_f32_16x16x32_bf16 v[122:125], v[158:161], v[188:191], v[122:125]
	v_mfma_f32_16x16x32_bf16 v[114:117], v[150:153], v[196:199], v[114:117]
	v_mfma_f32_16x16x32_bf16 v[106:109], v[158:161], v[196:199], v[106:109]
	v_mfma_f32_16x16x32_bf16 v[98:101], v[150:153], v[204:207], v[98:101]
	v_mfma_f32_16x16x32_bf16 v[90:93], v[158:161], v[204:207], v[90:93]
	v_mfma_f32_16x16x32_bf16 v[82:85], v[150:153], v[212:215], v[82:85]
	v_mfma_f32_16x16x32_bf16 v[74:77], v[158:161], v[212:215], v[74:77]
	v_mfma_f32_16x16x32_bf16 v[118:121], v[162:165], v[184:187], v[118:121]
	v_mfma_f32_16x16x32_bf16 v[110:113], v[170:173], v[184:187], v[110:113]
	v_mfma_f32_16x16x32_bf16 v[102:105], v[162:165], v[192:195], v[102:105]
	v_mfma_f32_16x16x32_bf16 v[94:97], v[170:173], v[192:195], v[94:97]
	v_mfma_f32_16x16x32_bf16 v[86:89], v[162:165], v[200:203], v[86:89]
	v_mfma_f32_16x16x32_bf16 v[78:81], v[170:173], v[200:203], v[78:81]
	v_mfma_f32_16x16x32_bf16 v[70:73], v[162:165], v[208:211], v[70:73]
	v_mfma_f32_16x16x32_bf16 v[66:69], v[170:173], v[208:211], v[66:69]
	v_mfma_f32_16x16x32_bf16 v[118:121], v[166:169], v[188:191], v[118:121]
	v_mfma_f32_16x16x32_bf16 v[110:113], v[180:183], v[188:191], v[110:113]
	v_mfma_f32_16x16x32_bf16 v[102:105], v[166:169], v[196:199], v[102:105]
	v_mfma_f32_16x16x32_bf16 v[94:97], v[180:183], v[196:199], v[94:97]
	v_mfma_f32_16x16x32_bf16 v[86:89], v[166:169], v[204:207], v[86:89]
	v_mfma_f32_16x16x32_bf16 v[78:81], v[180:183], v[204:207], v[78:81]
	v_mfma_f32_16x16x32_bf16 v[70:73], v[166:169], v[212:215], v[70:73]
	v_mfma_f32_16x16x32_bf16 v[66:69], v[180:183], v[212:215], v[66:69]
	s_barrier
; #define PG8_STAGE(bufoff, gbase, voff) do { _Pragma("unroll") for (int _i = 0; _i < 2; ++_i) \
;         __builtin_amdgcn_global_load_lds((const unsigned*)((const char*)(gbase) + (voff)[_i]), (LAS unsigned*)(lds + (bufoff) + ldsw + _i * 8192), 16, 0, 0); } while (0)
; #define PG8_LDA(dst, b, h) do { _Pragma("unroll") for (int m = 0; m < 4; ++m) _Pragma("unroll") for (int k = 0; k < 2; ++k) dst[m][k] = *(const LAS bf16x8*)(lds + PG8_SA(b, h) + aoff + m * 2048 + k * 1024); } while (0)
; #define PG8_MMA(ai, bj, At, Bt) do { __builtin_amdgcn_s_setprio(1); _Pragma("unroll") for (int m = 0; m < 4; ++m) _Pragma("unroll") for (int n = 0; n < 2; ++n) _Pragma("unroll") for (int k = 0; k < 2; ++k) \
;         acc[ai][bj][m][n] = __builtin_amdgcn_mfma_f32_16x16x32_bf16(Bt[n][k], At[m][k], acc[ai][bj][m][n], 0, 0, 0); __builtin_amdgcn_s_setprio(0); } while (0)
; #define PG8_WAIT_V(n) asm volatile("s_waitcnt vmcnt(" #n ")" ::: "memory")
; #define PG8_WAIT_L(n) asm volatile("s_waitcnt lgkmcnt(" #n ")" ::: "memory")
; #define PG8_BAR __builtin_amdgcn_s_barrier()
; #define PG8_SCHED __builtin_amdgcn_sched_barrier(0)
; template <class Epi, class Sched, int LDA, int LDB, bool ALIGN_EPI = true>
; __device__ __forceinline__ void gemm_phase(LAS unsigned char* lds, const Gemm g, const Sched& S, const Epi& E, int wave) {
;     ...
;             PG8_LDA(At, 1, 1); PG8_STAGE(PG8_SB(1, 0), b3, voffB); PG8_STAGE(PG8_SB(1, 1), b3 + hstepB, voffB); PG8_STAGE(PG8_SA(1, 0), a3, voffA);
;             PG8_WAIT_V(8); PG8_WAIT_L(0); PG8_BAR; PG8_MMA(1, 0, At, B0); PG8_MMA(1, 1, At, B1); PG8_BAR; PG8_SCHED;
;         }
;         if constexpr (ALIGN_EPI) { if (wr == 0) PG8_BAR; }
	s_setprio 0
	s_add_i32 s14, s39, s47
	v_lshl_add_u64 v[140:141], v[140:141], 0, s[48:49]
	s_mov_b32 m0, s14
	ds_read_b128 v[184:187], v145 offset:49152
	ds_read_b128 v[188:191], v145 offset:50176
	ds_read_b128 v[192:195], v145 offset:51200
	ds_read_b128 v[196:199], v145 offset:52224
	ds_read_b128 v[200:203], v145 offset:53248
	ds_read_b128 v[204:207], v145 offset:54272
	ds_read_b128 v[208:211], v145 offset:55296
	ds_read_b128 v[212:215], v145 offset:56320
	global_load_lds_dwordx4 v[140:141], off
	s_add_i32 m0, s14, 0x2000
	s_add_u32 s12, s12, 0x84080
	v_lshl_add_u64 v[140:141], v[174:175], 0, s[48:49]
	s_addc_u32 s13, s13, 0
	s_add_i32 s14, s44, s47
	global_load_lds_dwordx4 v[140:141], off
	v_lshl_add_u64 v[140:141], s[12:13], 0, v[0:1]
	s_mov_b32 m0, s14
	s_nop 0
	global_load_lds_dwordx4 v[140:141], off
	v_lshl_add_u64 v[140:141], s[12:13], 0, v[134:135]
	s_add_i32 m0, s14, 0x2000
	s_nop 0
	global_load_lds_dwordx4 v[140:141], off
	v_lshl_add_u64 v[140:141], v[216:217], 0, s[48:49]
	s_mov_b32 m0, s26
	s_nop 0
	global_load_lds_dwordx4 v[140:141], off
	v_lshl_add_u64 v[140:141], v[218:219], 0, s[48:49]
	s_mov_b32 m0, s27
	s_nop 0
	global_load_lds_dwordx4 v[140:141], off
	s_waitcnt vmcnt(8)
	s_waitcnt lgkmcnt(0)
	s_setprio 1
	s_barrier
	v_mfma_f32_16x16x32_bf16 v[62:65], v[146:149], v[184:187], v[62:65]
	v_mfma_f32_16x16x32_bf16 v[58:61], v[154:157], v[184:187], v[58:61]
	v_mfma_f32_16x16x32_bf16 v[50:53], v[146:149], v[192:195], v[50:53]
	v_mfma_f32_16x16x32_bf16 v[42:45], v[154:157], v[192:195], v[42:45]
	v_mfma_f32_16x16x32_bf16 v[34:37], v[146:149], v[200:203], v[34:37]
	v_mfma_f32_16x16x32_bf16 v[26:29], v[154:157], v[200:203], v[26:29]
	v_mfma_f32_16x16x32_bf16 v[18:21], v[146:149], v[208:211], v[18:21]
	v_mfma_f32_16x16x32_bf16 v[10:13], v[154:157], v[208:211], v[10:13]
	v_mfma_f32_16x16x32_bf16 v[62:65], v[150:153], v[188:191], v[62:65]
	v_mfma_f32_16x16x32_bf16 v[58:61], v[158:161], v[188:191], v[58:61]
	v_mfma_f32_16x16x32_bf16 v[50:53], v[150:153], v[196:199], v[50:53]
	v_mfma_f32_16x16x32_bf16 v[42:45], v[158:161], v[196:199], v[42:45]
	v_mfma_f32_16x16x32_bf16 v[34:37], v[150:153], v[204:207], v[34:37]
	v_mfma_f32_16x16x32_bf16 v[26:29], v[158:161], v[204:207], v[26:29]
	v_mfma_f32_16x16x32_bf16 v[18:21], v[150:153], v[212:215], v[18:21]
	v_mfma_f32_16x16x32_bf16 v[10:13], v[158:161], v[212:215], v[10:13]
	v_mfma_f32_16x16x32_bf16 v[54:57], v[162:165], v[184:187], v[54:57]
	v_mfma_f32_16x16x32_bf16 v[46:49], v[170:173], v[184:187], v[46:49]
	v_mfma_f32_16x16x32_bf16 v[38:41], v[162:165], v[192:195], v[38:41]
	v_mfma_f32_16x16x32_bf16 v[30:33], v[170:173], v[192:195], v[30:33]
	v_mfma_f32_16x16x32_bf16 v[22:25], v[162:165], v[200:203], v[22:25]
	v_mfma_f32_16x16x32_bf16 v[14:17], v[170:173], v[200:203], v[14:17]
	v_mfma_f32_16x16x32_bf16 v[6:9], v[162:165], v[208:211], v[6:9]
	v_mfma_f32_16x16x32_bf16 v[2:5], v[170:173], v[208:211], v[2:5]
	v_mfma_f32_16x16x32_bf16 v[54:57], v[166:169], v[188:191], v[54:57]
	v_mfma_f32_16x16x32_bf16 v[46:49], v[180:183], v[188:191], v[46:49]
	v_mfma_f32_16x16x32_bf16 v[38:41], v[166:169], v[196:199], v[38:41]
	v_mfma_f32_16x16x32_bf16 v[30:33], v[180:183], v[196:199], v[30:33]
	v_mfma_f32_16x16x32_bf16 v[22:25], v[166:169], v[204:207], v[22:25]
	v_mfma_f32_16x16x32_bf16 v[14:17], v[180:183], v[204:207], v[14:17]
	v_mfma_f32_16x16x32_bf16 v[6:9], v[166:169], v[212:215], v[6:9]
	v_mfma_f32_16x16x32_bf16 v[2:5], v[180:183], v[212:215], v[2:5]
	s_barrier
	s_setprio 0
	s_add_i32 s38, s38, 2
	s_add_u32 s10, s10, 0x100
	s_addc_u32 s11, s11, 0
	s_add_u32 s36, s36, 0x100
	s_addc_u32 s37, s37, 0
	s_cmp_gt_u32 s38, 29
	s_cbranch_scc0 .LBB0_2415
	v_readlane_b32 s10, v252, 14
	v_readlane_b32 s11, v252, 15
	s_and_b64 vcc, exec, s[10:11]
	s_cbranch_vccz .LBB0_2418
	s_barrier

; #define PG8_STAGE(bufoff, gbase, voff) do { _Pragma("unroll") for (int _i = 0; _i < 2; ++_i) \
;         __builtin_amdgcn_global_load_lds((const unsigned*)((const char*)(gbase) + (voff)[_i]), (LAS unsigned*)(lds + (bufoff) + ldsw + _i * 8192), 16, 0, 0); } while (0)
; #define PG8_LDA(dst, b, h) do { _Pragma("unroll") for (int m = 0; m < 4; ++m) _Pragma("unroll") for (int k = 0; k < 2; ++k) dst[m][k] = *(const LAS bf16x8*)(lds + PG8_SA(b, h) + aoff + m * 2048 + k * 1024); } while (0)
; #define PG8_LDB(dst, b, h) do { _Pragma("unroll") for (int n = 0; n < 2; ++n) _Pragma("unroll") for (int k = 0; k < 2; ++k) dst[n][k] = *(const LAS bf16x8*)(lds + PG8_SB(b, h) + boff + n * 2048 + k * 1024); } while (0)
; #define PG8_MMA(ai, bj, At, Bt) do { __builtin_amdgcn_s_setprio(1); _Pragma("unroll") for (int m = 0; m < 4; ++m) _Pragma("unroll") for (int n = 0; n < 2; ++n) _Pragma("unroll") for (int k = 0; k < 2; ++k) \
;         acc[ai][bj][m][n] = __builtin_amdgcn_mfma_f32_16x16x32_bf16(Bt[n][k], At[m][k], acc[ai][bj][m][n], 0, 0, 0); __builtin_amdgcn_s_setprio(0); } while (0)
; #define PG8_WAIT_V(n) asm volatile("s_waitcnt vmcnt(" #n ")" ::: "memory")
; #define PG8_WAIT_L(n) asm volatile("s_waitcnt lgkmcnt(" #n ")" ::: "memory")
; #define PG8_BAR __builtin_amdgcn_s_barrier()
; #define PG8_SCHED __builtin_amdgcn_sched_barrier(0)
; template <class Epi, class Sched, int LDA, int LDB, bool ALIGN_EPI = true>
; __device__ __forceinline__ void gemm_phase(LAS unsigned char* lds, const Gemm g, const Sched& S, const Epi& E, int wave) {
;     ...
;             const bool last = (t == nt - 2);
;             const char* a1 = cA + (size_t)(t + 1) * kstep;
;             const char* a2 = last ? nA : cA + (size_t)(t + 2) * kstep; const char* b2 = last ? nB : cB + (size_t)(t + 2) * kstep;
;             const char* a3 = a2 + kstep; const char* b3 = b2 + kstep;
;             PG8_LDB(B0, 0, 0); PG8_LDB(B1, 0, 1); PG8_SCHED; PG8_LDA(At, 0, 0); PG8_STAGE(PG8_SA(1, 1), a1 + hstepA, voffA);
;             PG8_WAIT_V(8); PG8_WAIT_L(0); PG8_BAR; PG8_MMA(0, 0, At, B0); PG8_MMA(0, 1, At, B1); PG8_BAR; PG8_SCHED;
;             PG8_LDA(At, 0, 1); PG8_STAGE(PG8_SB(0, 0), b2, voffB); PG8_STAGE(PG8_SB(0, 1), b2 + hstepB, voffB); PG8_STAGE(PG8_SA(0, 0), a2, voffA);
.LBB0_2513:
	ds_read_b128 v[184:187], v145
	ds_read_b128 v[188:191], v145 offset:1024
	ds_read_b128 v[192:195], v145 offset:2048
	ds_read_b128 v[196:199], v145 offset:3072
	ds_read_b128 v[200:203], v145 offset:4096
	ds_read_b128 v[204:207], v145 offset:5120
	ds_read_b128 v[208:211], v145 offset:6144
	ds_read_b128 v[212:215], v145 offset:7168
	s_add_u32 s14, s12, 0xfff80080
	s_addc_u32 s15, s13, -1
	s_add_i32 s44, 0, 0x10000
	s_cmp_eq_u32 s39, 28
	s_cselect_b32 s17, s1, s15
	s_cselect_b32 s16, s3, s14
	v_add_u32_e32 v140, s44, v143
	s_cselect_b32 s15, s9, s38
	s_cselect_b32 s14, s8, s37
	s_add_i32 s46, 0, 0x14000
	ds_read_b128 v[146:149], v140
	ds_read_b128 v[150:153], v140 offset:1024
	ds_read_b128 v[154:157], v140 offset:2048
	ds_read_b128 v[158:161], v140 offset:3072
	v_add_u32_e32 v140, s46, v143
	ds_read_b128 v[162:165], v140
	ds_read_b128 v[166:169], v140 offset:1024
	ds_read_b128 v[170:173], v140 offset:2048
	ds_read_b128 v[180:183], v140 offset:3072
	v_lshl_add_u64 v[140:141], s[12:13], 0, v[136:137]
	s_add_i32 m0, s24, 0xc000
	s_nop 0
	global_load_lds_dwordx4 v[140:141], off
	v_lshl_add_u64 v[140:141], s[12:13], 0, v[138:139]
	s_add_i32 m0, s24, 0xe000
	s_nop 0
	global_load_lds_dwordx4 v[140:141], off
	s_waitcnt vmcnt(8)
	s_waitcnt lgkmcnt(0)
	s_setprio 1
	s_barrier
	v_mfma_f32_16x16x32_bf16 v[126:129], v[146:149], v[184:187], v[126:129]
	v_mfma_f32_16x16x32_bf16 v[122:125], v[154:157], v[184:187], v[122:125]
	v_mfma_f32_16x16x32_bf16 v[114:117], v[146:149], v[192:195], v[114:117]
	v_mfma_f32_16x16x32_bf16 v[106:109], v[154:157], v[192:195], v[106:109]
	v_mfma_f32_16x16x32_bf16 v[98:101], v[146:149], v[200:203], v[98:101]
	v_mfma_f32_16x16x32_bf16 v[90:93], v[154:157], v[200:203], v[90:93]
	v_mfma_f32_16x16x32_bf16 v[82:85], v[146:149], v[208:211], v[82:85]
	v_mfma_f32_16x16x32_bf16 v[74:77], v[154:157], v[208:211], v[74:77]
	v_mfma_f32_16x16x32_bf16 v[126:129], v[150:153], v[188:191], v[126:129]
	v_mfma_f32_16x16x32_bf16 v[122:125], v[158:161], v[188:191], v[122:125]
	v_mfma_f32_16x16x32_bf16 v[114:117], v[150:153], v[196:199], v[114:117]
	v_mfma_f32_16x16x32_bf16 v[106:109], v[158:161], v[196:199], v[106:109]
	v_mfma_f32_16x16x32_bf16 v[98:101], v[150:153], v[204:207], v[98:101]
	v_mfma_f32_16x16x32_bf16 v[90:93], v[158:161], v[204:207], v[90:93]
	v_mfma_f32_16x16x32_bf16 v[82:85], v[150:153], v[212:215], v[82:85]
	v_mfma_f32_16x16x32_bf16 v[74:77], v[158:161], v[212:215], v[74:77]
	v_mfma_f32_16x16x32_bf16 v[118:121], v[162:165], v[184:187], v[118:121]
	v_mfma_f32_16x16x32_bf16 v[110:113], v[170:173], v[184:187], v[110:113]
	v_mfma_f32_16x16x32_bf16 v[102:105], v[162:165], v[192:195], v[102:105]
	v_mfma_f32_16x16x32_bf16 v[94:97], v[170:173], v[192:195], v[94:97]
	v_mfma_f32_16x16x32_bf16 v[86:89], v[162:165], v[200:203], v[86:89]
	v_mfma_f32_16x16x32_bf16 v[78:81], v[170:173], v[200:203], v[78:81]
	v_mfma_f32_16x16x32_bf16 v[70:73], v[162:165], v[208:211], v[70:73]
	v_mfma_f32_16x16x32_bf16 v[66:69], v[170:173], v[208:211], v[66:69]
	v_mfma_f32_16x16x32_bf16 v[118:121], v[166:169], v[188:191], v[118:121]
	v_mfma_f32_16x16x32_bf16 v[110:113], v[180:183], v[188:191], v[110:113]
	v_mfma_f32_16x16x32_bf16 v[102:105], v[166:169], v[196:199], v[102:105]
	v_mfma_f32_16x16x32_bf16 v[94:97], v[180:183], v[196:199], v[94:97]
	v_mfma_f32_16x16x32_bf16 v[86:89], v[166:169], v[204:207], v[86:89]
	v_mfma_f32_16x16x32_bf16 v[78:81], v[180:183], v[204:207], v[78:81]
	v_mfma_f32_16x16x32_bf16 v[70:73], v[166:169], v[212:215], v[70:73]
	v_mfma_f32_16x16x32_bf16 v[66:69], v[180:183], v[212:215], v[66:69]
	s_barrier
	s_setprio 0
	s_add_i32 s44, s44, s47
	v_lshl_add_u64 v[140:141], s[14:15], 0, v[0:1]
	s_mov_b32 m0, s44
	ds_read_b128 v[184:187], v145 offset:16384
	ds_read_b128 v[188:191], v145 offset:17408
	ds_read_b128 v[192:195], v145 offset:18432
	ds_read_b128 v[196:199], v145 offset:19456
	ds_read_b128 v[200:203], v145 offset:20480
	ds_read_b128 v[204:207], v145 offset:21504
	ds_read_b128 v[208:211], v145 offset:22528
	ds_read_b128 v[212:215], v145 offset:23552
	global_load_lds_dwordx4 v[140:141], off
	s_add_i32 m0, s44, 0x2000
	s_add_u32 s44, s14, 0x84000
	v_lshl_add_u64 v[174:175], s[14:15], 0, v[134:135]
	s_addc_u32 s45, s15, 0
	s_add_i32 s46, s46, s47
	global_load_lds_dwordx4 v[174:175], off
	v_lshl_add_u64 v[216:217], s[44:45], 0, v[0:1]
	s_mov_b32 m0, s46
	v_lshl_add_u64 v[218:219], s[16:17], 0, v[132:133]
	global_load_lds_dwordx4 v[216:217], off
	v_lshl_add_u64 v[216:217], s[44:45], 0, v[134:135]
	s_add_i32 m0, s46, 0x2000
	s_nop 0
	global_load_lds_dwordx4 v[216:217], off
	v_lshl_add_u64 v[216:217], s[16:17], 0, v[130:131]
	s_mov_b32 m0, s24
	s_nop 0
	global_load_lds_dwordx4 v[216:217], off
	s_mov_b32 m0, s25
	s_nop 0
	global_load_lds_dwordx4 v[218:219], off
	s_waitcnt vmcnt(8)
	s_waitcnt lgkmcnt(0)
	s_setprio 1
	s_barrier
; #define PG8_STAGE(bufoff, gbase, voff) do { _Pragma("unroll") for (int _i = 0; _i < 2; ++_i) \
;         __builtin_amdgcn_global_load_lds((const unsigned*)((const char*)(gbase) + (voff)[_i]), (LAS unsigned*)(lds + (bufoff) + ldsw + _i * 8192), 16, 0, 0); } while (0)
; #define PG8_LDA(dst, b, h) do { _Pragma("unroll") for (int m = 0; m < 4; ++m) _Pragma("unroll") for (int k = 0; k < 2; ++k) dst[m][k] = *(const LAS bf16x8*)(lds + PG8_SA(b, h) + aoff + m * 2048 + k * 1024); } while (0)
; #define PG8_LDB(dst, b, h) do { _Pragma("unroll") for (int n = 0; n < 2; ++n) _Pragma("unroll") for (int k = 0; k < 2; ++k) dst[n][k] = *(const LAS bf16x8*)(lds + PG8_SB(b, h) + boff + n * 2048 + k * 1024); } while (0)
; #define PG8_MMA(ai, bj, At, Bt) do { __builtin_amdgcn_s_setprio(1); _Pragma("unroll") for (int m = 0; m < 4; ++m) _Pragma("unroll") for (int n = 0; n < 2; ++n) _Pragma("unroll") for (int k = 0; k < 2; ++k) \
;         acc[ai][bj][m][n] = __builtin_amdgcn_mfma_f32_16x16x32_bf16(Bt[n][k], At[m][k], acc[ai][bj][m][n], 0, 0, 0); __builtin_amdgcn_s_setprio(0); } while (0)
; #define PG8_WAIT_V(n) asm volatile("s_waitcnt vmcnt(" #n ")" ::: "memory")
; #define PG8_WAIT_L(n) asm volatile("s_waitcnt lgkmcnt(" #n ")" ::: "memory")
; #define PG8_BAR __builtin_amdgcn_s_barrier()
; #define PG8_SCHED __builtin_amdgcn_sched_barrier(0)
; template <class Epi, class Sched, int LDA, int LDB, bool ALIGN_EPI = true>
; __device__ __forceinline__ void gemm_phase(LAS unsigned char* lds, const Gemm g, const Sched& S, const Epi& E, int wave) {
;     ...
;             PG8_WAIT_V(8); PG8_WAIT_L(0); PG8_BAR; PG8_MMA(1, 0, At, B0); PG8_MMA(1, 1, At, B1); PG8_BAR; PG8_SCHED;
;             PG8_LDB(B0, 1, 0); PG8_LDB(B1, 1, 1); PG8_SCHED; PG8_LDA(At, 1, 0); PG8_STAGE(PG8_SA(0, 1), a2 + hstepA, voffA);
;             PG8_WAIT_V(8); PG8_WAIT_L(0); PG8_BAR; PG8_MMA(0, 0, At, B0); PG8_MMA(0, 1, At, B1); PG8_BAR; PG8_SCHED;
	v_mfma_f32_16x16x32_bf16 v[62:65], v[146:149], v[184:187], v[62:65]
	v_mfma_f32_16x16x32_bf16 v[58:61], v[154:157], v[184:187], v[58:61]
	v_mfma_f32_16x16x32_bf16 v[50:53], v[146:149], v[192:195], v[50:53]
	v_mfma_f32_16x16x32_bf16 v[42:45], v[154:157], v[192:195], v[42:45]
	v_mfma_f32_16x16x32_bf16 v[34:37], v[146:149], v[200:203], v[34:37]
	v_mfma_f32_16x16x32_bf16 v[26:29], v[154:157], v[200:203], v[26:29]
	v_mfma_f32_16x16x32_bf16 v[18:21], v[146:149], v[208:211], v[18:21]
	v_mfma_f32_16x16x32_bf16 v[10:13], v[154:157], v[208:211], v[10:13]
	v_mfma_f32_16x16x32_bf16 v[62:65], v[150:153], v[188:191], v[62:65]
	v_mfma_f32_16x16x32_bf16 v[58:61], v[158:161], v[188:191], v[58:61]
	v_mfma_f32_16x16x32_bf16 v[50:53], v[150:153], v[196:199], v[50:53]
	v_mfma_f32_16x16x32_bf16 v[42:45], v[158:161], v[196:199], v[42:45]
	v_mfma_f32_16x16x32_bf16 v[34:37], v[150:153], v[204:207], v[34:37]
	v_mfma_f32_16x16x32_bf16 v[26:29], v[158:161], v[204:207], v[26:29]
	v_mfma_f32_16x16x32_bf16 v[18:21], v[150:153], v[212:215], v[18:21]
	v_mfma_f32_16x16x32_bf16 v[10:13], v[158:161], v[212:215], v[10:13]
	v_mfma_f32_16x16x32_bf16 v[54:57], v[162:165], v[184:187], v[54:57]
	v_mfma_f32_16x16x32_bf16 v[46:49], v[170:173], v[184:187], v[46:49]
	v_mfma_f32_16x16x32_bf16 v[38:41], v[162:165], v[192:195], v[38:41]
	v_mfma_f32_16x16x32_bf16 v[30:33], v[170:173], v[192:195], v[30:33]
	v_mfma_f32_16x16x32_bf16 v[22:25], v[162:165], v[200:203], v[22:25]
	v_mfma_f32_16x16x32_bf16 v[14:17], v[170:173], v[200:203], v[14:17]
	v_mfma_f32_16x16x32_bf16 v[6:9], v[162:165], v[208:211], v[6:9]
	v_mfma_f32_16x16x32_bf16 v[2:5], v[170:173], v[208:211], v[2:5]
	v_mfma_f32_16x16x32_bf16 v[54:57], v[166:169], v[188:191], v[54:57]
	v_mfma_f32_16x16x32_bf16 v[46:49], v[180:183], v[188:191], v[46:49]
	v_mfma_f32_16x16x32_bf16 v[38:41], v[166:169], v[196:199], v[38:41]
	v_mfma_f32_16x16x32_bf16 v[30:33], v[180:183], v[196:199], v[30:33]
	v_mfma_f32_16x16x32_bf16 v[22:25], v[166:169], v[204:207], v[22:25]
	v_mfma_f32_16x16x32_bf16 v[14:17], v[180:183], v[204:207], v[14:17]
	v_mfma_f32_16x16x32_bf16 v[6:9], v[166:169], v[212:215], v[6:9]
	v_mfma_f32_16x16x32_bf16 v[2:5], v[180:183], v[212:215], v[2:5]
	s_barrier
	s_setprio 0
	ds_read_b128 v[184:187], v145 offset:32768
	ds_read_b128 v[188:191], v145 offset:33792
	ds_read_b128 v[192:195], v145 offset:34816
	ds_read_b128 v[196:199], v145 offset:35840
	ds_read_b128 v[200:203], v145 offset:36864
	ds_read_b128 v[204:207], v145 offset:37888
	ds_read_b128 v[208:211], v145 offset:38912
	ds_read_b128 v[212:215], v145 offset:39936
	s_add_i32 s44, 0, 0x18000
	s_add_i32 s45, 0, 0x1c000
	v_add_u32_e32 v158, s44, v143
	v_add_u32_e32 v180, s45, v143
	ds_read_b128 v[146:149], v158
	ds_read_b128 v[150:153], v158 offset:1024
	ds_read_b128 v[154:157], v158 offset:2048
	ds_read_b128 v[158:161], v158 offset:3072
	ds_read_b128 v[162:165], v180
	ds_read_b128 v[166:169], v180 offset:1024
	ds_read_b128 v[170:173], v180 offset:2048
	ds_read_b128 v[180:183], v180 offset:3072
	s_add_u32 s16, s16, 0x80000
	s_addc_u32 s17, s17, 0
	s_mov_b32 m0, s26
	v_lshl_add_u64 v[220:221], s[16:17], 0, v[130:131]
	global_load_lds_dwordx4 v[220:221], off
	v_lshl_add_u64 v[220:221], s[16:17], 0, v[132:133]
	s_mov_b32 m0, s27
	s_nop 0
	global_load_lds_dwordx4 v[220:221], off
	s_waitcnt vmcnt(8)
	s_waitcnt lgkmcnt(0)
	s_setprio 1
	s_barrier
	v_mfma_f32_16x16x32_bf16 v[126:129], v[146:149], v[184:187], v[126:129]
	v_mfma_f32_16x16x32_bf16 v[122:125], v[154:157], v[184:187], v[122:125]
	v_mfma_f32_16x16x32_bf16 v[114:117], v[146:149], v[192:195], v[114:117]
	v_mfma_f32_16x16x32_bf16 v[106:109], v[154:157], v[192:195], v[106:109]
	v_mfma_f32_16x16x32_bf16 v[98:101], v[146:149], v[200:203], v[98:101]
	v_mfma_f32_16x16x32_bf16 v[90:93], v[154:157], v[200:203], v[90:93]
	v_mfma_f32_16x16x32_bf16 v[82:85], v[146:149], v[208:211], v[82:85]
	v_mfma_f32_16x16x32_bf16 v[74:77], v[154:157], v[208:211], v[74:77]
	v_mfma_f32_16x16x32_bf16 v[126:129], v[150:153], v[188:191], v[126:129]
	v_mfma_f32_16x16x32_bf16 v[122:125], v[158:161], v[188:191], v[122:125]
	v_mfma_f32_16x16x32_bf16 v[114:117], v[150:153], v[196:199], v[114:117]
	v_mfma_f32_16x16x32_bf16 v[106:109], v[158:161], v[196:199], v[106:109]
	v_mfma_f32_16x16x32_bf16 v[98:101], v[150:153], v[204:207], v[98:101]
	v_mfma_f32_16x16x32_bf16 v[90:93], v[158:161], v[204:207], v[90:93]
	v_mfma_f32_16x16x32_bf16 v[82:85], v[150:153], v[212:215], v[82:85]
	v_mfma_f32_16x16x32_bf16 v[74:77], v[158:161], v[212:215], v[74:77]
	v_mfma_f32_16x16x32_bf16 v[118:121], v[162:165], v[184:187], v[118:121]
	v_mfma_f32_16x16x32_bf16 v[110:113], v[170:173], v[184:187], v[110:113]
	v_mfma_f32_16x16x32_bf16 v[102:105], v[162:165], v[192:195], v[102:105]
	v_mfma_f32_16x16x32_bf16 v[94:97], v[170:173], v[192:195], v[94:97]
	v_mfma_f32_16x16x32_bf16 v[86:89], v[162:165], v[200:203], v[86:89]
	v_mfma_f32_16x16x32_bf16 v[78:81], v[170:173], v[200:203], v[78:81]
	v_mfma_f32_16x16x32_bf16 v[70:73], v[162:165], v[208:211], v[70:73]
	v_mfma_f32_16x16x32_bf16 v[66:69], v[170:173], v[208:211], v[66:69]
	v_mfma_f32_16x16x32_bf16 v[118:121], v[166:169], v[188:191], v[118:121]
	v_mfma_f32_16x16x32_bf16 v[110:113], v[180:183], v[188:191], v[110:113]
	v_mfma_f32_16x16x32_bf16 v[102:105], v[166:169], v[196:199], v[102:105]
	v_mfma_f32_16x16x32_bf16 v[94:97], v[180:183], v[196:199], v[94:97]
	v_mfma_f32_16x16x32_bf16 v[86:89], v[166:169], v[204:207], v[86:89]
	v_mfma_f32_16x16x32_bf16 v[78:81], v[180:183], v[204:207], v[78:81]
	v_mfma_f32_16x16x32_bf16 v[70:73], v[166:169], v[212:215], v[70:73]
	v_mfma_f32_16x16x32_bf16 v[66:69], v[180:183], v[212:215], v[66:69]
	s_barrier
; #define PG8_STAGE(bufoff, gbase, voff) do { _Pragma("unroll") for (int _i = 0; _i < 2; ++_i) \
;         __builtin_amdgcn_global_load_lds((const unsigned*)((const char*)(gbase) + (voff)[_i]), (LAS unsigned*)(lds + (bufoff) + ldsw + _i * 8192), 16, 0, 0); } while (0)
; #define PG8_LDA(dst, b, h) do { _Pragma("unroll") for (int m = 0; m < 4; ++m) _Pragma("unroll") for (int k = 0; k < 2; ++k) dst[m][k] = *(const LAS bf16x8*)(lds + PG8_SA(b, h) + aoff + m * 2048 + k * 1024); } while (0)
; #define PG8_MMA(ai, bj, At, Bt) do { __builtin_amdgcn_s_setprio(1); _Pragma("unroll") for (int m = 0; m < 4; ++m) _Pragma("unroll") for (int n = 0; n < 2; ++n) _Pragma("unroll") for (int k = 0; k < 2; ++k) \
;         acc[ai][bj][m][n] = __builtin_amdgcn_mfma_f32_16x16x32_bf16(Bt[n][k], At[m][k], acc[ai][bj][m][n], 0, 0, 0); __builtin_amdgcn_s_setprio(0); } while (0)
; #define PG8_WAIT_V(n) asm volatile("s_waitcnt vmcnt(" #n ")" ::: "memory")
; #define PG8_WAIT_L(n) asm volatile("s_waitcnt lgkmcnt(" #n ")" ::: "memory")
; #define PG8_BAR __builtin_amdgcn_s_barrier()
; #define PG8_SCHED __builtin_amdgcn_sched_barrier(0)
; template <class Epi, class Sched, int LDA, int LDB, bool ALIGN_EPI = true>
; __device__ __forceinline__ void gemm_phase(LAS unsigned char* lds, const Gemm g, const Sched& S, const Epi& E, int wave) {
;     ...
;             PG8_LDA(At, 1, 1); PG8_STAGE(PG8_SB(1, 0), b3, voffB); PG8_STAGE(PG8_SB(1, 1), b3 + hstepB, voffB); PG8_STAGE(PG8_SA(1, 0), a3, voffA);
;             PG8_WAIT_V(8); PG8_WAIT_L(0); PG8_BAR; PG8_MMA(1, 0, At, B0); PG8_MMA(1, 1, At, B1); PG8_BAR; PG8_SCHED;
;         }
;         if constexpr (ALIGN_EPI) { if (wr == 0) PG8_BAR; }
	s_setprio 0
	s_add_i32 s16, s44, s47
	v_lshl_add_u64 v[140:141], v[140:141], 0, s[72:73]
	s_mov_b32 m0, s16
	ds_read_b128 v[184:187], v145 offset:49152
	ds_read_b128 v[188:191], v145 offset:50176
	ds_read_b128 v[192:195], v145 offset:51200
	ds_read_b128 v[196:199], v145 offset:52224
	ds_read_b128 v[200:203], v145 offset:53248
	ds_read_b128 v[204:207], v145 offset:54272
	ds_read_b128 v[208:211], v145 offset:55296
	ds_read_b128 v[212:215], v145 offset:56320
	global_load_lds_dwordx4 v[140:141], off
	s_add_i32 m0, s16, 0x2000
	s_add_u32 s14, s14, 0x84080
	v_lshl_add_u64 v[140:141], v[174:175], 0, s[72:73]
	s_addc_u32 s15, s15, 0
	s_add_i32 s16, s45, s47
	global_load_lds_dwordx4 v[140:141], off
	v_lshl_add_u64 v[140:141], s[14:15], 0, v[0:1]
	s_mov_b32 m0, s16
	s_nop 0
	global_load_lds_dwordx4 v[140:141], off
	v_lshl_add_u64 v[140:141], s[14:15], 0, v[134:135]
	s_add_i32 m0, s16, 0x2000
	s_nop 0
	global_load_lds_dwordx4 v[140:141], off
	v_lshl_add_u64 v[140:141], v[216:217], 0, s[72:73]
	s_mov_b32 m0, s28
	s_nop 0
	global_load_lds_dwordx4 v[140:141], off
	v_lshl_add_u64 v[140:141], v[218:219], 0, s[72:73]
	s_mov_b32 m0, s29
	s_nop 0
	global_load_lds_dwordx4 v[140:141], off
	s_waitcnt vmcnt(8)
	s_waitcnt lgkmcnt(0)
	s_setprio 1
	s_barrier
	v_mfma_f32_16x16x32_bf16 v[62:65], v[146:149], v[184:187], v[62:65]
	v_mfma_f32_16x16x32_bf16 v[58:61], v[154:157], v[184:187], v[58:61]
	v_mfma_f32_16x16x32_bf16 v[50:53], v[146:149], v[192:195], v[50:53]
	v_mfma_f32_16x16x32_bf16 v[42:45], v[154:157], v[192:195], v[42:45]
	v_mfma_f32_16x16x32_bf16 v[34:37], v[146:149], v[200:203], v[34:37]
	v_mfma_f32_16x16x32_bf16 v[26:29], v[154:157], v[200:203], v[26:29]
	v_mfma_f32_16x16x32_bf16 v[18:21], v[146:149], v[208:211], v[18:21]
	v_mfma_f32_16x16x32_bf16 v[10:13], v[154:157], v[208:211], v[10:13]
	v_mfma_f32_16x16x32_bf16 v[62:65], v[150:153], v[188:191], v[62:65]
	v_mfma_f32_16x16x32_bf16 v[58:61], v[158:161], v[188:191], v[58:61]
	v_mfma_f32_16x16x32_bf16 v[50:53], v[150:153], v[196:199], v[50:53]
	v_mfma_f32_16x16x32_bf16 v[42:45], v[158:161], v[196:199], v[42:45]
	v_mfma_f32_16x16x32_bf16 v[34:37], v[150:153], v[204:207], v[34:37]
	v_mfma_f32_16x16x32_bf16 v[26:29], v[158:161], v[204:207], v[26:29]
	v_mfma_f32_16x16x32_bf16 v[18:21], v[150:153], v[212:215], v[18:21]
	v_mfma_f32_16x16x32_bf16 v[10:13], v[158:161], v[212:215], v[10:13]
	v_mfma_f32_16x16x32_bf16 v[54:57], v[162:165], v[184:187], v[54:57]
	v_mfma_f32_16x16x32_bf16 v[46:49], v[170:173], v[184:187], v[46:49]
	v_mfma_f32_16x16x32_bf16 v[38:41], v[162:165], v[192:195], v[38:41]
	v_mfma_f32_16x16x32_bf16 v[30:33], v[170:173], v[192:195], v[30:33]
	v_mfma_f32_16x16x32_bf16 v[22:25], v[162:165], v[200:203], v[22:25]
	v_mfma_f32_16x16x32_bf16 v[14:17], v[170:173], v[200:203], v[14:17]
	v_mfma_f32_16x16x32_bf16 v[6:9], v[162:165], v[208:211], v[6:9]
	v_mfma_f32_16x16x32_bf16 v[2:5], v[170:173], v[208:211], v[2:5]
	v_mfma_f32_16x16x32_bf16 v[54:57], v[166:169], v[188:191], v[54:57]
	v_mfma_f32_16x16x32_bf16 v[46:49], v[180:183], v[188:191], v[46:49]
	v_mfma_f32_16x16x32_bf16 v[38:41], v[166:169], v[196:199], v[38:41]
	v_mfma_f32_16x16x32_bf16 v[30:33], v[180:183], v[196:199], v[30:33]
	v_mfma_f32_16x16x32_bf16 v[22:25], v[166:169], v[204:207], v[22:25]
	v_mfma_f32_16x16x32_bf16 v[14:17], v[180:183], v[204:207], v[14:17]
	v_mfma_f32_16x16x32_bf16 v[6:9], v[166:169], v[212:215], v[6:9]
	v_mfma_f32_16x16x32_bf16 v[2:5], v[180:183], v[212:215], v[2:5]
	s_barrier
	s_setprio 0
	s_add_i32 s39, s39, 2
	s_add_u32 s12, s12, 0x100
	s_addc_u32 s13, s13, 0
	s_add_u32 s37, s37, 0x100
	s_addc_u32 s38, s38, 0
	s_cmp_gt_u32 s39, 29
	s_cbranch_scc0 .LBB0_2513
	v_readlane_b32 s12, v252, 14
	v_readlane_b32 s13, v252, 15
	s_and_b64 vcc, exec, s[12:13]
	s_cbranch_vccz .LBB0_2516
	s_barrier

; #define PG8_STAGE(bufoff, gbase, voff) do { _Pragma("unroll") for (int _i = 0; _i < 2; ++_i) \
;         __builtin_amdgcn_global_load_lds((const unsigned*)((const char*)(gbase) + (voff)[_i]), (LAS unsigned*)(lds + (bufoff) + ldsw + _i * 8192), 16, 0, 0); } while (0)
; #define PG8_LDA(dst, b, h) do { _Pragma("unroll") for (int m = 0; m < 4; ++m) _Pragma("unroll") for (int k = 0; k < 2; ++k) dst[m][k] = *(const LAS bf16x8*)(lds + PG8_SA(b, h) + aoff + m * 2048 + k * 1024); } while (0)
; #define PG8_LDB(dst, b, h) do { _Pragma("unroll") for (int n = 0; n < 2; ++n) _Pragma("unroll") for (int k = 0; k < 2; ++k) dst[n][k] = *(const LAS bf16x8*)(lds + PG8_SB(b, h) + boff + n * 2048 + k * 1024); } while (0)
; #define PG8_MMA(ai, bj, At, Bt) do { __builtin_amdgcn_s_setprio(1); _Pragma("unroll") for (int m = 0; m < 4; ++m) _Pragma("unroll") for (int n = 0; n < 2; ++n) _Pragma("unroll") for (int k = 0; k < 2; ++k) \
;         acc[ai][bj][m][n] = __builtin_amdgcn_mfma_f32_16x16x32_bf16(Bt[n][k], At[m][k], acc[ai][bj][m][n], 0, 0, 0); __builtin_amdgcn_s_setprio(0); } while (0)
; #define PG8_WAIT_V(n) asm volatile("s_waitcnt vmcnt(" #n ")" ::: "memory")
; #define PG8_WAIT_L(n) asm volatile("s_waitcnt lgkmcnt(" #n ")" ::: "memory")
; #define PG8_BAR __builtin_amdgcn_s_barrier()
; #define PG8_SCHED __builtin_amdgcn_sched_barrier(0)
; template <class Epi, class Sched, int LDA, int LDB, bool ALIGN_EPI = true>
; __device__ __forceinline__ void gemm_phase(LAS unsigned char* lds, const Gemm g, const Sched& S, const Epi& E, int wave) {
;     ...
;             const bool last = (t == nt - 2);
;             const char* a1 = cA + (size_t)(t + 1) * kstep;
;             const char* a2 = last ? nA : cA + (size_t)(t + 2) * kstep; const char* b2 = last ? nB : cB + (size_t)(t + 2) * kstep;
;             const char* a3 = a2 + kstep; const char* b3 = b2 + kstep;
;             PG8_LDB(B0, 0, 0); PG8_LDB(B1, 0, 1); PG8_SCHED; PG8_LDA(At, 0, 0); PG8_STAGE(PG8_SA(1, 1), a1 + hstepA, voffA);
;             PG8_WAIT_V(8); PG8_WAIT_L(0); PG8_BAR; PG8_MMA(0, 0, At, B0); PG8_MMA(0, 1, At, B1); PG8_BAR; PG8_SCHED;
;             PG8_LDA(At, 0, 1); PG8_STAGE(PG8_SB(0, 0), b2, voffB); PG8_STAGE(PG8_SB(0, 1), b2 + hstepB, voffB); PG8_STAGE(PG8_SA(0, 0), a2, voffA);
.LBB0_2551:
	ds_read_b128 v[188:191], v156
	ds_read_b128 v[192:195], v156 offset:1024
	ds_read_b128 v[196:199], v156 offset:2048
	ds_read_b128 v[200:203], v156 offset:3072
	ds_read_b128 v[204:207], v156 offset:4096
	ds_read_b128 v[208:211], v156 offset:5120
	ds_read_b128 v[212:215], v156 offset:6144
	ds_read_b128 v[216:219], v156 offset:7168
	s_add_u32 s2, s0, 0x100
	s_addc_u32 s3, s1, 0
	s_add_i32 s50, 0, 0x10000
	s_cmp_eq_u32 s49, 8
	s_cselect_b32 s17, s11, s3
	s_cselect_b32 s16, s10, s2
	v_add_u32_e32 v0, s50, v154
	s_cselect_b32 s15, s13, s47
	s_cselect_b32 s14, s12, s46
	s_add_i32 s51, 0, 0x14000
	ds_read_b128 v[130:133], v0
	ds_read_b128 v[148:151], v0 offset:1024
	ds_read_b128 v[158:161], v0 offset:2048
	ds_read_b128 v[162:165], v0 offset:3072
	v_add_u32_e32 v0, s51, v154
	ds_read_b128 v[166:169], v0
	ds_read_b128 v[170:173], v0 offset:1024
	ds_read_b128 v[180:183], v0 offset:2048
	ds_read_b128 v[184:187], v0 offset:3072
	v_lshl_add_u64 v[152:153], s[0:1], 0, v[144:145]
	s_add_i32 m0, s28, 0xc000
	s_nop 0
	global_load_lds_dwordx4 v[152:153], off
	v_lshl_add_u64 v[152:153], s[0:1], 0, v[146:147]
	s_add_i32 m0, s28, 0xe000
	s_nop 0
	global_load_lds_dwordx4 v[152:153], off
	s_waitcnt vmcnt(8)
	s_waitcnt lgkmcnt(0)
	s_setprio 1
	s_barrier
	v_mfma_f32_16x16x32_bf16 v[126:129], v[130:133], v[188:191], v[126:129]
	v_mfma_f32_16x16x32_bf16 v[122:125], v[158:161], v[188:191], v[122:125]
	v_mfma_f32_16x16x32_bf16 v[118:121], v[130:133], v[196:199], v[118:121]
	v_mfma_f32_16x16x32_bf16 v[114:117], v[158:161], v[196:199], v[114:117]
	v_mfma_f32_16x16x32_bf16 v[110:113], v[130:133], v[204:207], v[110:113]
	v_mfma_f32_16x16x32_bf16 v[106:109], v[158:161], v[204:207], v[106:109]
	v_mfma_f32_16x16x32_bf16 v[102:105], v[130:133], v[212:215], v[102:105]
	v_mfma_f32_16x16x32_bf16 v[98:101], v[158:161], v[212:215], v[98:101]
	v_mfma_f32_16x16x32_bf16 v[126:129], v[148:151], v[192:195], v[126:129]
	v_mfma_f32_16x16x32_bf16 v[122:125], v[162:165], v[192:195], v[122:125]
	v_mfma_f32_16x16x32_bf16 v[118:121], v[148:151], v[200:203], v[118:121]
	v_mfma_f32_16x16x32_bf16 v[114:117], v[162:165], v[200:203], v[114:117]
	v_mfma_f32_16x16x32_bf16 v[110:113], v[148:151], v[208:211], v[110:113]
	v_mfma_f32_16x16x32_bf16 v[106:109], v[162:165], v[208:211], v[106:109]
	v_mfma_f32_16x16x32_bf16 v[102:105], v[148:151], v[216:219], v[102:105]
	v_mfma_f32_16x16x32_bf16 v[98:101], v[162:165], v[216:219], v[98:101]
	v_mfma_f32_16x16x32_bf16 v[62:65], v[166:169], v[188:191], v[62:65]
	v_mfma_f32_16x16x32_bf16 v[58:61], v[180:183], v[188:191], v[58:61]
	v_mfma_f32_16x16x32_bf16 v[54:57], v[166:169], v[196:199], v[54:57]
	v_mfma_f32_16x16x32_bf16 v[50:53], v[180:183], v[196:199], v[50:53]
	v_mfma_f32_16x16x32_bf16 v[46:49], v[166:169], v[204:207], v[46:49]
	v_mfma_f32_16x16x32_bf16 v[42:45], v[180:183], v[204:207], v[42:45]
	v_mfma_f32_16x16x32_bf16 v[38:41], v[166:169], v[212:215], v[38:41]
	v_mfma_f32_16x16x32_bf16 v[34:37], v[180:183], v[212:215], v[34:37]
	v_mfma_f32_16x16x32_bf16 v[62:65], v[170:173], v[192:195], v[62:65]
	v_mfma_f32_16x16x32_bf16 v[58:61], v[184:187], v[192:195], v[58:61]
	v_mfma_f32_16x16x32_bf16 v[54:57], v[170:173], v[200:203], v[54:57]
	v_mfma_f32_16x16x32_bf16 v[50:53], v[184:187], v[200:203], v[50:53]
	v_mfma_f32_16x16x32_bf16 v[46:49], v[170:173], v[208:211], v[46:49]
	v_mfma_f32_16x16x32_bf16 v[42:45], v[184:187], v[208:211], v[42:45]
	v_mfma_f32_16x16x32_bf16 v[38:41], v[170:173], v[216:219], v[38:41]
	v_mfma_f32_16x16x32_bf16 v[34:37], v[184:187], v[216:219], v[34:37]
	s_barrier
	s_setprio 0
	s_add_i32 s0, s50, s54
	v_lshl_add_u64 v[152:153], s[14:15], 0, v[136:137]
	s_mov_b32 m0, s0
	ds_read_b128 v[188:191], v156 offset:16384
	ds_read_b128 v[192:195], v156 offset:17408
	ds_read_b128 v[196:199], v156 offset:18432
	ds_read_b128 v[200:203], v156 offset:19456
	ds_read_b128 v[204:207], v156 offset:20480
	ds_read_b128 v[208:211], v156 offset:21504
	ds_read_b128 v[212:215], v156 offset:22528
	ds_read_b128 v[216:219], v156 offset:23552
	global_load_lds_dwordx4 v[152:153], off
	s_add_i32 m0, s0, 0x2000
	s_add_u32 s0, s14, 0x30000
	v_lshl_add_u64 v[174:175], s[14:15], 0, v[140:141]
	s_addc_u32 s1, s15, 0
	s_add_i32 s50, s51, s54
	global_load_lds_dwordx4 v[174:175], off
	v_lshl_add_u64 v[220:221], s[0:1], 0, v[136:137]
	s_mov_b32 m0, s50
	v_lshl_add_u64 v[222:223], s[16:17], 0, v[138:139]
	global_load_lds_dwordx4 v[220:221], off
	v_lshl_add_u64 v[220:221], s[0:1], 0, v[140:141]
	s_add_i32 m0, s50, 0x2000
	s_nop 0
	global_load_lds_dwordx4 v[220:221], off
	v_lshl_add_u64 v[220:221], s[16:17], 0, v[134:135]
	s_mov_b32 m0, s28
	s_nop 0
	global_load_lds_dwordx4 v[220:221], off
	s_mov_b32 m0, s29
	s_nop 0
	global_load_lds_dwordx4 v[222:223], off
	s_waitcnt vmcnt(8)
	s_waitcnt lgkmcnt(0)
	s_setprio 1
	s_barrier
; #define PG8_STAGE(bufoff, gbase, voff) do { _Pragma("unroll") for (int _i = 0; _i < 2; ++_i) \
;         __builtin_amdgcn_global_load_lds((const unsigned*)((const char*)(gbase) + (voff)[_i]), (LAS unsigned*)(lds + (bufoff) + ldsw + _i * 8192), 16, 0, 0); } while (0)
; #define PG8_LDA(dst, b, h) do { _Pragma("unroll") for (int m = 0; m < 4; ++m) _Pragma("unroll") for (int k = 0; k < 2; ++k) dst[m][k] = *(const LAS bf16x8*)(lds + PG8_SA(b, h) + aoff + m * 2048 + k * 1024); } while (0)
; #define PG8_LDB(dst, b, h) do { _Pragma("unroll") for (int n = 0; n < 2; ++n) _Pragma("unroll") for (int k = 0; k < 2; ++k) dst[n][k] = *(const LAS bf16x8*)(lds + PG8_SB(b, h) + boff + n * 2048 + k * 1024); } while (0)
; #define PG8_MMA(ai, bj, At, Bt) do { __builtin_amdgcn_s_setprio(1); _Pragma("unroll") for (int m = 0; m < 4; ++m) _Pragma("unroll") for (int n = 0; n < 2; ++n) _Pragma("unroll") for (int k = 0; k < 2; ++k) \
;         acc[ai][bj][m][n] = __builtin_amdgcn_mfma_f32_16x16x32_bf16(Bt[n][k], At[m][k], acc[ai][bj][m][n], 0, 0, 0); __builtin_amdgcn_s_setprio(0); } while (0)
; #define PG8_WAIT_V(n) asm volatile("s_waitcnt vmcnt(" #n ")" ::: "memory")
; #define PG8_WAIT_L(n) asm volatile("s_waitcnt lgkmcnt(" #n ")" ::: "memory")
; #define PG8_BAR __builtin_amdgcn_s_barrier()
; #define PG8_SCHED __builtin_amdgcn_sched_barrier(0)
; template <class Epi, class Sched, int LDA, int LDB, bool ALIGN_EPI = true>
; __device__ __forceinline__ void gemm_phase(LAS unsigned char* lds, const Gemm g, const Sched& S, const Epi& E, int wave) {
;     ...
;             PG8_WAIT_V(8); PG8_WAIT_L(0); PG8_BAR; PG8_MMA(1, 0, At, B0); PG8_MMA(1, 1, At, B1); PG8_BAR; PG8_SCHED;
;             PG8_LDB(B0, 1, 0); PG8_LDB(B1, 1, 1); PG8_SCHED; PG8_LDA(At, 1, 0); PG8_STAGE(PG8_SA(0, 1), a2 + hstepA, voffA);
;             PG8_WAIT_V(8); PG8_WAIT_L(0); PG8_BAR; PG8_MMA(0, 0, At, B0); PG8_MMA(0, 1, At, B1); PG8_BAR; PG8_SCHED;
	v_mfma_f32_16x16x32_bf16 v[94:97], v[130:133], v[188:191], v[94:97]
	v_mfma_f32_16x16x32_bf16 v[90:93], v[158:161], v[188:191], v[90:93]
	v_mfma_f32_16x16x32_bf16 v[86:89], v[130:133], v[196:199], v[86:89]
	v_mfma_f32_16x16x32_bf16 v[82:85], v[158:161], v[196:199], v[82:85]
	v_mfma_f32_16x16x32_bf16 v[78:81], v[130:133], v[204:207], v[78:81]
	v_mfma_f32_16x16x32_bf16 v[74:77], v[158:161], v[204:207], v[74:77]
	v_mfma_f32_16x16x32_bf16 v[70:73], v[130:133], v[212:215], v[70:73]
	v_mfma_f32_16x16x32_bf16 v[66:69], v[158:161], v[212:215], v[66:69]
	v_mfma_f32_16x16x32_bf16 v[94:97], v[148:151], v[192:195], v[94:97]
	v_mfma_f32_16x16x32_bf16 v[90:93], v[162:165], v[192:195], v[90:93]
	v_mfma_f32_16x16x32_bf16 v[86:89], v[148:151], v[200:203], v[86:89]
	v_mfma_f32_16x16x32_bf16 v[82:85], v[162:165], v[200:203], v[82:85]
	v_mfma_f32_16x16x32_bf16 v[78:81], v[148:151], v[208:211], v[78:81]
	v_mfma_f32_16x16x32_bf16 v[74:77], v[162:165], v[208:211], v[74:77]
	v_mfma_f32_16x16x32_bf16 v[70:73], v[148:151], v[216:219], v[70:73]
	v_mfma_f32_16x16x32_bf16 v[66:69], v[162:165], v[216:219], v[66:69]
	v_mfma_f32_16x16x32_bf16 v[30:33], v[166:169], v[188:191], v[30:33]
	v_mfma_f32_16x16x32_bf16 v[26:29], v[180:183], v[188:191], v[26:29]
	v_mfma_f32_16x16x32_bf16 v[22:25], v[166:169], v[196:199], v[22:25]
	v_mfma_f32_16x16x32_bf16 v[18:21], v[180:183], v[196:199], v[18:21]
	v_mfma_f32_16x16x32_bf16 v[14:17], v[166:169], v[204:207], v[14:17]
	v_mfma_f32_16x16x32_bf16 v[10:13], v[180:183], v[204:207], v[10:13]
	v_mfma_f32_16x16x32_bf16 v[6:9], v[166:169], v[212:215], v[6:9]
	v_mfma_f32_16x16x32_bf16 v[2:5], v[180:183], v[212:215], v[2:5]
	v_mfma_f32_16x16x32_bf16 v[30:33], v[170:173], v[192:195], v[30:33]
	v_mfma_f32_16x16x32_bf16 v[26:29], v[184:187], v[192:195], v[26:29]
	v_mfma_f32_16x16x32_bf16 v[22:25], v[170:173], v[200:203], v[22:25]
	v_mfma_f32_16x16x32_bf16 v[18:21], v[184:187], v[200:203], v[18:21]
	v_mfma_f32_16x16x32_bf16 v[14:17], v[170:173], v[208:211], v[14:17]
	v_mfma_f32_16x16x32_bf16 v[10:13], v[184:187], v[208:211], v[10:13]
	v_mfma_f32_16x16x32_bf16 v[6:9], v[170:173], v[216:219], v[6:9]
	v_mfma_f32_16x16x32_bf16 v[2:5], v[184:187], v[216:219], v[2:5]
	s_barrier
	s_setprio 0
	ds_read_b128 v[188:191], v156 offset:32768
	ds_read_b128 v[192:195], v156 offset:33792
	ds_read_b128 v[196:199], v156 offset:34816
	ds_read_b128 v[200:203], v156 offset:35840
	ds_read_b128 v[204:207], v156 offset:36864
	ds_read_b128 v[208:211], v156 offset:37888
	ds_read_b128 v[212:215], v156 offset:38912
	ds_read_b128 v[216:219], v156 offset:39936
	s_add_i32 s50, 0, 0x18000
	v_add_u32_e32 v0, s50, v154
	s_add_i32 s51, 0, 0x1c000
	ds_read_b128 v[130:133], v0
	ds_read_b128 v[148:151], v0 offset:1024
	ds_read_b128 v[158:161], v0 offset:2048
	ds_read_b128 v[162:165], v0 offset:3072
	v_add_u32_e32 v0, s51, v154
	ds_read_b128 v[166:169], v0
	ds_read_b128 v[170:173], v0 offset:1024
	ds_read_b128 v[180:183], v0 offset:2048
	ds_read_b128 v[184:187], v0 offset:3072
	s_add_u32 s0, s16, 0x30000
	s_addc_u32 s1, s17, 0
	s_mov_b32 m0, s34
	v_lshl_add_u64 v[224:225], s[0:1], 0, v[134:135]
	global_load_lds_dwordx4 v[224:225], off
	v_lshl_add_u64 v[224:225], s[0:1], 0, v[138:139]
	s_mov_b32 m0, s35
	s_nop 0
	global_load_lds_dwordx4 v[224:225], off
	s_waitcnt vmcnt(8)
	s_waitcnt lgkmcnt(0)
	s_setprio 1
	s_barrier
	v_mfma_f32_16x16x32_bf16 v[126:129], v[130:133], v[188:191], v[126:129]
	v_mfma_f32_16x16x32_bf16 v[122:125], v[158:161], v[188:191], v[122:125]
	v_mfma_f32_16x16x32_bf16 v[118:121], v[130:133], v[196:199], v[118:121]
	v_mfma_f32_16x16x32_bf16 v[114:117], v[158:161], v[196:199], v[114:117]
	v_mfma_f32_16x16x32_bf16 v[110:113], v[130:133], v[204:207], v[110:113]
	v_mfma_f32_16x16x32_bf16 v[106:109], v[158:161], v[204:207], v[106:109]
	v_mfma_f32_16x16x32_bf16 v[102:105], v[130:133], v[212:215], v[102:105]
	v_mfma_f32_16x16x32_bf16 v[98:101], v[158:161], v[212:215], v[98:101]
	v_mfma_f32_16x16x32_bf16 v[126:129], v[148:151], v[192:195], v[126:129]
	v_mfma_f32_16x16x32_bf16 v[122:125], v[162:165], v[192:195], v[122:125]
	v_mfma_f32_16x16x32_bf16 v[118:121], v[148:151], v[200:203], v[118:121]
	v_mfma_f32_16x16x32_bf16 v[114:117], v[162:165], v[200:203], v[114:117]
	v_mfma_f32_16x16x32_bf16 v[110:113], v[148:151], v[208:211], v[110:113]
	v_mfma_f32_16x16x32_bf16 v[106:109], v[162:165], v[208:211], v[106:109]
	v_mfma_f32_16x16x32_bf16 v[102:105], v[148:151], v[216:219], v[102:105]
	v_mfma_f32_16x16x32_bf16 v[98:101], v[162:165], v[216:219], v[98:101]
	v_mfma_f32_16x16x32_bf16 v[62:65], v[166:169], v[188:191], v[62:65]
	v_mfma_f32_16x16x32_bf16 v[58:61], v[180:183], v[188:191], v[58:61]
	v_mfma_f32_16x16x32_bf16 v[54:57], v[166:169], v[196:199], v[54:57]
	v_mfma_f32_16x16x32_bf16 v[50:53], v[180:183], v[196:199], v[50:53]
	v_mfma_f32_16x16x32_bf16 v[46:49], v[166:169], v[204:207], v[46:49]
	v_mfma_f32_16x16x32_bf16 v[42:45], v[180:183], v[204:207], v[42:45]
	v_mfma_f32_16x16x32_bf16 v[38:41], v[166:169], v[212:215], v[38:41]
	v_mfma_f32_16x16x32_bf16 v[34:37], v[180:183], v[212:215], v[34:37]
	v_mfma_f32_16x16x32_bf16 v[62:65], v[170:173], v[192:195], v[62:65]
	v_mfma_f32_16x16x32_bf16 v[58:61], v[184:187], v[192:195], v[58:61]
	v_mfma_f32_16x16x32_bf16 v[54:57], v[170:173], v[200:203], v[54:57]
	v_mfma_f32_16x16x32_bf16 v[50:53], v[184:187], v[200:203], v[50:53]
	v_mfma_f32_16x16x32_bf16 v[46:49], v[170:173], v[208:211], v[46:49]
	v_mfma_f32_16x16x32_bf16 v[42:45], v[184:187], v[208:211], v[42:45]
	v_mfma_f32_16x16x32_bf16 v[38:41], v[170:173], v[216:219], v[38:41]
	v_mfma_f32_16x16x32_bf16 v[34:37], v[184:187], v[216:219], v[34:37]
	s_barrier
; #define PG8_STAGE(bufoff, gbase, voff) do { _Pragma("unroll") for (int _i = 0; _i < 2; ++_i) \
;         __builtin_amdgcn_global_load_lds((const unsigned*)((const char*)(gbase) + (voff)[_i]), (LAS unsigned*)(lds + (bufoff) + ldsw + _i * 8192), 16, 0, 0); } while (0)
; #define PG8_LDA(dst, b, h) do { _Pragma("unroll") for (int m = 0; m < 4; ++m) _Pragma("unroll") for (int k = 0; k < 2; ++k) dst[m][k] = *(const LAS bf16x8*)(lds + PG8_SA(b, h) + aoff + m * 2048 + k * 1024); } while (0)
; #define PG8_MMA(ai, bj, At, Bt) do { __builtin_amdgcn_s_setprio(1); _Pragma("unroll") for (int m = 0; m < 4; ++m) _Pragma("unroll") for (int n = 0; n < 2; ++n) _Pragma("unroll") for (int k = 0; k < 2; ++k) \
;         acc[ai][bj][m][n] = __builtin_amdgcn_mfma_f32_16x16x32_bf16(Bt[n][k], At[m][k], acc[ai][bj][m][n], 0, 0, 0); __builtin_amdgcn_s_setprio(0); } while (0)
; #define PG8_WAIT_V(n) asm volatile("s_waitcnt vmcnt(" #n ")" ::: "memory")
; #define PG8_WAIT_L(n) asm volatile("s_waitcnt lgkmcnt(" #n ")" ::: "memory")
; #define PG8_BAR __builtin_amdgcn_s_barrier()
; #define PG8_SCHED __builtin_amdgcn_sched_barrier(0)
; template <class Epi, class Sched, int LDA, int LDB, bool ALIGN_EPI = true>
; __device__ __forceinline__ void gemm_phase(LAS unsigned char* lds, const Gemm g, const Sched& S, const Epi& E, int wave) {
;     ...
;             PG8_LDA(At, 1, 1); PG8_STAGE(PG8_SB(1, 0), b3, voffB); PG8_STAGE(PG8_SB(1, 1), b3 + hstepB, voffB); PG8_STAGE(PG8_SA(1, 0), a3, voffA);
;             PG8_WAIT_V(8); PG8_WAIT_L(0); PG8_BAR; PG8_MMA(1, 0, At, B0); PG8_MMA(1, 1, At, B1); PG8_BAR; PG8_SCHED;
;         }
;         if constexpr (ALIGN_EPI) { if (wr == 0) PG8_BAR; }
	s_setprio 0
	s_add_i32 s0, s50, s54
	v_lshl_add_u64 v[152:153], v[152:153], 0, s[72:73]
	s_mov_b32 m0, s0
	ds_read_b128 v[188:191], v156 offset:49152
	ds_read_b128 v[192:195], v156 offset:50176
	ds_read_b128 v[196:199], v156 offset:51200
	ds_read_b128 v[200:203], v156 offset:52224
	ds_read_b128 v[204:207], v156 offset:53248
	ds_read_b128 v[208:211], v156 offset:54272
	ds_read_b128 v[212:215], v156 offset:55296
	ds_read_b128 v[216:219], v156 offset:56320
	global_load_lds_dwordx4 v[152:153], off
	s_add_i32 m0, s0, 0x2000
	s_add_u32 s0, s14, 0x30080
	v_lshl_add_u64 v[152:153], v[174:175], 0, s[72:73]
	s_addc_u32 s1, s15, 0
	s_add_i32 s14, s51, s54
	global_load_lds_dwordx4 v[152:153], off
	v_lshl_add_u64 v[152:153], s[0:1], 0, v[136:137]
	s_mov_b32 m0, s14
	s_nop 0
	global_load_lds_dwordx4 v[152:153], off
	v_lshl_add_u64 v[152:153], s[0:1], 0, v[140:141]
	s_add_i32 m0, s14, 0x2000
	s_nop 0
	global_load_lds_dwordx4 v[152:153], off
	v_lshl_add_u64 v[152:153], v[220:221], 0, s[72:73]
	s_mov_b32 m0, s36
	s_nop 0
	global_load_lds_dwordx4 v[152:153], off
	v_lshl_add_u64 v[152:153], v[222:223], 0, s[72:73]
	s_mov_b32 m0, s37
	s_nop 0
	global_load_lds_dwordx4 v[152:153], off
	s_waitcnt vmcnt(8)
	s_waitcnt lgkmcnt(0)
	s_setprio 1
	s_barrier
	v_mfma_f32_16x16x32_bf16 v[94:97], v[130:133], v[188:191], v[94:97]
	v_mfma_f32_16x16x32_bf16 v[90:93], v[158:161], v[188:191], v[90:93]
	v_mfma_f32_16x16x32_bf16 v[86:89], v[130:133], v[196:199], v[86:89]
	v_mfma_f32_16x16x32_bf16 v[82:85], v[158:161], v[196:199], v[82:85]
	v_mfma_f32_16x16x32_bf16 v[78:81], v[130:133], v[204:207], v[78:81]
	v_mfma_f32_16x16x32_bf16 v[74:77], v[158:161], v[204:207], v[74:77]
	v_mfma_f32_16x16x32_bf16 v[70:73], v[130:133], v[212:215], v[70:73]
	v_mfma_f32_16x16x32_bf16 v[66:69], v[158:161], v[212:215], v[66:69]
	v_mfma_f32_16x16x32_bf16 v[94:97], v[148:151], v[192:195], v[94:97]
	v_mfma_f32_16x16x32_bf16 v[90:93], v[162:165], v[192:195], v[90:93]
	v_mfma_f32_16x16x32_bf16 v[86:89], v[148:151], v[200:203], v[86:89]
	v_mfma_f32_16x16x32_bf16 v[82:85], v[162:165], v[200:203], v[82:85]
	v_mfma_f32_16x16x32_bf16 v[78:81], v[148:151], v[208:211], v[78:81]
	v_mfma_f32_16x16x32_bf16 v[74:77], v[162:165], v[208:211], v[74:77]
	v_mfma_f32_16x16x32_bf16 v[70:73], v[148:151], v[216:219], v[70:73]
	v_mfma_f32_16x16x32_bf16 v[66:69], v[162:165], v[216:219], v[66:69]
	v_mfma_f32_16x16x32_bf16 v[30:33], v[166:169], v[188:191], v[30:33]
	v_mfma_f32_16x16x32_bf16 v[26:29], v[180:183], v[188:191], v[26:29]
	v_mfma_f32_16x16x32_bf16 v[22:25], v[166:169], v[196:199], v[22:25]
	v_mfma_f32_16x16x32_bf16 v[18:21], v[180:183], v[196:199], v[18:21]
	v_mfma_f32_16x16x32_bf16 v[14:17], v[166:169], v[204:207], v[14:17]
	v_mfma_f32_16x16x32_bf16 v[10:13], v[180:183], v[204:207], v[10:13]
	v_mfma_f32_16x16x32_bf16 v[6:9], v[166:169], v[212:215], v[6:9]
	v_mfma_f32_16x16x32_bf16 v[2:5], v[180:183], v[212:215], v[2:5]
	v_mfma_f32_16x16x32_bf16 v[30:33], v[170:173], v[192:195], v[30:33]
	v_mfma_f32_16x16x32_bf16 v[26:29], v[184:187], v[192:195], v[26:29]
	v_mfma_f32_16x16x32_bf16 v[22:25], v[170:173], v[200:203], v[22:25]
	v_mfma_f32_16x16x32_bf16 v[18:21], v[184:187], v[200:203], v[18:21]
	v_mfma_f32_16x16x32_bf16 v[14:17], v[170:173], v[208:211], v[14:17]
	v_mfma_f32_16x16x32_bf16 v[10:13], v[184:187], v[208:211], v[10:13]
	v_mfma_f32_16x16x32_bf16 v[6:9], v[170:173], v[216:219], v[6:9]
	v_mfma_f32_16x16x32_bf16 v[2:5], v[184:187], v[216:219], v[2:5]
	s_barrier
	s_setprio 0
	s_add_i32 s49, s49, 2
	s_add_u32 s46, s46, 0x100
	s_addc_u32 s47, s47, 0
	s_cmp_gt_u32 s49, 9
	s_mov_b64 s[0:1], s[2:3]
	s_cbranch_scc0 .LBB0_2551
	v_readlane_b32 s0, v252, 14
	v_readlane_b32 s1, v252, 15
	s_and_b64 vcc, exec, s[0:1]
	s_cbranch_vccz .LBB0_2554
	s_barrier

; #define PG8_STAGE(bufoff, gbase, voff) do { _Pragma("unroll") for (int _i = 0; _i < 2; ++_i) \
;         __builtin_amdgcn_global_load_lds((const unsigned*)((const char*)(gbase) + (voff)[_i]), (LAS unsigned*)(lds + (bufoff) + ldsw + _i * 8192), 16, 0, 0); } while (0)
; #define PG8_LDA(dst, b, h) do { _Pragma("unroll") for (int m = 0; m < 4; ++m) _Pragma("unroll") for (int k = 0; k < 2; ++k) dst[m][k] = *(const LAS bf16x8*)(lds + PG8_SA(b, h) + aoff + m * 2048 + k * 1024); } while (0)
; #define PG8_LDB(dst, b, h) do { _Pragma("unroll") for (int n = 0; n < 2; ++n) _Pragma("unroll") for (int k = 0; k < 2; ++k) dst[n][k] = *(const LAS bf16x8*)(lds + PG8_SB(b, h) + boff + n * 2048 + k * 1024); } while (0)
; #define PG8_MMA(ai, bj, At, Bt) do { __builtin_amdgcn_s_setprio(1); _Pragma("unroll") for (int m = 0; m < 4; ++m) _Pragma("unroll") for (int n = 0; n < 2; ++n) _Pragma("unroll") for (int k = 0; k < 2; ++k) \
;         acc[ai][bj][m][n] = __builtin_amdgcn_mfma_f32_16x16x32_bf16(Bt[n][k], At[m][k], acc[ai][bj][m][n], 0, 0, 0); __builtin_amdgcn_s_setprio(0); } while (0)
; #define PG8_WAIT_V(n) asm volatile("s_waitcnt vmcnt(" #n ")" ::: "memory")
; #define PG8_WAIT_L(n) asm volatile("s_waitcnt lgkmcnt(" #n ")" ::: "memory")
; #define PG8_BAR __builtin_amdgcn_s_barrier()
; #define PG8_SCHED __builtin_amdgcn_sched_barrier(0)
; template <class Epi, class Sched, int LDA, int LDB, bool ALIGN_EPI = true>
; __device__ __forceinline__ void gemm_phase(LAS unsigned char* lds, const Gemm g, const Sched& S, const Epi& E, int wave) {
;     ...
;             const bool last = (t == nt - 2);
;             const char* a1 = cA + (size_t)(t + 1) * kstep;
;             const char* a2 = last ? nA : cA + (size_t)(t + 2) * kstep; const char* b2 = last ? nB : cB + (size_t)(t + 2) * kstep;
;             const char* a3 = a2 + kstep; const char* b3 = b2 + kstep;
;             PG8_LDB(B0, 0, 0); PG8_LDB(B1, 0, 1); PG8_SCHED; PG8_LDA(At, 0, 0); PG8_STAGE(PG8_SA(1, 1), a1 + hstepA, voffA);
;             PG8_WAIT_V(8); PG8_WAIT_L(0); PG8_BAR; PG8_MMA(0, 0, At, B0); PG8_MMA(0, 1, At, B1); PG8_BAR; PG8_SCHED;
;             PG8_LDA(At, 0, 1); PG8_STAGE(PG8_SB(0, 0), b2, voffB); PG8_STAGE(PG8_SB(0, 1), b2 + hstepB, voffB); PG8_STAGE(PG8_SA(0, 0), a2, voffA);
.LBB0_2619:
	ds_read_b128 v[184:187], v151
	ds_read_b128 v[188:191], v151 offset:1024
	ds_read_b128 v[192:195], v151 offset:2048
	ds_read_b128 v[196:199], v151 offset:3072
	ds_read_b128 v[200:203], v151 offset:4096
	ds_read_b128 v[204:207], v151 offset:5120
	ds_read_b128 v[208:211], v151 offset:6144
	ds_read_b128 v[212:215], v151 offset:7168
	s_add_u32 s16, s14, 0xfffe0080
	s_addc_u32 s17, s15, -1
	s_add_i32 s53, 0, 0x10000
	s_cmp_eq_u32 s52, 4
	s_cselect_b32 s19, s7, s17
	s_cselect_b32 s18, s13, s16
	v_add_u32_e32 v0, s53, v150
	s_cselect_b32 s17, s3, s51
	s_cselect_b32 s16, s44, s45
	s_add_i32 s58, 0, 0x14000
	ds_read_b128 v[144:147], v0
	ds_read_b128 v[152:155], v0 offset:1024
	ds_read_b128 v[156:159], v0 offset:2048
	ds_read_b128 v[160:163], v0 offset:3072
	v_add_u32_e32 v0, s58, v150
	ds_read_b128 v[164:167], v0
	ds_read_b128 v[168:171], v0 offset:1024
	ds_read_b128 v[172:175], v0 offset:2048
	ds_read_b128 v[180:183], v0 offset:3072
	v_lshl_add_u64 v[148:149], s[14:15], 0, v[140:141]
	s_add_i32 m0, s36, 0xc000
	s_nop 0
	global_load_lds_dwordx4 v[148:149], off
	v_lshl_add_u64 v[148:149], s[14:15], 0, v[142:143]
	s_add_i32 m0, s36, 0xe000
	s_nop 0
	global_load_lds_dwordx4 v[148:149], off
	s_waitcnt vmcnt(8)
	s_waitcnt lgkmcnt(0)
	s_setprio 1
	s_barrier
	v_mfma_f32_16x16x32_bf16 v[126:129], v[144:147], v[184:187], v[126:129]
	v_mfma_f32_16x16x32_bf16 v[122:125], v[156:159], v[184:187], v[122:125]
	v_mfma_f32_16x16x32_bf16 v[118:121], v[144:147], v[192:195], v[118:121]
	v_mfma_f32_16x16x32_bf16 v[114:117], v[156:159], v[192:195], v[114:117]
	v_mfma_f32_16x16x32_bf16 v[110:113], v[144:147], v[200:203], v[110:113]
	v_mfma_f32_16x16x32_bf16 v[106:109], v[156:159], v[200:203], v[106:109]
	v_mfma_f32_16x16x32_bf16 v[102:105], v[144:147], v[208:211], v[102:105]
	v_mfma_f32_16x16x32_bf16 v[98:101], v[156:159], v[208:211], v[98:101]
	v_mfma_f32_16x16x32_bf16 v[126:129], v[152:155], v[188:191], v[126:129]
	v_mfma_f32_16x16x32_bf16 v[122:125], v[160:163], v[188:191], v[122:125]
	v_mfma_f32_16x16x32_bf16 v[118:121], v[152:155], v[196:199], v[118:121]
	v_mfma_f32_16x16x32_bf16 v[114:117], v[160:163], v[196:199], v[114:117]
	v_mfma_f32_16x16x32_bf16 v[110:113], v[152:155], v[204:207], v[110:113]
	v_mfma_f32_16x16x32_bf16 v[106:109], v[160:163], v[204:207], v[106:109]
	v_mfma_f32_16x16x32_bf16 v[102:105], v[152:155], v[212:215], v[102:105]
	v_mfma_f32_16x16x32_bf16 v[98:101], v[160:163], v[212:215], v[98:101]
	v_mfma_f32_16x16x32_bf16 v[62:65], v[164:167], v[184:187], v[62:65]
	v_mfma_f32_16x16x32_bf16 v[58:61], v[172:175], v[184:187], v[58:61]
	v_mfma_f32_16x16x32_bf16 v[54:57], v[164:167], v[192:195], v[54:57]
	v_mfma_f32_16x16x32_bf16 v[50:53], v[172:175], v[192:195], v[50:53]
	v_mfma_f32_16x16x32_bf16 v[46:49], v[164:167], v[200:203], v[46:49]
	v_mfma_f32_16x16x32_bf16 v[42:45], v[172:175], v[200:203], v[42:45]
	v_mfma_f32_16x16x32_bf16 v[38:41], v[164:167], v[208:211], v[38:41]
	v_mfma_f32_16x16x32_bf16 v[34:37], v[172:175], v[208:211], v[34:37]
	v_mfma_f32_16x16x32_bf16 v[62:65], v[168:171], v[188:191], v[62:65]
	v_mfma_f32_16x16x32_bf16 v[58:61], v[180:183], v[188:191], v[58:61]
	v_mfma_f32_16x16x32_bf16 v[54:57], v[168:171], v[196:199], v[54:57]
	v_mfma_f32_16x16x32_bf16 v[50:53], v[180:183], v[196:199], v[50:53]
	v_mfma_f32_16x16x32_bf16 v[46:49], v[168:171], v[204:207], v[46:49]
	v_mfma_f32_16x16x32_bf16 v[42:45], v[180:183], v[204:207], v[42:45]
	v_mfma_f32_16x16x32_bf16 v[38:41], v[168:171], v[212:215], v[38:41]
	v_mfma_f32_16x16x32_bf16 v[34:37], v[180:183], v[212:215], v[34:37]
	s_barrier
	s_setprio 0
	s_add_i32 s53, s53, s59
	v_lshl_add_u64 v[148:149], s[16:17], 0, v[132:133]
	s_mov_b32 m0, s53
	ds_read_b128 v[184:187], v151 offset:16384
	ds_read_b128 v[188:191], v151 offset:17408
	ds_read_b128 v[192:195], v151 offset:18432
	ds_read_b128 v[196:199], v151 offset:19456
	ds_read_b128 v[200:203], v151 offset:20480
	ds_read_b128 v[204:207], v151 offset:21504
	ds_read_b128 v[208:211], v151 offset:22528
	ds_read_b128 v[212:215], v151 offset:23552
	global_load_lds_dwordx4 v[148:149], off
	s_add_i32 m0, s53, 0x2000
	s_add_u32 s54, s16, 0x20000
	v_lshl_add_u64 v[216:217], s[16:17], 0, v[136:137]
	s_addc_u32 s55, s17, 0
	s_add_i32 s53, s58, s59
	global_load_lds_dwordx4 v[216:217], off
	v_lshl_add_u64 v[218:219], s[54:55], 0, v[132:133]
	s_mov_b32 m0, s53
	v_lshl_add_u64 v[220:221], s[18:19], 0, v[134:135]
	global_load_lds_dwordx4 v[218:219], off
	v_lshl_add_u64 v[218:219], s[54:55], 0, v[136:137]
	s_add_i32 m0, s53, 0x2000
	s_nop 0
	global_load_lds_dwordx4 v[218:219], off
	v_lshl_add_u64 v[218:219], s[18:19], 0, v[130:131]
	s_mov_b32 m0, s36
	s_nop 0
	global_load_lds_dwordx4 v[218:219], off
	s_mov_b32 m0, s37
	s_nop 0
	global_load_lds_dwordx4 v[220:221], off
	s_waitcnt vmcnt(8)
	s_waitcnt lgkmcnt(0)
	s_setprio 1
	s_barrier
; #define PG8_STAGE(bufoff, gbase, voff) do { _Pragma("unroll") for (int _i = 0; _i < 2; ++_i) \
;         __builtin_amdgcn_global_load_lds((const unsigned*)((const char*)(gbase) + (voff)[_i]), (LAS unsigned*)(lds + (bufoff) + ldsw + _i * 8192), 16, 0, 0); } while (0)
; #define PG8_LDA(dst, b, h) do { _Pragma("unroll") for (int m = 0; m < 4; ++m) _Pragma("unroll") for (int k = 0; k < 2; ++k) dst[m][k] = *(const LAS bf16x8*)(lds + PG8_SA(b, h) + aoff + m * 2048 + k * 1024); } while (0)
; #define PG8_LDB(dst, b, h) do { _Pragma("unroll") for (int n = 0; n < 2; ++n) _Pragma("unroll") for (int k = 0; k < 2; ++k) dst[n][k] = *(const LAS bf16x8*)(lds + PG8_SB(b, h) + boff + n * 2048 + k * 1024); } while (0)
; #define PG8_MMA(ai, bj, At, Bt) do { __builtin_amdgcn_s_setprio(1); _Pragma("unroll") for (int m = 0; m < 4; ++m) _Pragma("unroll") for (int n = 0; n < 2; ++n) _Pragma("unroll") for (int k = 0; k < 2; ++k) \
;         acc[ai][bj][m][n] = __builtin_amdgcn_mfma_f32_16x16x32_bf16(Bt[n][k], At[m][k], acc[ai][bj][m][n], 0, 0, 0); __builtin_amdgcn_s_setprio(0); } while (0)
; #define PG8_WAIT_V(n) asm volatile("s_waitcnt vmcnt(" #n ")" ::: "memory")
; #define PG8_WAIT_L(n) asm volatile("s_waitcnt lgkmcnt(" #n ")" ::: "memory")
; #define PG8_BAR __builtin_amdgcn_s_barrier()
; #define PG8_SCHED __builtin_amdgcn_sched_barrier(0)
; template <class Epi, class Sched, int LDA, int LDB, bool ALIGN_EPI = true>
; __device__ __forceinline__ void gemm_phase(LAS unsigned char* lds, const Gemm g, const Sched& S, const Epi& E, int wave) {
;     ...
;             PG8_WAIT_V(8); PG8_WAIT_L(0); PG8_BAR; PG8_MMA(1, 0, At, B0); PG8_MMA(1, 1, At, B1); PG8_BAR; PG8_SCHED;
;             PG8_LDB(B0, 1, 0); PG8_LDB(B1, 1, 1); PG8_SCHED; PG8_LDA(At, 1, 0); PG8_STAGE(PG8_SA(0, 1), a2 + hstepA, voffA);
;             PG8_WAIT_V(8); PG8_WAIT_L(0); PG8_BAR; PG8_MMA(0, 0, At, B0); PG8_MMA(0, 1, At, B1); PG8_BAR; PG8_SCHED;
	v_mfma_f32_16x16x32_bf16 v[94:97], v[144:147], v[184:187], v[94:97]
	v_mfma_f32_16x16x32_bf16 v[90:93], v[156:159], v[184:187], v[90:93]
	v_mfma_f32_16x16x32_bf16 v[86:89], v[144:147], v[192:195], v[86:89]
	v_mfma_f32_16x16x32_bf16 v[82:85], v[156:159], v[192:195], v[82:85]
	v_mfma_f32_16x16x32_bf16 v[78:81], v[144:147], v[200:203], v[78:81]
	v_mfma_f32_16x16x32_bf16 v[74:77], v[156:159], v[200:203], v[74:77]
	v_mfma_f32_16x16x32_bf16 v[70:73], v[144:147], v[208:211], v[70:73]
	v_mfma_f32_16x16x32_bf16 v[66:69], v[156:159], v[208:211], v[66:69]
	v_mfma_f32_16x16x32_bf16 v[94:97], v[152:155], v[188:191], v[94:97]
	v_mfma_f32_16x16x32_bf16 v[90:93], v[160:163], v[188:191], v[90:93]
	v_mfma_f32_16x16x32_bf16 v[86:89], v[152:155], v[196:199], v[86:89]
	v_mfma_f32_16x16x32_bf16 v[82:85], v[160:163], v[196:199], v[82:85]
	v_mfma_f32_16x16x32_bf16 v[78:81], v[152:155], v[204:207], v[78:81]
	v_mfma_f32_16x16x32_bf16 v[74:77], v[160:163], v[204:207], v[74:77]
	v_mfma_f32_16x16x32_bf16 v[70:73], v[152:155], v[212:215], v[70:73]
	v_mfma_f32_16x16x32_bf16 v[66:69], v[160:163], v[212:215], v[66:69]
	v_mfma_f32_16x16x32_bf16 v[30:33], v[164:167], v[184:187], v[30:33]
	v_mfma_f32_16x16x32_bf16 v[26:29], v[172:175], v[184:187], v[26:29]
	v_mfma_f32_16x16x32_bf16 v[22:25], v[164:167], v[192:195], v[22:25]
	v_mfma_f32_16x16x32_bf16 v[18:21], v[172:175], v[192:195], v[18:21]
	v_mfma_f32_16x16x32_bf16 v[14:17], v[164:167], v[200:203], v[14:17]
	v_mfma_f32_16x16x32_bf16 v[10:13], v[172:175], v[200:203], v[10:13]
	v_mfma_f32_16x16x32_bf16 v[6:9], v[164:167], v[208:211], v[6:9]
	v_mfma_f32_16x16x32_bf16 v[2:5], v[172:175], v[208:211], v[2:5]
	v_mfma_f32_16x16x32_bf16 v[30:33], v[168:171], v[188:191], v[30:33]
	v_mfma_f32_16x16x32_bf16 v[26:29], v[180:183], v[188:191], v[26:29]
	v_mfma_f32_16x16x32_bf16 v[22:25], v[168:171], v[196:199], v[22:25]
	v_mfma_f32_16x16x32_bf16 v[18:21], v[180:183], v[196:199], v[18:21]
	v_mfma_f32_16x16x32_bf16 v[14:17], v[168:171], v[204:207], v[14:17]
	v_mfma_f32_16x16x32_bf16 v[10:13], v[180:183], v[204:207], v[10:13]
	v_mfma_f32_16x16x32_bf16 v[6:9], v[168:171], v[212:215], v[6:9]
	v_mfma_f32_16x16x32_bf16 v[2:5], v[180:183], v[212:215], v[2:5]
	s_barrier
	s_setprio 0
	ds_read_b128 v[184:187], v151 offset:32768
	ds_read_b128 v[188:191], v151 offset:33792
	ds_read_b128 v[192:195], v151 offset:34816
	ds_read_b128 v[196:199], v151 offset:35840
	ds_read_b128 v[200:203], v151 offset:36864
	ds_read_b128 v[204:207], v151 offset:37888
	ds_read_b128 v[208:211], v151 offset:38912
	ds_read_b128 v[212:215], v151 offset:39936
	s_add_i32 s53, 0, 0x18000
	v_add_u32_e32 v0, s53, v150
	s_add_i32 s54, 0, 0x1c000
	ds_read_b128 v[144:147], v0
	ds_read_b128 v[152:155], v0 offset:1024
	ds_read_b128 v[156:159], v0 offset:2048
	ds_read_b128 v[160:163], v0 offset:3072
	v_add_u32_e32 v0, s54, v150
	ds_read_b128 v[164:167], v0
	ds_read_b128 v[168:171], v0 offset:1024
	ds_read_b128 v[172:175], v0 offset:2048
	ds_read_b128 v[180:183], v0 offset:3072
	s_add_u32 s18, s18, 0x20000
	s_addc_u32 s19, s19, 0
	s_mov_b32 m0, s38
	v_lshl_add_u64 v[222:223], s[18:19], 0, v[130:131]
	global_load_lds_dwordx4 v[222:223], off
	v_lshl_add_u64 v[222:223], s[18:19], 0, v[134:135]
	s_mov_b32 m0, s39
	s_nop 0
	global_load_lds_dwordx4 v[222:223], off
	s_waitcnt vmcnt(8)
	s_waitcnt lgkmcnt(0)
	s_setprio 1
	s_barrier
	v_mfma_f32_16x16x32_bf16 v[126:129], v[144:147], v[184:187], v[126:129]
	v_mfma_f32_16x16x32_bf16 v[122:125], v[156:159], v[184:187], v[122:125]
	v_mfma_f32_16x16x32_bf16 v[118:121], v[144:147], v[192:195], v[118:121]
	v_mfma_f32_16x16x32_bf16 v[114:117], v[156:159], v[192:195], v[114:117]
	v_mfma_f32_16x16x32_bf16 v[110:113], v[144:147], v[200:203], v[110:113]
	v_mfma_f32_16x16x32_bf16 v[106:109], v[156:159], v[200:203], v[106:109]
	v_mfma_f32_16x16x32_bf16 v[102:105], v[144:147], v[208:211], v[102:105]
	v_mfma_f32_16x16x32_bf16 v[98:101], v[156:159], v[208:211], v[98:101]
	v_mfma_f32_16x16x32_bf16 v[126:129], v[152:155], v[188:191], v[126:129]
	v_mfma_f32_16x16x32_bf16 v[122:125], v[160:163], v[188:191], v[122:125]
	v_mfma_f32_16x16x32_bf16 v[118:121], v[152:155], v[196:199], v[118:121]
	v_mfma_f32_16x16x32_bf16 v[114:117], v[160:163], v[196:199], v[114:117]
	v_mfma_f32_16x16x32_bf16 v[110:113], v[152:155], v[204:207], v[110:113]
	v_mfma_f32_16x16x32_bf16 v[106:109], v[160:163], v[204:207], v[106:109]
	v_mfma_f32_16x16x32_bf16 v[102:105], v[152:155], v[212:215], v[102:105]
	v_mfma_f32_16x16x32_bf16 v[98:101], v[160:163], v[212:215], v[98:101]
	v_mfma_f32_16x16x32_bf16 v[62:65], v[164:167], v[184:187], v[62:65]
	v_mfma_f32_16x16x32_bf16 v[58:61], v[172:175], v[184:187], v[58:61]
	v_mfma_f32_16x16x32_bf16 v[54:57], v[164:167], v[192:195], v[54:57]
	v_mfma_f32_16x16x32_bf16 v[50:53], v[172:175], v[192:195], v[50:53]
	v_mfma_f32_16x16x32_bf16 v[46:49], v[164:167], v[200:203], v[46:49]
	v_mfma_f32_16x16x32_bf16 v[42:45], v[172:175], v[200:203], v[42:45]
	v_mfma_f32_16x16x32_bf16 v[38:41], v[164:167], v[208:211], v[38:41]
	v_mfma_f32_16x16x32_bf16 v[34:37], v[172:175], v[208:211], v[34:37]
	v_mfma_f32_16x16x32_bf16 v[62:65], v[168:171], v[188:191], v[62:65]
	v_mfma_f32_16x16x32_bf16 v[58:61], v[180:183], v[188:191], v[58:61]
	v_mfma_f32_16x16x32_bf16 v[54:57], v[168:171], v[196:199], v[54:57]
	v_mfma_f32_16x16x32_bf16 v[50:53], v[180:183], v[196:199], v[50:53]
	v_mfma_f32_16x16x32_bf16 v[46:49], v[168:171], v[204:207], v[46:49]
	v_mfma_f32_16x16x32_bf16 v[42:45], v[180:183], v[204:207], v[42:45]
	v_mfma_f32_16x16x32_bf16 v[38:41], v[168:171], v[212:215], v[38:41]
	v_mfma_f32_16x16x32_bf16 v[34:37], v[180:183], v[212:215], v[34:37]
	s_barrier
; #define PG8_STAGE(bufoff, gbase, voff) do { _Pragma("unroll") for (int _i = 0; _i < 2; ++_i) \
;         __builtin_amdgcn_global_load_lds((const unsigned*)((const char*)(gbase) + (voff)[_i]), (LAS unsigned*)(lds + (bufoff) + ldsw + _i * 8192), 16, 0, 0); } while (0)
; #define PG8_LDA(dst, b, h) do { _Pragma("unroll") for (int m = 0; m < 4; ++m) _Pragma("unroll") for (int k = 0; k < 2; ++k) dst[m][k] = *(const LAS bf16x8*)(lds + PG8_SA(b, h) + aoff + m * 2048 + k * 1024); } while (0)
; #define PG8_MMA(ai, bj, At, Bt) do { __builtin_amdgcn_s_setprio(1); _Pragma("unroll") for (int m = 0; m < 4; ++m) _Pragma("unroll") for (int n = 0; n < 2; ++n) _Pragma("unroll") for (int k = 0; k < 2; ++k) \
;         acc[ai][bj][m][n] = __builtin_amdgcn_mfma_f32_16x16x32_bf16(Bt[n][k], At[m][k], acc[ai][bj][m][n], 0, 0, 0); __builtin_amdgcn_s_setprio(0); } while (0)
; #define PG8_WAIT_V(n) asm volatile("s_waitcnt vmcnt(" #n ")" ::: "memory")
; #define PG8_WAIT_L(n) asm volatile("s_waitcnt lgkmcnt(" #n ")" ::: "memory")
; #define PG8_BAR __builtin_amdgcn_s_barrier()
; #define PG8_SCHED __builtin_amdgcn_sched_barrier(0)
; template <class Epi, class Sched, int LDA, int LDB, bool ALIGN_EPI = true>
; __device__ __forceinline__ void gemm_phase(LAS unsigned char* lds, const Gemm g, const Sched& S, const Epi& E, int wave) {
;     ...
;             PG8_LDA(At, 1, 1); PG8_STAGE(PG8_SB(1, 0), b3, voffB); PG8_STAGE(PG8_SB(1, 1), b3 + hstepB, voffB); PG8_STAGE(PG8_SA(1, 0), a3, voffA);
;             PG8_WAIT_V(8); PG8_WAIT_L(0); PG8_BAR; PG8_MMA(1, 0, At, B0); PG8_MMA(1, 1, At, B1); PG8_BAR; PG8_SCHED;
;         }
;         if constexpr (ALIGN_EPI) { if (wr == 0) PG8_BAR; }
	s_setprio 0
	s_add_i32 s18, s53, s59
	v_lshl_add_u64 v[148:149], v[148:149], 0, s[70:71]
	s_mov_b32 m0, s18
	ds_read_b128 v[184:187], v151 offset:49152
	ds_read_b128 v[188:191], v151 offset:50176
	ds_read_b128 v[192:195], v151 offset:51200
	ds_read_b128 v[196:199], v151 offset:52224
	ds_read_b128 v[200:203], v151 offset:53248
	ds_read_b128 v[204:207], v151 offset:54272
	ds_read_b128 v[208:211], v151 offset:55296
	ds_read_b128 v[212:215], v151 offset:56320
	global_load_lds_dwordx4 v[148:149], off
	s_add_i32 m0, s18, 0x2000
	s_add_u32 s16, s16, 0x20080
	v_lshl_add_u64 v[148:149], v[216:217], 0, s[70:71]
	s_addc_u32 s17, s17, 0
	s_add_i32 s18, s54, s59
	global_load_lds_dwordx4 v[148:149], off
	v_lshl_add_u64 v[148:149], s[16:17], 0, v[132:133]
	s_mov_b32 m0, s18
	s_nop 0
	global_load_lds_dwordx4 v[148:149], off
	v_lshl_add_u64 v[148:149], s[16:17], 0, v[136:137]
	s_add_i32 m0, s18, 0x2000
	s_nop 0
	global_load_lds_dwordx4 v[148:149], off
	v_lshl_add_u64 v[148:149], v[218:219], 0, s[70:71]
	s_mov_b32 m0, s46
	s_nop 0
	global_load_lds_dwordx4 v[148:149], off
	v_lshl_add_u64 v[148:149], v[220:221], 0, s[70:71]
	s_mov_b32 m0, s47
	s_nop 0
	global_load_lds_dwordx4 v[148:149], off
	s_waitcnt vmcnt(8)
	s_waitcnt lgkmcnt(0)
	s_setprio 1
	s_barrier
	v_mfma_f32_16x16x32_bf16 v[94:97], v[144:147], v[184:187], v[94:97]
	v_mfma_f32_16x16x32_bf16 v[90:93], v[156:159], v[184:187], v[90:93]
	v_mfma_f32_16x16x32_bf16 v[86:89], v[144:147], v[192:195], v[86:89]
	v_mfma_f32_16x16x32_bf16 v[82:85], v[156:159], v[192:195], v[82:85]
	v_mfma_f32_16x16x32_bf16 v[78:81], v[144:147], v[200:203], v[78:81]
	v_mfma_f32_16x16x32_bf16 v[74:77], v[156:159], v[200:203], v[74:77]
	v_mfma_f32_16x16x32_bf16 v[70:73], v[144:147], v[208:211], v[70:73]
	v_mfma_f32_16x16x32_bf16 v[66:69], v[156:159], v[208:211], v[66:69]
	v_mfma_f32_16x16x32_bf16 v[94:97], v[152:155], v[188:191], v[94:97]
	v_mfma_f32_16x16x32_bf16 v[90:93], v[160:163], v[188:191], v[90:93]
	v_mfma_f32_16x16x32_bf16 v[86:89], v[152:155], v[196:199], v[86:89]
	v_mfma_f32_16x16x32_bf16 v[82:85], v[160:163], v[196:199], v[82:85]
	v_mfma_f32_16x16x32_bf16 v[78:81], v[152:155], v[204:207], v[78:81]
	v_mfma_f32_16x16x32_bf16 v[74:77], v[160:163], v[204:207], v[74:77]
	v_mfma_f32_16x16x32_bf16 v[70:73], v[152:155], v[212:215], v[70:73]
	v_mfma_f32_16x16x32_bf16 v[66:69], v[160:163], v[212:215], v[66:69]
	v_mfma_f32_16x16x32_bf16 v[30:33], v[164:167], v[184:187], v[30:33]
	v_mfma_f32_16x16x32_bf16 v[26:29], v[172:175], v[184:187], v[26:29]
	v_mfma_f32_16x16x32_bf16 v[22:25], v[164:167], v[192:195], v[22:25]
	v_mfma_f32_16x16x32_bf16 v[18:21], v[172:175], v[192:195], v[18:21]
	v_mfma_f32_16x16x32_bf16 v[14:17], v[164:167], v[200:203], v[14:17]
	v_mfma_f32_16x16x32_bf16 v[10:13], v[172:175], v[200:203], v[10:13]
	v_mfma_f32_16x16x32_bf16 v[6:9], v[164:167], v[208:211], v[6:9]
	v_mfma_f32_16x16x32_bf16 v[2:5], v[172:175], v[208:211], v[2:5]
	v_mfma_f32_16x16x32_bf16 v[30:33], v[168:171], v[188:191], v[30:33]
	v_mfma_f32_16x16x32_bf16 v[26:29], v[180:183], v[188:191], v[26:29]
	v_mfma_f32_16x16x32_bf16 v[22:25], v[168:171], v[196:199], v[22:25]
	v_mfma_f32_16x16x32_bf16 v[18:21], v[180:183], v[196:199], v[18:21]
	v_mfma_f32_16x16x32_bf16 v[14:17], v[168:171], v[204:207], v[14:17]
	v_mfma_f32_16x16x32_bf16 v[10:13], v[180:183], v[204:207], v[10:13]
	v_mfma_f32_16x16x32_bf16 v[6:9], v[168:171], v[212:215], v[6:9]
	v_mfma_f32_16x16x32_bf16 v[2:5], v[180:183], v[212:215], v[2:5]
	s_barrier
	s_setprio 0
	s_add_i32 s52, s52, 2
	s_add_u32 s14, s14, 0x100
	s_addc_u32 s15, s15, 0
	s_add_u32 s45, s45, 0x100
	s_addc_u32 s51, s51, 0
	s_cmp_gt_u32 s52, 5
	s_cbranch_scc0 .LBB0_2619
	v_readlane_b32 s14, v252, 14
	v_readlane_b32 s15, v252, 15
	s_and_b64 vcc, exec, s[14:15]
	s_cbranch_vccz .LBB0_2622
	s_barrier

; #define PG8_STAGE(bufoff, gbase, voff) do { _Pragma("unroll") for (int _i = 0; _i < 2; ++_i) \
;         __builtin_amdgcn_global_load_lds((const unsigned*)((const char*)(gbase) + (voff)[_i]), (LAS unsigned*)(lds + (bufoff) + ldsw + _i * 8192), 16, 0, 0); } while (0)
; #define PG8_LDA(dst, b, h) do { _Pragma("unroll") for (int m = 0; m < 4; ++m) _Pragma("unroll") for (int k = 0; k < 2; ++k) dst[m][k] = *(const LAS bf16x8*)(lds + PG8_SA(b, h) + aoff + m * 2048 + k * 1024); } while (0)
; #define PG8_LDB(dst, b, h) do { _Pragma("unroll") for (int n = 0; n < 2; ++n) _Pragma("unroll") for (int k = 0; k < 2; ++k) dst[n][k] = *(const LAS bf16x8*)(lds + PG8_SB(b, h) + boff + n * 2048 + k * 1024); } while (0)
; #define PG8_MMA(ai, bj, At, Bt) do { __builtin_amdgcn_s_setprio(1); _Pragma("unroll") for (int m = 0; m < 4; ++m) _Pragma("unroll") for (int n = 0; n < 2; ++n) _Pragma("unroll") for (int k = 0; k < 2; ++k) \
;         acc[ai][bj][m][n] = __builtin_amdgcn_mfma_f32_16x16x32_bf16(Bt[n][k], At[m][k], acc[ai][bj][m][n], 0, 0, 0); __builtin_amdgcn_s_setprio(0); } while (0)
; #define PG8_WAIT_V(n) asm volatile("s_waitcnt vmcnt(" #n ")" ::: "memory")
; #define PG8_WAIT_L(n) asm volatile("s_waitcnt lgkmcnt(" #n ")" ::: "memory")
; #define PG8_BAR __builtin_amdgcn_s_barrier()
; #define PG8_SCHED __builtin_amdgcn_sched_barrier(0)
; template <class Epi, class Sched, int LDA, int LDB, bool ALIGN_EPI = true>
; __device__ __forceinline__ void gemm_phase(LAS unsigned char* lds, const Gemm g, const Sched& S, const Epi& E, int wave) {
;     ...
;             const bool last = (t == nt - 2);
;             const char* a1 = cA + (size_t)(t + 1) * kstep;
;             const char* a2 = last ? nA : cA + (size_t)(t + 2) * kstep; const char* b2 = last ? nB : cB + (size_t)(t + 2) * kstep;
;             const char* a3 = a2 + kstep; const char* b3 = b2 + kstep;
;             PG8_LDB(B0, 0, 0); PG8_LDB(B1, 0, 1); PG8_SCHED; PG8_LDA(At, 0, 0); PG8_STAGE(PG8_SA(1, 1), a1 + hstepA, voffA);
;             PG8_WAIT_V(8); PG8_WAIT_L(0); PG8_BAR; PG8_MMA(0, 0, At, B0); PG8_MMA(0, 1, At, B1); PG8_BAR; PG8_SCHED;
;             PG8_LDA(At, 0, 1); PG8_STAGE(PG8_SB(0, 0), b2, voffB); PG8_STAGE(PG8_SB(0, 1), b2 + hstepB, voffB); PG8_STAGE(PG8_SA(0, 0), a2, voffA);
.LBB0_2649:
	ds_read_b128 v[180:183], v163
	ds_read_b128 v[184:187], v163 offset:1024
	ds_read_b128 v[188:191], v163 offset:2048
	ds_read_b128 v[192:195], v163 offset:3072
	ds_read_b128 v[196:199], v163 offset:4096
	ds_read_b128 v[200:203], v163 offset:5120
	ds_read_b128 v[204:207], v163 offset:6144
	ds_read_b128 v[208:211], v163 offset:7168
	s_add_u32 s18, s16, 0xfffe0080
	s_addc_u32 s19, s17, -1
	s_add_i32 s48, 0, 0x10000
	s_cmp_eq_u32 s47, 4
	s_cselect_b32 s25, s7, s19
	s_cselect_b32 s24, s13, s18
	s_cselect_b32 s19, s3, s46
	s_cselect_b32 s18, s44, s45
	s_add_i32 s50, 0, 0x14000
	v_add_u32_e32 v152, s48, v161
	v_add_u32_e32 v172, s50, v161
	ds_read_b128 v[130:133], v152
	ds_read_b128 v[134:137], v152 offset:1024
	ds_read_b128 v[148:151], v152 offset:2048
	ds_read_b128 v[152:155], v152 offset:3072
	ds_read_b128 v[156:159], v172
	ds_read_b128 v[164:167], v172 offset:1024
	ds_read_b128 v[168:171], v172 offset:2048
	ds_read_b128 v[172:175], v172 offset:3072
	v_lshl_add_u64 v[212:213], s[16:17], 0, v[144:145]
	s_add_i32 m0, s15, 0xc000
	s_nop 0
	global_load_lds_dwordx4 v[212:213], off
	v_lshl_add_u64 v[212:213], s[16:17], 0, v[146:147]
	s_add_i32 m0, s15, 0xe000
	s_nop 0
	global_load_lds_dwordx4 v[212:213], off
	s_waitcnt vmcnt(8)
	s_waitcnt lgkmcnt(0)
	s_setprio 1
	s_barrier
	v_mfma_f32_16x16x32_bf16 v[126:129], v[130:133], v[180:183], v[126:129]
	v_mfma_f32_16x16x32_bf16 v[122:125], v[148:151], v[180:183], v[122:125]
	v_mfma_f32_16x16x32_bf16 v[110:113], v[130:133], v[188:191], v[110:113]
	v_mfma_f32_16x16x32_bf16 v[106:109], v[148:151], v[188:191], v[106:109]
	v_mfma_f32_16x16x32_bf16 v[94:97], v[130:133], v[196:199], v[94:97]
	v_mfma_f32_16x16x32_bf16 v[90:93], v[148:151], v[196:199], v[90:93]
	v_mfma_f32_16x16x32_bf16 v[78:81], v[130:133], v[204:207], v[78:81]
	v_mfma_f32_16x16x32_bf16 v[74:77], v[148:151], v[204:207], v[74:77]
	v_mfma_f32_16x16x32_bf16 v[126:129], v[134:137], v[184:187], v[126:129]
	v_mfma_f32_16x16x32_bf16 v[122:125], v[152:155], v[184:187], v[122:125]
	v_mfma_f32_16x16x32_bf16 v[110:113], v[134:137], v[192:195], v[110:113]
	v_mfma_f32_16x16x32_bf16 v[106:109], v[152:155], v[192:195], v[106:109]
	v_mfma_f32_16x16x32_bf16 v[94:97], v[134:137], v[200:203], v[94:97]
	v_mfma_f32_16x16x32_bf16 v[90:93], v[152:155], v[200:203], v[90:93]
	v_mfma_f32_16x16x32_bf16 v[78:81], v[134:137], v[208:211], v[78:81]
	v_mfma_f32_16x16x32_bf16 v[74:77], v[152:155], v[208:211], v[74:77]
	v_mfma_f32_16x16x32_bf16 v[118:121], v[156:159], v[180:183], v[118:121]
	v_mfma_f32_16x16x32_bf16 v[114:117], v[168:171], v[180:183], v[114:117]
	v_mfma_f32_16x16x32_bf16 v[102:105], v[156:159], v[188:191], v[102:105]
	v_mfma_f32_16x16x32_bf16 v[98:101], v[168:171], v[188:191], v[98:101]
	v_mfma_f32_16x16x32_bf16 v[86:89], v[156:159], v[196:199], v[86:89]
	v_mfma_f32_16x16x32_bf16 v[82:85], v[168:171], v[196:199], v[82:85]
	v_mfma_f32_16x16x32_bf16 v[70:73], v[156:159], v[204:207], v[70:73]
	v_mfma_f32_16x16x32_bf16 v[66:69], v[168:171], v[204:207], v[66:69]
	v_mfma_f32_16x16x32_bf16 v[118:121], v[164:167], v[184:187], v[118:121]
	v_mfma_f32_16x16x32_bf16 v[114:117], v[172:175], v[184:187], v[114:117]
	v_mfma_f32_16x16x32_bf16 v[102:105], v[164:167], v[192:195], v[102:105]
	v_mfma_f32_16x16x32_bf16 v[98:101], v[172:175], v[192:195], v[98:101]
	v_mfma_f32_16x16x32_bf16 v[86:89], v[164:167], v[200:203], v[86:89]
	v_mfma_f32_16x16x32_bf16 v[82:85], v[172:175], v[200:203], v[82:85]
	v_mfma_f32_16x16x32_bf16 v[70:73], v[164:167], v[208:211], v[70:73]
	v_mfma_f32_16x16x32_bf16 v[66:69], v[172:175], v[208:211], v[66:69]
	s_barrier
	s_setprio 0
	s_add_i32 s48, s48, s51
	v_lshl_add_u64 v[212:213], s[18:19], 0, v[0:1]
	s_mov_b32 m0, s48
	ds_read_b128 v[180:183], v163 offset:16384
	ds_read_b128 v[184:187], v163 offset:17408
	ds_read_b128 v[188:191], v163 offset:18432
	ds_read_b128 v[192:195], v163 offset:19456
	ds_read_b128 v[196:199], v163 offset:20480
	ds_read_b128 v[200:203], v163 offset:21504
	ds_read_b128 v[204:207], v163 offset:22528
	ds_read_b128 v[208:211], v163 offset:23552
	global_load_lds_dwordx4 v[212:213], off
	s_add_i32 m0, s48, 0x2000
	s_add_u32 s48, s18, 0x20000
	v_lshl_add_u64 v[214:215], s[18:19], 0, v[142:143]
	s_addc_u32 s49, s19, 0
	s_add_i32 s50, s50, s51
	global_load_lds_dwordx4 v[214:215], off
	v_lshl_add_u64 v[216:217], s[48:49], 0, v[0:1]
	s_mov_b32 m0, s50
	v_lshl_add_u64 v[218:219], s[24:25], 0, v[140:141]
	global_load_lds_dwordx4 v[216:217], off
	v_lshl_add_u64 v[216:217], s[48:49], 0, v[142:143]
	s_add_i32 m0, s50, 0x2000
	s_nop 0
	global_load_lds_dwordx4 v[216:217], off
	v_lshl_add_u64 v[216:217], s[24:25], 0, v[138:139]
	s_mov_b32 m0, s15
	s_nop 0
	global_load_lds_dwordx4 v[216:217], off
	s_mov_b32 m0, s28
	s_nop 0
	global_load_lds_dwordx4 v[218:219], off
	s_waitcnt vmcnt(8)
	s_waitcnt lgkmcnt(0)
	s_setprio 1
	s_barrier
; #define PG8_STAGE(bufoff, gbase, voff) do { _Pragma("unroll") for (int _i = 0; _i < 2; ++_i) \
;         __builtin_amdgcn_global_load_lds((const unsigned*)((const char*)(gbase) + (voff)[_i]), (LAS unsigned*)(lds + (bufoff) + ldsw + _i * 8192), 16, 0, 0); } while (0)
; #define PG8_LDA(dst, b, h) do { _Pragma("unroll") for (int m = 0; m < 4; ++m) _Pragma("unroll") for (int k = 0; k < 2; ++k) dst[m][k] = *(const LAS bf16x8*)(lds + PG8_SA(b, h) + aoff + m * 2048 + k * 1024); } while (0)
; #define PG8_LDB(dst, b, h) do { _Pragma("unroll") for (int n = 0; n < 2; ++n) _Pragma("unroll") for (int k = 0; k < 2; ++k) dst[n][k] = *(const LAS bf16x8*)(lds + PG8_SB(b, h) + boff + n * 2048 + k * 1024); } while (0)
; #define PG8_MMA(ai, bj, At, Bt) do { __builtin_amdgcn_s_setprio(1); _Pragma("unroll") for (int m = 0; m < 4; ++m) _Pragma("unroll") for (int n = 0; n < 2; ++n) _Pragma("unroll") for (int k = 0; k < 2; ++k) \
;         acc[ai][bj][m][n] = __builtin_amdgcn_mfma_f32_16x16x32_bf16(Bt[n][k], At[m][k], acc[ai][bj][m][n], 0, 0, 0); __builtin_amdgcn_s_setprio(0); } while (0)
; #define PG8_WAIT_V(n) asm volatile("s_waitcnt vmcnt(" #n ")" ::: "memory")
; #define PG8_WAIT_L(n) asm volatile("s_waitcnt lgkmcnt(" #n ")" ::: "memory")
; #define PG8_BAR __builtin_amdgcn_s_barrier()
; #define PG8_SCHED __builtin_amdgcn_sched_barrier(0)
; template <class Epi, class Sched, int LDA, int LDB, bool ALIGN_EPI = true>
; __device__ __forceinline__ void gemm_phase(LAS unsigned char* lds, const Gemm g, const Sched& S, const Epi& E, int wave) {
;     ...
;             PG8_WAIT_V(8); PG8_WAIT_L(0); PG8_BAR; PG8_MMA(1, 0, At, B0); PG8_MMA(1, 1, At, B1); PG8_BAR; PG8_SCHED;
;             PG8_LDB(B0, 1, 0); PG8_LDB(B1, 1, 1); PG8_SCHED; PG8_LDA(At, 1, 0); PG8_STAGE(PG8_SA(0, 1), a2 + hstepA, voffA);
;             PG8_WAIT_V(8); PG8_WAIT_L(0); PG8_BAR; PG8_MMA(0, 0, At, B0); PG8_MMA(0, 1, At, B1); PG8_BAR; PG8_SCHED;
	v_mfma_f32_16x16x32_bf16 v[62:65], v[130:133], v[180:183], v[62:65]
	v_mfma_f32_16x16x32_bf16 v[58:61], v[148:151], v[180:183], v[58:61]
	v_mfma_f32_16x16x32_bf16 v[46:49], v[130:133], v[188:191], v[46:49]
	v_mfma_f32_16x16x32_bf16 v[42:45], v[148:151], v[188:191], v[42:45]
	v_mfma_f32_16x16x32_bf16 v[30:33], v[130:133], v[196:199], v[30:33]
	v_mfma_f32_16x16x32_bf16 v[26:29], v[148:151], v[196:199], v[26:29]
	v_mfma_f32_16x16x32_bf16 v[14:17], v[130:133], v[204:207], v[14:17]
	v_mfma_f32_16x16x32_bf16 v[10:13], v[148:151], v[204:207], v[10:13]
	v_mfma_f32_16x16x32_bf16 v[62:65], v[134:137], v[184:187], v[62:65]
	v_mfma_f32_16x16x32_bf16 v[58:61], v[152:155], v[184:187], v[58:61]
	v_mfma_f32_16x16x32_bf16 v[46:49], v[134:137], v[192:195], v[46:49]
	v_mfma_f32_16x16x32_bf16 v[42:45], v[152:155], v[192:195], v[42:45]
	v_mfma_f32_16x16x32_bf16 v[30:33], v[134:137], v[200:203], v[30:33]
	v_mfma_f32_16x16x32_bf16 v[26:29], v[152:155], v[200:203], v[26:29]
	v_mfma_f32_16x16x32_bf16 v[14:17], v[134:137], v[208:211], v[14:17]
	v_mfma_f32_16x16x32_bf16 v[10:13], v[152:155], v[208:211], v[10:13]
	v_mfma_f32_16x16x32_bf16 v[54:57], v[156:159], v[180:183], v[54:57]
	v_mfma_f32_16x16x32_bf16 v[50:53], v[168:171], v[180:183], v[50:53]
	v_mfma_f32_16x16x32_bf16 v[38:41], v[156:159], v[188:191], v[38:41]
	v_mfma_f32_16x16x32_bf16 v[34:37], v[168:171], v[188:191], v[34:37]
	v_mfma_f32_16x16x32_bf16 v[22:25], v[156:159], v[196:199], v[22:25]
	v_mfma_f32_16x16x32_bf16 v[18:21], v[168:171], v[196:199], v[18:21]
	v_mfma_f32_16x16x32_bf16 v[6:9], v[156:159], v[204:207], v[6:9]
	v_mfma_f32_16x16x32_bf16 v[2:5], v[168:171], v[204:207], v[2:5]
	v_mfma_f32_16x16x32_bf16 v[54:57], v[164:167], v[184:187], v[54:57]
	v_mfma_f32_16x16x32_bf16 v[50:53], v[172:175], v[184:187], v[50:53]
	v_mfma_f32_16x16x32_bf16 v[38:41], v[164:167], v[192:195], v[38:41]
	v_mfma_f32_16x16x32_bf16 v[34:37], v[172:175], v[192:195], v[34:37]
	v_mfma_f32_16x16x32_bf16 v[22:25], v[164:167], v[200:203], v[22:25]
	v_mfma_f32_16x16x32_bf16 v[18:21], v[172:175], v[200:203], v[18:21]
	v_mfma_f32_16x16x32_bf16 v[6:9], v[164:167], v[208:211], v[6:9]
	v_mfma_f32_16x16x32_bf16 v[2:5], v[172:175], v[208:211], v[2:5]
	s_barrier
	s_setprio 0
	ds_read_b128 v[180:183], v163 offset:32768
	ds_read_b128 v[184:187], v163 offset:33792
	ds_read_b128 v[188:191], v163 offset:34816
	ds_read_b128 v[192:195], v163 offset:35840
	ds_read_b128 v[196:199], v163 offset:36864
	ds_read_b128 v[200:203], v163 offset:37888
	ds_read_b128 v[204:207], v163 offset:38912
	ds_read_b128 v[208:211], v163 offset:39936
	s_add_i32 s48, 0, 0x18000
	s_add_i32 s49, 0, 0x1c000
	v_add_u32_e32 v152, s48, v161
	v_add_u32_e32 v172, s49, v161
	ds_read_b128 v[130:133], v152
	ds_read_b128 v[134:137], v152 offset:1024
	ds_read_b128 v[148:151], v152 offset:2048
	ds_read_b128 v[152:155], v152 offset:3072
	ds_read_b128 v[156:159], v172
	ds_read_b128 v[164:167], v172 offset:1024
	ds_read_b128 v[168:171], v172 offset:2048
	ds_read_b128 v[172:175], v172 offset:3072
	s_add_u32 s24, s24, 0x20000
	s_addc_u32 s25, s25, 0
	s_mov_b32 m0, s29
	v_lshl_add_u64 v[220:221], s[24:25], 0, v[138:139]
	global_load_lds_dwordx4 v[220:221], off
	v_lshl_add_u64 v[220:221], s[24:25], 0, v[140:141]
	s_mov_b32 m0, s34
	s_nop 0
	global_load_lds_dwordx4 v[220:221], off
	s_waitcnt vmcnt(8)
	s_waitcnt lgkmcnt(0)
	s_setprio 1
	s_barrier
	v_mfma_f32_16x16x32_bf16 v[126:129], v[130:133], v[180:183], v[126:129]
	v_mfma_f32_16x16x32_bf16 v[122:125], v[148:151], v[180:183], v[122:125]
	v_mfma_f32_16x16x32_bf16 v[110:113], v[130:133], v[188:191], v[110:113]
	v_mfma_f32_16x16x32_bf16 v[106:109], v[148:151], v[188:191], v[106:109]
	v_mfma_f32_16x16x32_bf16 v[94:97], v[130:133], v[196:199], v[94:97]
	v_mfma_f32_16x16x32_bf16 v[90:93], v[148:151], v[196:199], v[90:93]
	v_mfma_f32_16x16x32_bf16 v[78:81], v[130:133], v[204:207], v[78:81]
	v_mfma_f32_16x16x32_bf16 v[74:77], v[148:151], v[204:207], v[74:77]
	v_mfma_f32_16x16x32_bf16 v[126:129], v[134:137], v[184:187], v[126:129]
	v_mfma_f32_16x16x32_bf16 v[122:125], v[152:155], v[184:187], v[122:125]
	v_mfma_f32_16x16x32_bf16 v[110:113], v[134:137], v[192:195], v[110:113]
	v_mfma_f32_16x16x32_bf16 v[106:109], v[152:155], v[192:195], v[106:109]
	v_mfma_f32_16x16x32_bf16 v[94:97], v[134:137], v[200:203], v[94:97]
	v_mfma_f32_16x16x32_bf16 v[90:93], v[152:155], v[200:203], v[90:93]
	v_mfma_f32_16x16x32_bf16 v[78:81], v[134:137], v[208:211], v[78:81]
	v_mfma_f32_16x16x32_bf16 v[74:77], v[152:155], v[208:211], v[74:77]
	v_mfma_f32_16x16x32_bf16 v[118:121], v[156:159], v[180:183], v[118:121]
	v_mfma_f32_16x16x32_bf16 v[114:117], v[168:171], v[180:183], v[114:117]
	v_mfma_f32_16x16x32_bf16 v[102:105], v[156:159], v[188:191], v[102:105]
	v_mfma_f32_16x16x32_bf16 v[98:101], v[168:171], v[188:191], v[98:101]
	v_mfma_f32_16x16x32_bf16 v[86:89], v[156:159], v[196:199], v[86:89]
	v_mfma_f32_16x16x32_bf16 v[82:85], v[168:171], v[196:199], v[82:85]
	v_mfma_f32_16x16x32_bf16 v[70:73], v[156:159], v[204:207], v[70:73]
	v_mfma_f32_16x16x32_bf16 v[66:69], v[168:171], v[204:207], v[66:69]
	v_mfma_f32_16x16x32_bf16 v[118:121], v[164:167], v[184:187], v[118:121]
	v_mfma_f32_16x16x32_bf16 v[114:117], v[172:175], v[184:187], v[114:117]
	v_mfma_f32_16x16x32_bf16 v[102:105], v[164:167], v[192:195], v[102:105]
	v_mfma_f32_16x16x32_bf16 v[98:101], v[172:175], v[192:195], v[98:101]
	v_mfma_f32_16x16x32_bf16 v[86:89], v[164:167], v[200:203], v[86:89]
	v_mfma_f32_16x16x32_bf16 v[82:85], v[172:175], v[200:203], v[82:85]
	v_mfma_f32_16x16x32_bf16 v[70:73], v[164:167], v[208:211], v[70:73]
	v_mfma_f32_16x16x32_bf16 v[66:69], v[172:175], v[208:211], v[66:69]
	s_barrier
; #define PG8_STAGE(bufoff, gbase, voff) do { _Pragma("unroll") for (int _i = 0; _i < 2; ++_i) \
;         __builtin_amdgcn_global_load_lds((const unsigned*)((const char*)(gbase) + (voff)[_i]), (LAS unsigned*)(lds + (bufoff) + ldsw + _i * 8192), 16, 0, 0); } while (0)
; #define PG8_LDA(dst, b, h) do { _Pragma("unroll") for (int m = 0; m < 4; ++m) _Pragma("unroll") for (int k = 0; k < 2; ++k) dst[m][k] = *(const LAS bf16x8*)(lds + PG8_SA(b, h) + aoff + m * 2048 + k * 1024); } while (0)
; #define PG8_MMA(ai, bj, At, Bt) do { __builtin_amdgcn_s_setprio(1); _Pragma("unroll") for (int m = 0; m < 4; ++m) _Pragma("unroll") for (int n = 0; n < 2; ++n) _Pragma("unroll") for (int k = 0; k < 2; ++k) \
;         acc[ai][bj][m][n] = __builtin_amdgcn_mfma_f32_16x16x32_bf16(Bt[n][k], At[m][k], acc[ai][bj][m][n], 0, 0, 0); __builtin_amdgcn_s_setprio(0); } while (0)
; #define PG8_WAIT_V(n) asm volatile("s_waitcnt vmcnt(" #n ")" ::: "memory")
; #define PG8_WAIT_L(n) asm volatile("s_waitcnt lgkmcnt(" #n ")" ::: "memory")
; #define PG8_BAR __builtin_amdgcn_s_barrier()
; #define PG8_SCHED __builtin_amdgcn_sched_barrier(0)
; template <class Epi, class Sched, int LDA, int LDB, bool ALIGN_EPI = true>
; __device__ __forceinline__ void gemm_phase(LAS unsigned char* lds, const Gemm g, const Sched& S, const Epi& E, int wave) {
;     ...
;             PG8_LDA(At, 1, 1); PG8_STAGE(PG8_SB(1, 0), b3, voffB); PG8_STAGE(PG8_SB(1, 1), b3 + hstepB, voffB); PG8_STAGE(PG8_SA(1, 0), a3, voffA);
;             PG8_WAIT_V(8); PG8_WAIT_L(0); PG8_BAR; PG8_MMA(1, 0, At, B0); PG8_MMA(1, 1, At, B1); PG8_BAR; PG8_SCHED;
;         }
;         if constexpr (ALIGN_EPI) { if (wr == 0) PG8_BAR; }
	s_setprio 0
	s_add_i32 s24, s48, s51
	v_lshl_add_u64 v[212:213], v[212:213], 0, s[52:53]
	s_mov_b32 m0, s24
	ds_read_b128 v[180:183], v163 offset:49152
	ds_read_b128 v[184:187], v163 offset:50176
	ds_read_b128 v[188:191], v163 offset:51200
	ds_read_b128 v[192:195], v163 offset:52224
	ds_read_b128 v[196:199], v163 offset:53248
	ds_read_b128 v[200:203], v163 offset:54272
	ds_read_b128 v[204:207], v163 offset:55296
	ds_read_b128 v[208:211], v163 offset:56320
	global_load_lds_dwordx4 v[212:213], off
	s_add_i32 m0, s24, 0x2000
	s_add_u32 s18, s18, 0x20080
	v_lshl_add_u64 v[212:213], v[214:215], 0, s[52:53]
	s_addc_u32 s19, s19, 0
	s_add_i32 s24, s49, s51
	global_load_lds_dwordx4 v[212:213], off
	v_lshl_add_u64 v[212:213], s[18:19], 0, v[0:1]
	s_mov_b32 m0, s24
	s_nop 0
	global_load_lds_dwordx4 v[212:213], off
	v_lshl_add_u64 v[212:213], s[18:19], 0, v[142:143]
	s_add_i32 m0, s24, 0x2000
	s_nop 0
	global_load_lds_dwordx4 v[212:213], off
	v_lshl_add_u64 v[212:213], v[216:217], 0, s[52:53]
	s_mov_b32 m0, s35
	s_nop 0
	global_load_lds_dwordx4 v[212:213], off
	v_lshl_add_u64 v[212:213], v[218:219], 0, s[52:53]
	s_mov_b32 m0, s36
	s_nop 0
	global_load_lds_dwordx4 v[212:213], off
	s_waitcnt vmcnt(8)
	s_waitcnt lgkmcnt(0)
	s_setprio 1
	s_barrier
	v_mfma_f32_16x16x32_bf16 v[62:65], v[130:133], v[180:183], v[62:65]
	v_mfma_f32_16x16x32_bf16 v[58:61], v[148:151], v[180:183], v[58:61]
	v_mfma_f32_16x16x32_bf16 v[46:49], v[130:133], v[188:191], v[46:49]
	v_mfma_f32_16x16x32_bf16 v[42:45], v[148:151], v[188:191], v[42:45]
	v_mfma_f32_16x16x32_bf16 v[30:33], v[130:133], v[196:199], v[30:33]
	v_mfma_f32_16x16x32_bf16 v[26:29], v[148:151], v[196:199], v[26:29]
	v_mfma_f32_16x16x32_bf16 v[14:17], v[130:133], v[204:207], v[14:17]
	v_mfma_f32_16x16x32_bf16 v[10:13], v[148:151], v[204:207], v[10:13]
	v_mfma_f32_16x16x32_bf16 v[62:65], v[134:137], v[184:187], v[62:65]
	v_mfma_f32_16x16x32_bf16 v[58:61], v[152:155], v[184:187], v[58:61]
	v_mfma_f32_16x16x32_bf16 v[46:49], v[134:137], v[192:195], v[46:49]
	v_mfma_f32_16x16x32_bf16 v[42:45], v[152:155], v[192:195], v[42:45]
	v_mfma_f32_16x16x32_bf16 v[30:33], v[134:137], v[200:203], v[30:33]
	v_mfma_f32_16x16x32_bf16 v[26:29], v[152:155], v[200:203], v[26:29]
	v_mfma_f32_16x16x32_bf16 v[14:17], v[134:137], v[208:211], v[14:17]
	v_mfma_f32_16x16x32_bf16 v[10:13], v[152:155], v[208:211], v[10:13]
	v_mfma_f32_16x16x32_bf16 v[54:57], v[156:159], v[180:183], v[54:57]
	v_mfma_f32_16x16x32_bf16 v[50:53], v[168:171], v[180:183], v[50:53]
	v_mfma_f32_16x16x32_bf16 v[38:41], v[156:159], v[188:191], v[38:41]
	v_mfma_f32_16x16x32_bf16 v[34:37], v[168:171], v[188:191], v[34:37]
	v_mfma_f32_16x16x32_bf16 v[22:25], v[156:159], v[196:199], v[22:25]
	v_mfma_f32_16x16x32_bf16 v[18:21], v[168:171], v[196:199], v[18:21]
	v_mfma_f32_16x16x32_bf16 v[6:9], v[156:159], v[204:207], v[6:9]
	v_mfma_f32_16x16x32_bf16 v[2:5], v[168:171], v[204:207], v[2:5]
	v_mfma_f32_16x16x32_bf16 v[54:57], v[164:167], v[184:187], v[54:57]
	v_mfma_f32_16x16x32_bf16 v[50:53], v[172:175], v[184:187], v[50:53]
	v_mfma_f32_16x16x32_bf16 v[38:41], v[164:167], v[192:195], v[38:41]
	v_mfma_f32_16x16x32_bf16 v[34:37], v[172:175], v[192:195], v[34:37]
	v_mfma_f32_16x16x32_bf16 v[22:25], v[164:167], v[200:203], v[22:25]
	v_mfma_f32_16x16x32_bf16 v[18:21], v[172:175], v[200:203], v[18:21]
	v_mfma_f32_16x16x32_bf16 v[6:9], v[164:167], v[208:211], v[6:9]
	v_mfma_f32_16x16x32_bf16 v[2:5], v[172:175], v[208:211], v[2:5]
	s_barrier
	s_setprio 0
	s_add_i32 s47, s47, 2
	s_add_u32 s16, s16, 0x100
	s_addc_u32 s17, s17, 0
	s_add_u32 s45, s45, 0x100
	s_addc_u32 s46, s46, 0
	s_cmp_gt_u32 s47, 5
	s_cbranch_scc0 .LBB0_2649
	v_readlane_b32 s16, v252, 14
	v_readlane_b32 s17, v252, 15
	s_and_b64 vcc, exec, s[16:17]
	s_cbranch_vccz .LBB0_2652
	s_barrier

; #define PG8_STAGE(bufoff, gbase, voff) do { _Pragma("unroll") for (int _i = 0; _i < 2; ++_i) \
;         __builtin_amdgcn_global_load_lds((const unsigned*)((const char*)(gbase) + (voff)[_i]), (LAS unsigned*)(lds + (bufoff) + ldsw + _i * 8192), 16, 0, 0); } while (0)
; #define PG8_LDA(dst, b, h) do { _Pragma("unroll") for (int m = 0; m < 4; ++m) _Pragma("unroll") for (int k = 0; k < 2; ++k) dst[m][k] = *(const LAS bf16x8*)(lds + PG8_SA(b, h) + aoff + m * 2048 + k * 1024); } while (0)
; #define PG8_LDB(dst, b, h) do { _Pragma("unroll") for (int n = 0; n < 2; ++n) _Pragma("unroll") for (int k = 0; k < 2; ++k) dst[n][k] = *(const LAS bf16x8*)(lds + PG8_SB(b, h) + boff + n * 2048 + k * 1024); } while (0)
; #define PG8_MMA(ai, bj, At, Bt) do { __builtin_amdgcn_s_setprio(1); _Pragma("unroll") for (int m = 0; m < 4; ++m) _Pragma("unroll") for (int n = 0; n < 2; ++n) _Pragma("unroll") for (int k = 0; k < 2; ++k) \
;         acc[ai][bj][m][n] = __builtin_amdgcn_mfma_f32_16x16x32_bf16(Bt[n][k], At[m][k], acc[ai][bj][m][n], 0, 0, 0); __builtin_amdgcn_s_setprio(0); } while (0)
; #define PG8_WAIT_V(n) asm volatile("s_waitcnt vmcnt(" #n ")" ::: "memory")
; #define PG8_WAIT_L(n) asm volatile("s_waitcnt lgkmcnt(" #n ")" ::: "memory")
; #define PG8_BAR __builtin_amdgcn_s_barrier()
; #define PG8_SCHED __builtin_amdgcn_sched_barrier(0)
; template <class Epi, class Sched, int LDA, int LDB, bool ALIGN_EPI = true>
; __device__ __forceinline__ void gemm_phase(LAS unsigned char* lds, const Gemm g, const Sched& S, const Epi& E, int wave) {
;     ...
;             const bool last = (t == nt - 2);
;             const char* a1 = cA + (size_t)(t + 1) * kstep;
;             const char* a2 = last ? nA : cA + (size_t)(t + 2) * kstep; const char* b2 = last ? nB : cB + (size_t)(t + 2) * kstep;
;             const char* a3 = a2 + kstep; const char* b3 = b2 + kstep;
;             PG8_LDB(B0, 0, 0); PG8_LDB(B1, 0, 1); PG8_SCHED; PG8_LDA(At, 0, 0); PG8_STAGE(PG8_SA(1, 1), a1 + hstepA, voffA);
;             PG8_WAIT_V(8); PG8_WAIT_L(0); PG8_BAR; PG8_MMA(0, 0, At, B0); PG8_MMA(0, 1, At, B1); PG8_BAR; PG8_SCHED;
;             PG8_LDA(At, 0, 1); PG8_STAGE(PG8_SB(0, 0), b2, voffB); PG8_STAGE(PG8_SB(0, 1), b2 + hstepB, voffB); PG8_STAGE(PG8_SA(0, 0), a2, voffA);
.LBB0_4715:
	ds_read_b128 v[184:187], v155
	ds_read_b128 v[188:191], v155 offset:1024
	ds_read_b128 v[192:195], v155 offset:2048
	ds_read_b128 v[196:199], v155 offset:3072
	ds_read_b128 v[200:203], v155 offset:4096
	ds_read_b128 v[204:207], v155 offset:5120
	ds_read_b128 v[208:211], v155 offset:6144
	ds_read_b128 v[212:215], v155 offset:7168
	s_add_i32 s49, s24, 2
	s_add_u32 s25, s18, 0xfff80080
	s_addc_u32 s28, s19, -1
	s_add_i32 s50, 0, 0x10000
	s_cmp_eq_u32 s17, s24
	s_cselect_b32 s29, s1, s28
	s_cselect_b32 s28, s7, s25
	v_add_u32_e32 v0, s50, v153
	s_cselect_b32 s25, s3, s45
	s_cselect_b32 s24, s15, s44
	s_add_i32 s52, 0, 0x14000
	ds_read_b128 v[144:147], v0
	ds_read_b128 v[148:151], v0 offset:1024
	ds_read_b128 v[156:159], v0 offset:2048
	ds_read_b128 v[160:163], v0 offset:3072
	v_add_u32_e32 v0, s52, v153
	ds_read_b128 v[164:167], v0
	ds_read_b128 v[168:171], v0 offset:1024
	ds_read_b128 v[172:175], v0 offset:2048
	ds_read_b128 v[180:183], v0 offset:3072
	v_lshl_add_u64 v[216:217], s[18:19], 0, v[140:141]
	s_add_i32 m0, s27, 0xc000
	s_nop 0
	global_load_lds_dwordx4 v[216:217], off
	v_lshl_add_u64 v[216:217], s[18:19], 0, v[142:143]
	s_add_i32 m0, s27, 0xe000
	s_nop 0
	global_load_lds_dwordx4 v[216:217], off
	s_waitcnt vmcnt(8)
	s_waitcnt lgkmcnt(0)
	s_setprio 1
	s_barrier
	v_mfma_f32_16x16x32_bf16 v[126:129], v[144:147], v[184:187], v[126:129]
	v_mfma_f32_16x16x32_bf16 v[122:125], v[156:159], v[184:187], v[122:125]
	v_mfma_f32_16x16x32_bf16 v[110:113], v[144:147], v[192:195], v[110:113]
	v_mfma_f32_16x16x32_bf16 v[106:109], v[156:159], v[192:195], v[106:109]
	v_mfma_f32_16x16x32_bf16 v[94:97], v[144:147], v[200:203], v[94:97]
	v_mfma_f32_16x16x32_bf16 v[90:93], v[156:159], v[200:203], v[90:93]
	v_mfma_f32_16x16x32_bf16 v[78:81], v[144:147], v[208:211], v[78:81]
	v_mfma_f32_16x16x32_bf16 v[74:77], v[156:159], v[208:211], v[74:77]
	v_mfma_f32_16x16x32_bf16 v[126:129], v[148:151], v[188:191], v[126:129]
	v_mfma_f32_16x16x32_bf16 v[122:125], v[160:163], v[188:191], v[122:125]
	v_mfma_f32_16x16x32_bf16 v[110:113], v[148:151], v[196:199], v[110:113]
	v_mfma_f32_16x16x32_bf16 v[106:109], v[160:163], v[196:199], v[106:109]
	v_mfma_f32_16x16x32_bf16 v[94:97], v[148:151], v[204:207], v[94:97]
	v_mfma_f32_16x16x32_bf16 v[90:93], v[160:163], v[204:207], v[90:93]
	v_mfma_f32_16x16x32_bf16 v[78:81], v[148:151], v[212:215], v[78:81]
	v_mfma_f32_16x16x32_bf16 v[74:77], v[160:163], v[212:215], v[74:77]
	v_mfma_f32_16x16x32_bf16 v[118:121], v[164:167], v[184:187], v[118:121]
	v_mfma_f32_16x16x32_bf16 v[114:117], v[172:175], v[184:187], v[114:117]
	v_mfma_f32_16x16x32_bf16 v[102:105], v[164:167], v[192:195], v[102:105]
	v_mfma_f32_16x16x32_bf16 v[98:101], v[172:175], v[192:195], v[98:101]
	v_mfma_f32_16x16x32_bf16 v[86:89], v[164:167], v[200:203], v[86:89]
	v_mfma_f32_16x16x32_bf16 v[82:85], v[172:175], v[200:203], v[82:85]
	v_mfma_f32_16x16x32_bf16 v[70:73], v[164:167], v[208:211], v[70:73]
	v_mfma_f32_16x16x32_bf16 v[66:69], v[172:175], v[208:211], v[66:69]
	v_mfma_f32_16x16x32_bf16 v[118:121], v[168:171], v[188:191], v[118:121]
	v_mfma_f32_16x16x32_bf16 v[114:117], v[180:183], v[188:191], v[114:117]
	v_mfma_f32_16x16x32_bf16 v[102:105], v[168:171], v[196:199], v[102:105]
	v_mfma_f32_16x16x32_bf16 v[98:101], v[180:183], v[196:199], v[98:101]
	v_mfma_f32_16x16x32_bf16 v[86:89], v[168:171], v[204:207], v[86:89]
	v_mfma_f32_16x16x32_bf16 v[82:85], v[180:183], v[204:207], v[82:85]
	v_mfma_f32_16x16x32_bf16 v[70:73], v[168:171], v[212:215], v[70:73]
	v_mfma_f32_16x16x32_bf16 v[66:69], v[180:183], v[212:215], v[66:69]
	s_barrier
	s_setprio 0
	s_add_i32 s50, s50, s53
	v_lshl_add_u64 v[216:217], s[24:25], 0, v[132:133]
	s_mov_b32 m0, s50
	ds_read_b128 v[184:187], v155 offset:16384
	ds_read_b128 v[188:191], v155 offset:17408
	ds_read_b128 v[192:195], v155 offset:18432
	ds_read_b128 v[196:199], v155 offset:19456
	ds_read_b128 v[200:203], v155 offset:20480
	ds_read_b128 v[204:207], v155 offset:21504
	ds_read_b128 v[208:211], v155 offset:22528
	ds_read_b128 v[212:215], v155 offset:23552
	global_load_lds_dwordx4 v[216:217], off
	s_add_i32 m0, s50, 0x2000
	s_add_u32 s50, s24, 0x80000
	v_lshl_add_u64 v[218:219], s[24:25], 0, v[136:137]
	s_addc_u32 s51, s25, 0
	s_add_i32 s52, s52, s53
	global_load_lds_dwordx4 v[218:219], off
	v_lshl_add_u64 v[220:221], s[50:51], 0, v[132:133]
	s_mov_b32 m0, s52
	v_lshl_add_u64 v[222:223], s[28:29], 0, v[134:135]
	global_load_lds_dwordx4 v[220:221], off
	v_lshl_add_u64 v[220:221], s[50:51], 0, v[136:137]
	s_add_i32 m0, s52, 0x2000
	s_nop 0
	global_load_lds_dwordx4 v[220:221], off
	v_lshl_add_u64 v[220:221], s[28:29], 0, v[130:131]
	s_mov_b32 m0, s27
	s_nop 0
	global_load_lds_dwordx4 v[220:221], off
	s_mov_b32 m0, s34
	s_nop 0
	global_load_lds_dwordx4 v[222:223], off
	s_waitcnt vmcnt(8)
	s_waitcnt lgkmcnt(0)
	s_setprio 1
	s_barrier
; #define PG8_STAGE(bufoff, gbase, voff) do { _Pragma("unroll") for (int _i = 0; _i < 2; ++_i) \
;         __builtin_amdgcn_global_load_lds((const unsigned*)((const char*)(gbase) + (voff)[_i]), (LAS unsigned*)(lds + (bufoff) + ldsw + _i * 8192), 16, 0, 0); } while (0)
; #define PG8_LDA(dst, b, h) do { _Pragma("unroll") for (int m = 0; m < 4; ++m) _Pragma("unroll") for (int k = 0; k < 2; ++k) dst[m][k] = *(const LAS bf16x8*)(lds + PG8_SA(b, h) + aoff + m * 2048 + k * 1024); } while (0)
; #define PG8_LDB(dst, b, h) do { _Pragma("unroll") for (int n = 0; n < 2; ++n) _Pragma("unroll") for (int k = 0; k < 2; ++k) dst[n][k] = *(const LAS bf16x8*)(lds + PG8_SB(b, h) + boff + n * 2048 + k * 1024); } while (0)
; #define PG8_MMA(ai, bj, At, Bt) do { __builtin_amdgcn_s_setprio(1); _Pragma("unroll") for (int m = 0; m < 4; ++m) _Pragma("unroll") for (int n = 0; n < 2; ++n) _Pragma("unroll") for (int k = 0; k < 2; ++k) \
;         acc[ai][bj][m][n] = __builtin_amdgcn_mfma_f32_16x16x32_bf16(Bt[n][k], At[m][k], acc[ai][bj][m][n], 0, 0, 0); __builtin_amdgcn_s_setprio(0); } while (0)
; #define PG8_WAIT_V(n) asm volatile("s_waitcnt vmcnt(" #n ")" ::: "memory")
; #define PG8_WAIT_L(n) asm volatile("s_waitcnt lgkmcnt(" #n ")" ::: "memory")
; #define PG8_BAR __builtin_amdgcn_s_barrier()
; #define PG8_SCHED __builtin_amdgcn_sched_barrier(0)
; template <class Epi, class Sched, int LDA, int LDB, bool ALIGN_EPI = true>
; __device__ __forceinline__ void gemm_phase(LAS unsigned char* lds, const Gemm g, const Sched& S, const Epi& E, int wave) {
;     ...
;             PG8_WAIT_V(8); PG8_WAIT_L(0); PG8_BAR; PG8_MMA(1, 0, At, B0); PG8_MMA(1, 1, At, B1); PG8_BAR; PG8_SCHED;
;             PG8_LDB(B0, 1, 0); PG8_LDB(B1, 1, 1); PG8_SCHED; PG8_LDA(At, 1, 0); PG8_STAGE(PG8_SA(0, 1), a2 + hstepA, voffA);
;             PG8_WAIT_V(8); PG8_WAIT_L(0); PG8_BAR; PG8_MMA(0, 0, At, B0); PG8_MMA(0, 1, At, B1); PG8_BAR; PG8_SCHED;
	v_mfma_f32_16x16x32_bf16 v[62:65], v[144:147], v[184:187], v[62:65]
	v_mfma_f32_16x16x32_bf16 v[58:61], v[156:159], v[184:187], v[58:61]
	v_mfma_f32_16x16x32_bf16 v[46:49], v[144:147], v[192:195], v[46:49]
	v_mfma_f32_16x16x32_bf16 v[42:45], v[156:159], v[192:195], v[42:45]
	v_mfma_f32_16x16x32_bf16 v[30:33], v[144:147], v[200:203], v[30:33]
	v_mfma_f32_16x16x32_bf16 v[26:29], v[156:159], v[200:203], v[26:29]
	v_mfma_f32_16x16x32_bf16 v[14:17], v[144:147], v[208:211], v[14:17]
	v_mfma_f32_16x16x32_bf16 v[10:13], v[156:159], v[208:211], v[10:13]
	v_mfma_f32_16x16x32_bf16 v[62:65], v[148:151], v[188:191], v[62:65]
	v_mfma_f32_16x16x32_bf16 v[58:61], v[160:163], v[188:191], v[58:61]
	v_mfma_f32_16x16x32_bf16 v[46:49], v[148:151], v[196:199], v[46:49]
	v_mfma_f32_16x16x32_bf16 v[42:45], v[160:163], v[196:199], v[42:45]
	v_mfma_f32_16x16x32_bf16 v[30:33], v[148:151], v[204:207], v[30:33]
	v_mfma_f32_16x16x32_bf16 v[26:29], v[160:163], v[204:207], v[26:29]
	v_mfma_f32_16x16x32_bf16 v[14:17], v[148:151], v[212:215], v[14:17]
	v_mfma_f32_16x16x32_bf16 v[10:13], v[160:163], v[212:215], v[10:13]
	v_mfma_f32_16x16x32_bf16 v[54:57], v[164:167], v[184:187], v[54:57]
	v_mfma_f32_16x16x32_bf16 v[50:53], v[172:175], v[184:187], v[50:53]
	v_mfma_f32_16x16x32_bf16 v[38:41], v[164:167], v[192:195], v[38:41]
	v_mfma_f32_16x16x32_bf16 v[34:37], v[172:175], v[192:195], v[34:37]
	v_mfma_f32_16x16x32_bf16 v[22:25], v[164:167], v[200:203], v[22:25]
	v_mfma_f32_16x16x32_bf16 v[18:21], v[172:175], v[200:203], v[18:21]
	v_mfma_f32_16x16x32_bf16 v[6:9], v[164:167], v[208:211], v[6:9]
	v_mfma_f32_16x16x32_bf16 v[2:5], v[172:175], v[208:211], v[2:5]
	v_mfma_f32_16x16x32_bf16 v[54:57], v[168:171], v[188:191], v[54:57]
	v_mfma_f32_16x16x32_bf16 v[50:53], v[180:183], v[188:191], v[50:53]
	v_mfma_f32_16x16x32_bf16 v[38:41], v[168:171], v[196:199], v[38:41]
	v_mfma_f32_16x16x32_bf16 v[34:37], v[180:183], v[196:199], v[34:37]
	v_mfma_f32_16x16x32_bf16 v[22:25], v[168:171], v[204:207], v[22:25]
	v_mfma_f32_16x16x32_bf16 v[18:21], v[180:183], v[204:207], v[18:21]
	v_mfma_f32_16x16x32_bf16 v[6:9], v[168:171], v[212:215], v[6:9]
	v_mfma_f32_16x16x32_bf16 v[2:5], v[180:183], v[212:215], v[2:5]
	s_barrier
	s_setprio 0
	ds_read_b128 v[184:187], v155 offset:32768
	ds_read_b128 v[188:191], v155 offset:33792
	ds_read_b128 v[192:195], v155 offset:34816
	ds_read_b128 v[196:199], v155 offset:35840
	ds_read_b128 v[200:203], v155 offset:36864
	ds_read_b128 v[204:207], v155 offset:37888
	ds_read_b128 v[208:211], v155 offset:38912
	ds_read_b128 v[212:215], v155 offset:39936
	s_add_i32 s50, 0, 0x18000
	v_add_u32_e32 v0, s50, v153
	s_add_i32 s51, 0, 0x1c000
	ds_read_b128 v[144:147], v0
	ds_read_b128 v[148:151], v0 offset:1024
	ds_read_b128 v[156:159], v0 offset:2048
	ds_read_b128 v[160:163], v0 offset:3072
	v_add_u32_e32 v0, s51, v153
	ds_read_b128 v[164:167], v0
	ds_read_b128 v[168:171], v0 offset:1024
	ds_read_b128 v[172:175], v0 offset:2048
	ds_read_b128 v[180:183], v0 offset:3072
	s_add_u32 s28, s28, 0x80000
	s_addc_u32 s29, s29, 0
	s_mov_b32 m0, s35
	v_lshl_add_u64 v[224:225], s[28:29], 0, v[130:131]
	global_load_lds_dwordx4 v[224:225], off
	v_lshl_add_u64 v[224:225], s[28:29], 0, v[134:135]
	s_mov_b32 m0, s36
	s_nop 0
	global_load_lds_dwordx4 v[224:225], off
	s_waitcnt vmcnt(8)
	s_waitcnt lgkmcnt(0)
	s_setprio 1
	s_barrier
	v_mfma_f32_16x16x32_bf16 v[126:129], v[144:147], v[184:187], v[126:129]
	v_mfma_f32_16x16x32_bf16 v[122:125], v[156:159], v[184:187], v[122:125]
	v_mfma_f32_16x16x32_bf16 v[110:113], v[144:147], v[192:195], v[110:113]
	v_mfma_f32_16x16x32_bf16 v[106:109], v[156:159], v[192:195], v[106:109]
	v_mfma_f32_16x16x32_bf16 v[94:97], v[144:147], v[200:203], v[94:97]
	v_mfma_f32_16x16x32_bf16 v[90:93], v[156:159], v[200:203], v[90:93]
	v_mfma_f32_16x16x32_bf16 v[78:81], v[144:147], v[208:211], v[78:81]
	v_mfma_f32_16x16x32_bf16 v[74:77], v[156:159], v[208:211], v[74:77]
	v_mfma_f32_16x16x32_bf16 v[126:129], v[148:151], v[188:191], v[126:129]
	v_mfma_f32_16x16x32_bf16 v[122:125], v[160:163], v[188:191], v[122:125]
	v_mfma_f32_16x16x32_bf16 v[110:113], v[148:151], v[196:199], v[110:113]
	v_mfma_f32_16x16x32_bf16 v[106:109], v[160:163], v[196:199], v[106:109]
	v_mfma_f32_16x16x32_bf16 v[94:97], v[148:151], v[204:207], v[94:97]
	v_mfma_f32_16x16x32_bf16 v[90:93], v[160:163], v[204:207], v[90:93]
	v_mfma_f32_16x16x32_bf16 v[78:81], v[148:151], v[212:215], v[78:81]
	v_mfma_f32_16x16x32_bf16 v[74:77], v[160:163], v[212:215], v[74:77]
	v_mfma_f32_16x16x32_bf16 v[118:121], v[164:167], v[184:187], v[118:121]
	v_mfma_f32_16x16x32_bf16 v[114:117], v[172:175], v[184:187], v[114:117]
	v_mfma_f32_16x16x32_bf16 v[102:105], v[164:167], v[192:195], v[102:105]
	v_mfma_f32_16x16x32_bf16 v[98:101], v[172:175], v[192:195], v[98:101]
	v_mfma_f32_16x16x32_bf16 v[86:89], v[164:167], v[200:203], v[86:89]
	v_mfma_f32_16x16x32_bf16 v[82:85], v[172:175], v[200:203], v[82:85]
	v_mfma_f32_16x16x32_bf16 v[70:73], v[164:167], v[208:211], v[70:73]
	v_mfma_f32_16x16x32_bf16 v[66:69], v[172:175], v[208:211], v[66:69]
	v_mfma_f32_16x16x32_bf16 v[118:121], v[168:171], v[188:191], v[118:121]
	v_mfma_f32_16x16x32_bf16 v[114:117], v[180:183], v[188:191], v[114:117]
	v_mfma_f32_16x16x32_bf16 v[102:105], v[168:171], v[196:199], v[102:105]
	v_mfma_f32_16x16x32_bf16 v[98:101], v[180:183], v[196:199], v[98:101]
	v_mfma_f32_16x16x32_bf16 v[86:89], v[168:171], v[204:207], v[86:89]
	v_mfma_f32_16x16x32_bf16 v[82:85], v[180:183], v[204:207], v[82:85]
	v_mfma_f32_16x16x32_bf16 v[70:73], v[168:171], v[212:215], v[70:73]
	v_mfma_f32_16x16x32_bf16 v[66:69], v[180:183], v[212:215], v[66:69]
	s_barrier
; #define PG8_STAGE(bufoff, gbase, voff) do { _Pragma("unroll") for (int _i = 0; _i < 2; ++_i) \
;         __builtin_amdgcn_global_load_lds((const unsigned*)((const char*)(gbase) + (voff)[_i]), (LAS unsigned*)(lds + (bufoff) + ldsw + _i * 8192), 16, 0, 0); } while (0)
; #define PG8_LDA(dst, b, h) do { _Pragma("unroll") for (int m = 0; m < 4; ++m) _Pragma("unroll") for (int k = 0; k < 2; ++k) dst[m][k] = *(const LAS bf16x8*)(lds + PG8_SA(b, h) + aoff + m * 2048 + k * 1024); } while (0)
; #define PG8_MMA(ai, bj, At, Bt) do { __builtin_amdgcn_s_setprio(1); _Pragma("unroll") for (int m = 0; m < 4; ++m) _Pragma("unroll") for (int n = 0; n < 2; ++n) _Pragma("unroll") for (int k = 0; k < 2; ++k) \
;         acc[ai][bj][m][n] = __builtin_amdgcn_mfma_f32_16x16x32_bf16(Bt[n][k], At[m][k], acc[ai][bj][m][n], 0, 0, 0); __builtin_amdgcn_s_setprio(0); } while (0)
; #define PG8_WAIT_V(n) asm volatile("s_waitcnt vmcnt(" #n ")" ::: "memory")
; #define PG8_WAIT_L(n) asm volatile("s_waitcnt lgkmcnt(" #n ")" ::: "memory")
; #define PG8_BAR __builtin_amdgcn_s_barrier()
; #define PG8_SCHED __builtin_amdgcn_sched_barrier(0)
; template <class Epi, class Sched, int LDA, int LDB, bool ALIGN_EPI = true>
; __device__ __forceinline__ void gemm_phase(LAS unsigned char* lds, const Gemm g, const Sched& S, const Epi& E, int wave) {
;     ...
;             PG8_LDA(At, 1, 1); PG8_STAGE(PG8_SB(1, 0), b3, voffB); PG8_STAGE(PG8_SB(1, 1), b3 + hstepB, voffB); PG8_STAGE(PG8_SA(1, 0), a3, voffA);
;             PG8_WAIT_V(8); PG8_WAIT_L(0); PG8_BAR; PG8_MMA(1, 0, At, B0); PG8_MMA(1, 1, At, B1); PG8_BAR; PG8_SCHED;
;         }
;         if constexpr (ALIGN_EPI) { if (wr == 0) PG8_BAR; }
	s_setprio 0
	s_add_i32 s28, s50, s53
	v_lshl_add_u64 v[216:217], v[216:217], 0, s[54:55]
	s_mov_b32 m0, s28
	ds_read_b128 v[184:187], v155 offset:49152
	ds_read_b128 v[188:191], v155 offset:50176
	ds_read_b128 v[192:195], v155 offset:51200
	ds_read_b128 v[196:199], v155 offset:52224
	ds_read_b128 v[200:203], v155 offset:53248
	ds_read_b128 v[204:207], v155 offset:54272
	ds_read_b128 v[208:211], v155 offset:55296
	ds_read_b128 v[212:215], v155 offset:56320
	global_load_lds_dwordx4 v[216:217], off
	s_add_i32 m0, s28, 0x2000
	s_add_u32 s24, s24, 0x80080
	v_lshl_add_u64 v[216:217], v[218:219], 0, s[54:55]
	s_addc_u32 s25, s25, 0
	s_add_i32 s28, s51, s53
	global_load_lds_dwordx4 v[216:217], off
	v_lshl_add_u64 v[216:217], s[24:25], 0, v[132:133]
	s_mov_b32 m0, s28
	s_nop 0
	global_load_lds_dwordx4 v[216:217], off
	v_lshl_add_u64 v[216:217], s[24:25], 0, v[136:137]
	s_add_i32 m0, s28, 0x2000
	s_nop 0
	global_load_lds_dwordx4 v[216:217], off
	v_lshl_add_u64 v[216:217], v[220:221], 0, s[54:55]
	s_mov_b32 m0, s37
	s_nop 0
	global_load_lds_dwordx4 v[216:217], off
	v_lshl_add_u64 v[216:217], v[222:223], 0, s[54:55]
	s_mov_b32 m0, s38
	s_nop 0
	global_load_lds_dwordx4 v[216:217], off
	s_waitcnt vmcnt(8)
	s_waitcnt lgkmcnt(0)
	s_setprio 1
	s_barrier
	v_mfma_f32_16x16x32_bf16 v[62:65], v[144:147], v[184:187], v[62:65]
	v_mfma_f32_16x16x32_bf16 v[58:61], v[156:159], v[184:187], v[58:61]
	v_mfma_f32_16x16x32_bf16 v[46:49], v[144:147], v[192:195], v[46:49]
	v_mfma_f32_16x16x32_bf16 v[42:45], v[156:159], v[192:195], v[42:45]
	v_mfma_f32_16x16x32_bf16 v[30:33], v[144:147], v[200:203], v[30:33]
	v_mfma_f32_16x16x32_bf16 v[26:29], v[156:159], v[200:203], v[26:29]
	v_mfma_f32_16x16x32_bf16 v[14:17], v[144:147], v[208:211], v[14:17]
	v_mfma_f32_16x16x32_bf16 v[10:13], v[156:159], v[208:211], v[10:13]
	v_mfma_f32_16x16x32_bf16 v[62:65], v[148:151], v[188:191], v[62:65]
	v_mfma_f32_16x16x32_bf16 v[58:61], v[160:163], v[188:191], v[58:61]
	v_mfma_f32_16x16x32_bf16 v[46:49], v[148:151], v[196:199], v[46:49]
	v_mfma_f32_16x16x32_bf16 v[42:45], v[160:163], v[196:199], v[42:45]
	v_mfma_f32_16x16x32_bf16 v[30:33], v[148:151], v[204:207], v[30:33]
	v_mfma_f32_16x16x32_bf16 v[26:29], v[160:163], v[204:207], v[26:29]
	v_mfma_f32_16x16x32_bf16 v[14:17], v[148:151], v[212:215], v[14:17]
	v_mfma_f32_16x16x32_bf16 v[10:13], v[160:163], v[212:215], v[10:13]
	v_mfma_f32_16x16x32_bf16 v[54:57], v[164:167], v[184:187], v[54:57]
	v_mfma_f32_16x16x32_bf16 v[50:53], v[172:175], v[184:187], v[50:53]
	v_mfma_f32_16x16x32_bf16 v[38:41], v[164:167], v[192:195], v[38:41]
	v_mfma_f32_16x16x32_bf16 v[34:37], v[172:175], v[192:195], v[34:37]
	v_mfma_f32_16x16x32_bf16 v[22:25], v[164:167], v[200:203], v[22:25]
	v_mfma_f32_16x16x32_bf16 v[18:21], v[172:175], v[200:203], v[18:21]
	v_mfma_f32_16x16x32_bf16 v[6:9], v[164:167], v[208:211], v[6:9]
	v_mfma_f32_16x16x32_bf16 v[2:5], v[172:175], v[208:211], v[2:5]
	v_mfma_f32_16x16x32_bf16 v[54:57], v[168:171], v[188:191], v[54:57]
	v_mfma_f32_16x16x32_bf16 v[50:53], v[180:183], v[188:191], v[50:53]
	v_mfma_f32_16x16x32_bf16 v[38:41], v[168:171], v[196:199], v[38:41]
	v_mfma_f32_16x16x32_bf16 v[34:37], v[180:183], v[196:199], v[34:37]
	v_mfma_f32_16x16x32_bf16 v[22:25], v[168:171], v[204:207], v[22:25]
	v_mfma_f32_16x16x32_bf16 v[18:21], v[180:183], v[204:207], v[18:21]
	v_mfma_f32_16x16x32_bf16 v[6:9], v[168:171], v[212:215], v[6:9]
	v_mfma_f32_16x16x32_bf16 v[2:5], v[180:183], v[212:215], v[2:5]
	s_barrier
	s_setprio 0
	s_add_u32 s18, s18, 0x100
	s_addc_u32 s19, s19, 0
	s_add_u32 s44, s44, 0x100
	s_addc_u32 s45, s45, 0
	s_cmp_ge_i32 s49, s43
	s_mov_b32 s24, s49
	s_cbranch_scc0 .LBB0_4715
	v_readlane_b32 s18, v252, 14
	v_readlane_b32 s19, v252, 15
	s_and_b64 vcc, exec, s[18:19]
	s_cbranch_vccz .LBB0_4718
	s_barrier

; #define PG8_STAGE(bufoff, gbase, voff) do { _Pragma("unroll") for (int _i = 0; _i < 2; ++_i) \
;         __builtin_amdgcn_global_load_lds((const unsigned*)((const char*)(gbase) + (voff)[_i]), (LAS unsigned*)(lds + (bufoff) + ldsw + _i * 8192), 16, 0, 0); } while (0)
; #define PG8_LDA(dst, b, h) do { _Pragma("unroll") for (int m = 0; m < 4; ++m) _Pragma("unroll") for (int k = 0; k < 2; ++k) dst[m][k] = *(const LAS bf16x8*)(lds + PG8_SA(b, h) + aoff + m * 2048 + k * 1024); } while (0)
; #define PG8_LDB(dst, b, h) do { _Pragma("unroll") for (int n = 0; n < 2; ++n) _Pragma("unroll") for (int k = 0; k < 2; ++k) dst[n][k] = *(const LAS bf16x8*)(lds + PG8_SB(b, h) + boff + n * 2048 + k * 1024); } while (0)
; #define PG8_MMA(ai, bj, At, Bt) do { __builtin_amdgcn_s_setprio(1); _Pragma("unroll") for (int m = 0; m < 4; ++m) _Pragma("unroll") for (int n = 0; n < 2; ++n) _Pragma("unroll") for (int k = 0; k < 2; ++k) \
;         acc[ai][bj][m][n] = __builtin_amdgcn_mfma_f32_16x16x32_bf16(Bt[n][k], At[m][k], acc[ai][bj][m][n], 0, 0, 0); __builtin_amdgcn_s_setprio(0); } while (0)
; #define PG8_WAIT_V(n) asm volatile("s_waitcnt vmcnt(" #n ")" ::: "memory")
; #define PG8_WAIT_L(n) asm volatile("s_waitcnt lgkmcnt(" #n ")" ::: "memory")
; #define PG8_BAR __builtin_amdgcn_s_barrier()
; #define PG8_SCHED __builtin_amdgcn_sched_barrier(0)
; template <class Epi, class Sched, int LDA, int LDB, bool ALIGN_EPI = true>
; __device__ __forceinline__ void gemm_phase(LAS unsigned char* lds, const Gemm g, const Sched& S, const Epi& E, int wave) {
;     ...
;             const bool last = (t == nt - 2);
;             const char* a1 = cA + (size_t)(t + 1) * kstep;
;             const char* a2 = last ? nA : cA + (size_t)(t + 2) * kstep; const char* b2 = last ? nB : cB + (size_t)(t + 2) * kstep;
;             const char* a3 = a2 + kstep; const char* b3 = b2 + kstep;
;             PG8_LDB(B0, 0, 0); PG8_LDB(B1, 0, 1); PG8_SCHED; PG8_LDA(At, 0, 0); PG8_STAGE(PG8_SA(1, 1), a1 + hstepA, voffA);
;             PG8_WAIT_V(8); PG8_WAIT_L(0); PG8_BAR; PG8_MMA(0, 0, At, B0); PG8_MMA(0, 1, At, B1); PG8_BAR; PG8_SCHED;
;             PG8_LDA(At, 0, 1); PG8_STAGE(PG8_SB(0, 0), b2, voffB); PG8_STAGE(PG8_SB(0, 1), b2 + hstepB, voffB); PG8_STAGE(PG8_SA(0, 0), a2, voffA);
.LBB0_4901:
	ds_read_b128 v[172:175], v215
	ds_read_b128 v[180:183], v215 offset:1024
	ds_read_b128 v[184:187], v215 offset:2048
	ds_read_b128 v[188:191], v215 offset:3072
	ds_read_b128 v[192:195], v215 offset:4096
	ds_read_b128 v[196:199], v215 offset:5120
	ds_read_b128 v[200:203], v215 offset:6144
	ds_read_b128 v[204:207], v215 offset:7168
	s_add_i32 s65, s36, 2
	s_add_u32 s37, s34, 0xfff80080
	s_addc_u32 s38, s35, -1
	s_add_i32 s66, 0, 0x10000
	s_cmp_eq_u32 s29, s36
	s_cselect_b32 s39, s9, s38
	s_cselect_b32 s38, s13, s37
	s_cselect_b32 s37, s11, s64
	s_cselect_b32 s36, s25, s59
	s_add_i32 s72, 0, 0x14000
	v_add_u32_e32 v70, s66, v213
	v_add_u32_e32 v168, s72, v213
	ds_read_b128 v[50:53], v70
	ds_read_b128 v[54:57], v70 offset:1024
	ds_read_b128 v[66:69], v70 offset:2048
	ds_read_b128 v[70:73], v70 offset:3072
	ds_read_b128 v[156:159], v168
	ds_read_b128 v[160:163], v168 offset:1024
	ds_read_b128 v[164:167], v168 offset:2048
	ds_read_b128 v[168:171], v168 offset:3072
	v_lshl_add_u64 v[208:209], s[34:35], 0, v[152:153]
	s_add_i32 m0, s27, 0xc000
	s_nop 0
	global_load_lds_dwordx4 v[208:209], off
	v_lshl_add_u64 v[208:209], s[34:35], 0, v[154:155]
	s_add_i32 m0, s27, 0xe000
	s_nop 0
	global_load_lds_dwordx4 v[208:209], off
	s_waitcnt vmcnt(8)
	s_waitcnt lgkmcnt(0)
	s_setprio 1
	s_barrier
	v_mfma_f32_16x16x32_bf16 v[142:145], v[50:53], v[172:175], v[142:145]
	v_mfma_f32_16x16x32_bf16 v[138:141], v[66:69], v[172:175], v[138:141]
	v_mfma_f32_16x16x32_bf16 v[126:129], v[50:53], v[184:187], v[126:129]
	v_mfma_f32_16x16x32_bf16 v[122:125], v[66:69], v[184:187], v[122:125]
	v_mfma_f32_16x16x32_bf16 v[110:113], v[50:53], v[192:195], v[110:113]
	v_mfma_f32_16x16x32_bf16 v[106:109], v[66:69], v[192:195], v[106:109]
	v_mfma_f32_16x16x32_bf16 v[94:97], v[50:53], v[200:203], v[94:97]
	v_mfma_f32_16x16x32_bf16 v[90:93], v[66:69], v[200:203], v[90:93]
	v_mfma_f32_16x16x32_bf16 v[142:145], v[54:57], v[180:183], v[142:145]
	v_mfma_f32_16x16x32_bf16 v[138:141], v[70:73], v[180:183], v[138:141]
	v_mfma_f32_16x16x32_bf16 v[126:129], v[54:57], v[188:191], v[126:129]
	v_mfma_f32_16x16x32_bf16 v[122:125], v[70:73], v[188:191], v[122:125]
	v_mfma_f32_16x16x32_bf16 v[110:113], v[54:57], v[196:199], v[110:113]
	v_mfma_f32_16x16x32_bf16 v[106:109], v[70:73], v[196:199], v[106:109]
	v_mfma_f32_16x16x32_bf16 v[94:97], v[54:57], v[204:207], v[94:97]
	v_mfma_f32_16x16x32_bf16 v[90:93], v[70:73], v[204:207], v[90:93]
	v_mfma_f32_16x16x32_bf16 v[134:137], v[156:159], v[172:175], v[134:137]
	v_mfma_f32_16x16x32_bf16 v[130:133], v[164:167], v[172:175], v[130:133]
	v_mfma_f32_16x16x32_bf16 v[118:121], v[156:159], v[184:187], v[118:121]
	v_mfma_f32_16x16x32_bf16 v[114:117], v[164:167], v[184:187], v[114:117]
	v_mfma_f32_16x16x32_bf16 v[102:105], v[156:159], v[192:195], v[102:105]
	v_mfma_f32_16x16x32_bf16 v[98:101], v[164:167], v[192:195], v[98:101]
	v_mfma_f32_16x16x32_bf16 v[86:89], v[156:159], v[200:203], v[86:89]
	v_mfma_f32_16x16x32_bf16 v[82:85], v[164:167], v[200:203], v[82:85]
	v_mfma_f32_16x16x32_bf16 v[134:137], v[160:163], v[180:183], v[134:137]
	v_mfma_f32_16x16x32_bf16 v[130:133], v[168:171], v[180:183], v[130:133]
	v_mfma_f32_16x16x32_bf16 v[118:121], v[160:163], v[188:191], v[118:121]
	v_mfma_f32_16x16x32_bf16 v[114:117], v[168:171], v[188:191], v[114:117]
	v_mfma_f32_16x16x32_bf16 v[102:105], v[160:163], v[196:199], v[102:105]
	v_mfma_f32_16x16x32_bf16 v[98:101], v[168:171], v[196:199], v[98:101]
	v_mfma_f32_16x16x32_bf16 v[86:89], v[160:163], v[204:207], v[86:89]
	v_mfma_f32_16x16x32_bf16 v[82:85], v[168:171], v[204:207], v[82:85]
	s_barrier
	s_setprio 0
	s_add_i32 s66, s66, s60
	v_lshl_add_u64 v[208:209], s[36:37], 0, v[0:1]
	s_mov_b32 m0, s66
	ds_read_b128 v[172:175], v215 offset:16384
	ds_read_b128 v[180:183], v215 offset:17408
	ds_read_b128 v[184:187], v215 offset:18432
	ds_read_b128 v[188:191], v215 offset:19456
	ds_read_b128 v[192:195], v215 offset:20480
	ds_read_b128 v[196:199], v215 offset:21504
	ds_read_b128 v[200:203], v215 offset:22528
	ds_read_b128 v[204:207], v215 offset:23552
	global_load_lds_dwordx4 v[208:209], off
	s_add_i32 m0, s66, 0x2000
	s_add_u32 s66, s36, 0x80000
	v_lshl_add_u64 v[210:211], s[36:37], 0, v[150:151]
	s_addc_u32 s67, s37, 0
	s_add_i32 s72, s72, s60
	global_load_lds_dwordx4 v[210:211], off
	v_lshl_add_u64 v[216:217], s[66:67], 0, v[0:1]
	s_mov_b32 m0, s72
	v_lshl_add_u64 v[218:219], s[38:39], 0, v[148:149]
	global_load_lds_dwordx4 v[216:217], off
	v_lshl_add_u64 v[216:217], s[66:67], 0, v[150:151]
	s_add_i32 m0, s72, 0x2000
	s_nop 0
	global_load_lds_dwordx4 v[216:217], off
	v_lshl_add_u64 v[216:217], s[38:39], 0, v[146:147]
	s_mov_b32 m0, s27
	s_nop 0
	global_load_lds_dwordx4 v[216:217], off
	s_mov_b32 m0, s44
	s_nop 0
	global_load_lds_dwordx4 v[218:219], off
	s_waitcnt vmcnt(8)
	s_waitcnt lgkmcnt(0)
	s_setprio 1
	s_barrier
; #define PG8_STAGE(bufoff, gbase, voff) do { _Pragma("unroll") for (int _i = 0; _i < 2; ++_i) \
;         __builtin_amdgcn_global_load_lds((const unsigned*)((const char*)(gbase) + (voff)[_i]), (LAS unsigned*)(lds + (bufoff) + ldsw + _i * 8192), 16, 0, 0); } while (0)
; #define PG8_LDA(dst, b, h) do { _Pragma("unroll") for (int m = 0; m < 4; ++m) _Pragma("unroll") for (int k = 0; k < 2; ++k) dst[m][k] = *(const LAS bf16x8*)(lds + PG8_SA(b, h) + aoff + m * 2048 + k * 1024); } while (0)
; #define PG8_LDB(dst, b, h) do { _Pragma("unroll") for (int n = 0; n < 2; ++n) _Pragma("unroll") for (int k = 0; k < 2; ++k) dst[n][k] = *(const LAS bf16x8*)(lds + PG8_SB(b, h) + boff + n * 2048 + k * 1024); } while (0)
; #define PG8_MMA(ai, bj, At, Bt) do { __builtin_amdgcn_s_setprio(1); _Pragma("unroll") for (int m = 0; m < 4; ++m) _Pragma("unroll") for (int n = 0; n < 2; ++n) _Pragma("unroll") for (int k = 0; k < 2; ++k) \
;         acc[ai][bj][m][n] = __builtin_amdgcn_mfma_f32_16x16x32_bf16(Bt[n][k], At[m][k], acc[ai][bj][m][n], 0, 0, 0); __builtin_amdgcn_s_setprio(0); } while (0)
; #define PG8_WAIT_V(n) asm volatile("s_waitcnt vmcnt(" #n ")" ::: "memory")
; #define PG8_WAIT_L(n) asm volatile("s_waitcnt lgkmcnt(" #n ")" ::: "memory")
; #define PG8_BAR __builtin_amdgcn_s_barrier()
; #define PG8_SCHED __builtin_amdgcn_sched_barrier(0)
; template <class Epi, class Sched, int LDA, int LDB, bool ALIGN_EPI = true>
; __device__ __forceinline__ void gemm_phase(LAS unsigned char* lds, const Gemm g, const Sched& S, const Epi& E, int wave) {
;     ...
;             PG8_WAIT_V(8); PG8_WAIT_L(0); PG8_BAR; PG8_MMA(1, 0, At, B0); PG8_MMA(1, 1, At, B1); PG8_BAR; PG8_SCHED;
;             PG8_LDB(B0, 1, 0); PG8_LDB(B1, 1, 1); PG8_SCHED; PG8_LDA(At, 1, 0); PG8_STAGE(PG8_SA(0, 1), a2 + hstepA, voffA);
;             PG8_WAIT_V(8); PG8_WAIT_L(0); PG8_BAR; PG8_MMA(0, 0, At, B0); PG8_MMA(0, 1, At, B1); PG8_BAR; PG8_SCHED;
	v_mfma_f32_16x16x32_bf16 v[78:81], v[50:53], v[172:175], v[78:81]
	v_mfma_f32_16x16x32_bf16 v[74:77], v[66:69], v[172:175], v[74:77]
	v_mfma_f32_16x16x32_bf16 v[46:49], v[50:53], v[184:187], v[46:49]
	v_mfma_f32_16x16x32_bf16 v[42:45], v[66:69], v[184:187], v[42:45]
	v_mfma_f32_16x16x32_bf16 v[30:33], v[50:53], v[192:195], v[30:33]
	v_mfma_f32_16x16x32_bf16 v[26:29], v[66:69], v[192:195], v[26:29]
	v_mfma_f32_16x16x32_bf16 v[14:17], v[50:53], v[200:203], v[14:17]
	v_mfma_f32_16x16x32_bf16 v[10:13], v[66:69], v[200:203], v[10:13]
	v_mfma_f32_16x16x32_bf16 v[78:81], v[54:57], v[180:183], v[78:81]
	v_mfma_f32_16x16x32_bf16 v[74:77], v[70:73], v[180:183], v[74:77]
	v_mfma_f32_16x16x32_bf16 v[46:49], v[54:57], v[188:191], v[46:49]
	v_mfma_f32_16x16x32_bf16 v[42:45], v[70:73], v[188:191], v[42:45]
	v_mfma_f32_16x16x32_bf16 v[30:33], v[54:57], v[196:199], v[30:33]
	v_mfma_f32_16x16x32_bf16 v[26:29], v[70:73], v[196:199], v[26:29]
	v_mfma_f32_16x16x32_bf16 v[14:17], v[54:57], v[204:207], v[14:17]
	v_mfma_f32_16x16x32_bf16 v[10:13], v[70:73], v[204:207], v[10:13]
	v_mfma_f32_16x16x32_bf16 v[38:41], v[156:159], v[184:187], v[38:41]
	v_mfma_f32_16x16x32_bf16 v[34:37], v[164:167], v[184:187], v[34:37]
	v_mfma_f32_16x16x32_bf16 v[22:25], v[156:159], v[192:195], v[22:25]
	v_mfma_f32_16x16x32_bf16 v[18:21], v[164:167], v[192:195], v[18:21]
	v_mfma_f32_16x16x32_bf16 v[6:9], v[156:159], v[200:203], v[6:9]
	v_mfma_f32_16x16x32_bf16 v[2:5], v[164:167], v[200:203], v[2:5]
	v_mfma_f32_16x16x32_bf16 v[50:53], v[156:159], v[172:175], v[62:65]
	v_mfma_f32_16x16x32_bf16 v[54:57], v[164:167], v[172:175], v[58:61]
	v_mfma_f32_16x16x32_bf16 v[38:41], v[160:163], v[188:191], v[38:41]
	v_mfma_f32_16x16x32_bf16 v[34:37], v[168:171], v[188:191], v[34:37]
	v_mfma_f32_16x16x32_bf16 v[22:25], v[160:163], v[196:199], v[22:25]
	v_mfma_f32_16x16x32_bf16 v[18:21], v[168:171], v[196:199], v[18:21]
	v_mfma_f32_16x16x32_bf16 v[6:9], v[160:163], v[204:207], v[6:9]
	v_mfma_f32_16x16x32_bf16 v[2:5], v[168:171], v[204:207], v[2:5]
	v_mfma_f32_16x16x32_bf16 v[50:53], v[160:163], v[180:183], v[50:53]
	v_mfma_f32_16x16x32_bf16 v[54:57], v[168:171], v[180:183], v[54:57]
	s_barrier
	s_setprio 0
	ds_read_b128 v[172:175], v215 offset:32768
	ds_read_b128 v[180:183], v215 offset:33792
	ds_read_b128 v[184:187], v215 offset:34816
	ds_read_b128 v[188:191], v215 offset:35840
	ds_read_b128 v[192:195], v215 offset:36864
	ds_read_b128 v[196:199], v215 offset:37888
	ds_read_b128 v[200:203], v215 offset:38912
	ds_read_b128 v[204:207], v215 offset:39936
	s_add_i32 s66, 0, 0x18000
	s_add_i32 s67, 0, 0x1c000
	v_add_u32_e32 v70, s66, v213
	v_add_u32_e32 v168, s67, v213
	ds_read_b128 v[58:61], v70
	ds_read_b128 v[62:65], v70 offset:1024
	ds_read_b128 v[66:69], v70 offset:2048
	ds_read_b128 v[70:73], v70 offset:3072
	ds_read_b128 v[156:159], v168
	ds_read_b128 v[160:163], v168 offset:1024
	ds_read_b128 v[164:167], v168 offset:2048
	ds_read_b128 v[168:171], v168 offset:3072
	s_add_u32 s38, s38, 0x80000
	s_addc_u32 s39, s39, 0
	s_mov_b32 m0, s45
	v_lshl_add_u64 v[220:221], s[38:39], 0, v[146:147]
	global_load_lds_dwordx4 v[220:221], off
	v_lshl_add_u64 v[220:221], s[38:39], 0, v[148:149]
	s_mov_b32 m0, s46
	s_nop 0
	global_load_lds_dwordx4 v[220:221], off
	s_waitcnt vmcnt(8)
	s_waitcnt lgkmcnt(0)
	s_setprio 1
	s_barrier
	v_mfma_f32_16x16x32_bf16 v[142:145], v[58:61], v[172:175], v[142:145]
	v_mfma_f32_16x16x32_bf16 v[138:141], v[66:69], v[172:175], v[138:141]
	v_mfma_f32_16x16x32_bf16 v[126:129], v[58:61], v[184:187], v[126:129]
	v_mfma_f32_16x16x32_bf16 v[122:125], v[66:69], v[184:187], v[122:125]
	v_mfma_f32_16x16x32_bf16 v[110:113], v[58:61], v[192:195], v[110:113]
	v_mfma_f32_16x16x32_bf16 v[106:109], v[66:69], v[192:195], v[106:109]
	v_mfma_f32_16x16x32_bf16 v[94:97], v[58:61], v[200:203], v[94:97]
	v_mfma_f32_16x16x32_bf16 v[90:93], v[66:69], v[200:203], v[90:93]
	v_mfma_f32_16x16x32_bf16 v[142:145], v[62:65], v[180:183], v[142:145]
	v_mfma_f32_16x16x32_bf16 v[138:141], v[70:73], v[180:183], v[138:141]
	v_mfma_f32_16x16x32_bf16 v[126:129], v[62:65], v[188:191], v[126:129]
	v_mfma_f32_16x16x32_bf16 v[122:125], v[70:73], v[188:191], v[122:125]
	v_mfma_f32_16x16x32_bf16 v[110:113], v[62:65], v[196:199], v[110:113]
	v_mfma_f32_16x16x32_bf16 v[106:109], v[70:73], v[196:199], v[106:109]
	v_mfma_f32_16x16x32_bf16 v[94:97], v[62:65], v[204:207], v[94:97]
	v_mfma_f32_16x16x32_bf16 v[90:93], v[70:73], v[204:207], v[90:93]
	v_mfma_f32_16x16x32_bf16 v[134:137], v[156:159], v[172:175], v[134:137]
	v_mfma_f32_16x16x32_bf16 v[130:133], v[164:167], v[172:175], v[130:133]
	v_mfma_f32_16x16x32_bf16 v[118:121], v[156:159], v[184:187], v[118:121]
	v_mfma_f32_16x16x32_bf16 v[114:117], v[164:167], v[184:187], v[114:117]
	v_mfma_f32_16x16x32_bf16 v[102:105], v[156:159], v[192:195], v[102:105]
	v_mfma_f32_16x16x32_bf16 v[98:101], v[164:167], v[192:195], v[98:101]
	v_mfma_f32_16x16x32_bf16 v[86:89], v[156:159], v[200:203], v[86:89]
	v_mfma_f32_16x16x32_bf16 v[82:85], v[164:167], v[200:203], v[82:85]
	v_mfma_f32_16x16x32_bf16 v[134:137], v[160:163], v[180:183], v[134:137]
	v_mfma_f32_16x16x32_bf16 v[130:133], v[168:171], v[180:183], v[130:133]
	v_mfma_f32_16x16x32_bf16 v[118:121], v[160:163], v[188:191], v[118:121]
	v_mfma_f32_16x16x32_bf16 v[114:117], v[168:171], v[188:191], v[114:117]
	v_mfma_f32_16x16x32_bf16 v[102:105], v[160:163], v[196:199], v[102:105]
	v_mfma_f32_16x16x32_bf16 v[98:101], v[168:171], v[196:199], v[98:101]
	v_mfma_f32_16x16x32_bf16 v[86:89], v[160:163], v[204:207], v[86:89]
	v_mfma_f32_16x16x32_bf16 v[82:85], v[168:171], v[204:207], v[82:85]
	s_barrier
; #define PG8_STAGE(bufoff, gbase, voff) do { _Pragma("unroll") for (int _i = 0; _i < 2; ++_i) \
;         __builtin_amdgcn_global_load_lds((const unsigned*)((const char*)(gbase) + (voff)[_i]), (LAS unsigned*)(lds + (bufoff) + ldsw + _i * 8192), 16, 0, 0); } while (0)
; #define PG8_LDA(dst, b, h) do { _Pragma("unroll") for (int m = 0; m < 4; ++m) _Pragma("unroll") for (int k = 0; k < 2; ++k) dst[m][k] = *(const LAS bf16x8*)(lds + PG8_SA(b, h) + aoff + m * 2048 + k * 1024); } while (0)
; #define PG8_MMA(ai, bj, At, Bt) do { __builtin_amdgcn_s_setprio(1); _Pragma("unroll") for (int m = 0; m < 4; ++m) _Pragma("unroll") for (int n = 0; n < 2; ++n) _Pragma("unroll") for (int k = 0; k < 2; ++k) \
;         acc[ai][bj][m][n] = __builtin_amdgcn_mfma_f32_16x16x32_bf16(Bt[n][k], At[m][k], acc[ai][bj][m][n], 0, 0, 0); __builtin_amdgcn_s_setprio(0); } while (0)
; #define PG8_WAIT_V(n) asm volatile("s_waitcnt vmcnt(" #n ")" ::: "memory")
; #define PG8_WAIT_L(n) asm volatile("s_waitcnt lgkmcnt(" #n ")" ::: "memory")
; #define PG8_BAR __builtin_amdgcn_s_barrier()
; #define PG8_SCHED __builtin_amdgcn_sched_barrier(0)
; template <class Epi, class Sched, int LDA, int LDB, bool ALIGN_EPI = true>
; __device__ __forceinline__ void gemm_phase(LAS unsigned char* lds, const Gemm g, const Sched& S, const Epi& E, int wave) {
;     ...
;             PG8_LDA(At, 1, 1); PG8_STAGE(PG8_SB(1, 0), b3, voffB); PG8_STAGE(PG8_SB(1, 1), b3 + hstepB, voffB); PG8_STAGE(PG8_SA(1, 0), a3, voffA);
;             PG8_WAIT_V(8); PG8_WAIT_L(0); PG8_BAR; PG8_MMA(1, 0, At, B0); PG8_MMA(1, 1, At, B1); PG8_BAR; PG8_SCHED;
;         }
;         if constexpr (ALIGN_EPI) { if (wr == 0) PG8_BAR; }
	s_setprio 0
	s_add_i32 s38, s66, s60
	v_lshl_add_u64 v[208:209], v[208:209], 0, s[70:71]
	s_mov_b32 m0, s38
	ds_read_b128 v[172:175], v215 offset:49152
	ds_read_b128 v[180:183], v215 offset:50176
	ds_read_b128 v[184:187], v215 offset:51200
	ds_read_b128 v[188:191], v215 offset:52224
	ds_read_b128 v[192:195], v215 offset:53248
	ds_read_b128 v[196:199], v215 offset:54272
	ds_read_b128 v[200:203], v215 offset:55296
	ds_read_b128 v[204:207], v215 offset:56320
	global_load_lds_dwordx4 v[208:209], off
	s_add_i32 m0, s38, 0x2000
	s_add_u32 s36, s36, 0x80080
	v_lshl_add_u64 v[208:209], v[210:211], 0, s[70:71]
	s_addc_u32 s37, s37, 0
	s_add_i32 s38, s67, s60
	global_load_lds_dwordx4 v[208:209], off
	v_lshl_add_u64 v[208:209], s[36:37], 0, v[0:1]
	s_mov_b32 m0, s38
	s_nop 0
	global_load_lds_dwordx4 v[208:209], off
	v_lshl_add_u64 v[208:209], s[36:37], 0, v[150:151]
	s_add_i32 m0, s38, 0x2000
	s_nop 0
	global_load_lds_dwordx4 v[208:209], off
	v_lshl_add_u64 v[208:209], v[216:217], 0, s[70:71]
	s_mov_b32 m0, s51
	s_nop 0
	global_load_lds_dwordx4 v[208:209], off
	v_lshl_add_u64 v[208:209], v[218:219], 0, s[70:71]
	s_mov_b32 m0, s52
	s_nop 0
	global_load_lds_dwordx4 v[208:209], off
	s_waitcnt vmcnt(8)
	s_waitcnt lgkmcnt(0)
	s_setprio 1
	s_barrier
	v_mfma_f32_16x16x32_bf16 v[78:81], v[58:61], v[172:175], v[78:81]
	v_mfma_f32_16x16x32_bf16 v[74:77], v[66:69], v[172:175], v[74:77]
	v_mfma_f32_16x16x32_bf16 v[46:49], v[58:61], v[184:187], v[46:49]
	v_mfma_f32_16x16x32_bf16 v[42:45], v[66:69], v[184:187], v[42:45]
	v_mfma_f32_16x16x32_bf16 v[30:33], v[58:61], v[192:195], v[30:33]
	v_mfma_f32_16x16x32_bf16 v[26:29], v[66:69], v[192:195], v[26:29]
	v_mfma_f32_16x16x32_bf16 v[14:17], v[58:61], v[200:203], v[14:17]
	v_mfma_f32_16x16x32_bf16 v[10:13], v[66:69], v[200:203], v[10:13]
	v_mfma_f32_16x16x32_bf16 v[78:81], v[62:65], v[180:183], v[78:81]
	v_mfma_f32_16x16x32_bf16 v[74:77], v[70:73], v[180:183], v[74:77]
	v_mfma_f32_16x16x32_bf16 v[46:49], v[62:65], v[188:191], v[46:49]
	v_mfma_f32_16x16x32_bf16 v[42:45], v[70:73], v[188:191], v[42:45]
	v_mfma_f32_16x16x32_bf16 v[30:33], v[62:65], v[196:199], v[30:33]
	v_mfma_f32_16x16x32_bf16 v[26:29], v[70:73], v[196:199], v[26:29]
	v_mfma_f32_16x16x32_bf16 v[14:17], v[62:65], v[204:207], v[14:17]
	v_mfma_f32_16x16x32_bf16 v[10:13], v[70:73], v[204:207], v[10:13]
	v_mfma_f32_16x16x32_bf16 v[50:53], v[156:159], v[172:175], v[50:53]
	v_mfma_f32_16x16x32_bf16 v[62:65], v[160:163], v[180:183], v[50:53]
	v_mfma_f32_16x16x32_bf16 v[50:53], v[164:167], v[172:175], v[54:57]
	v_mfma_f32_16x16x32_bf16 v[38:41], v[156:159], v[184:187], v[38:41]
	v_mfma_f32_16x16x32_bf16 v[34:37], v[164:167], v[184:187], v[34:37]
	v_mfma_f32_16x16x32_bf16 v[22:25], v[156:159], v[192:195], v[22:25]
	v_mfma_f32_16x16x32_bf16 v[18:21], v[164:167], v[192:195], v[18:21]
	v_mfma_f32_16x16x32_bf16 v[6:9], v[156:159], v[200:203], v[6:9]
	v_mfma_f32_16x16x32_bf16 v[2:5], v[164:167], v[200:203], v[2:5]
	v_mfma_f32_16x16x32_bf16 v[58:61], v[168:171], v[180:183], v[50:53]
	v_mfma_f32_16x16x32_bf16 v[38:41], v[160:163], v[188:191], v[38:41]
	v_mfma_f32_16x16x32_bf16 v[34:37], v[168:171], v[188:191], v[34:37]
	v_mfma_f32_16x16x32_bf16 v[22:25], v[160:163], v[196:199], v[22:25]
	v_mfma_f32_16x16x32_bf16 v[18:21], v[168:171], v[196:199], v[18:21]
	v_mfma_f32_16x16x32_bf16 v[6:9], v[160:163], v[204:207], v[6:9]
	v_mfma_f32_16x16x32_bf16 v[2:5], v[168:171], v[204:207], v[2:5]
	s_barrier
	s_setprio 0
	s_add_u32 s34, s34, 0x100
	s_addc_u32 s35, s35, 0
	s_add_u32 s59, s59, 0x100
	s_addc_u32 s64, s64, 0
	s_cmp_ge_i32 s65, s43
	s_mov_b32 s36, s65
	s_cbranch_scc0 .LBB0_4901
	v_readlane_b32 s34, v252, 14
	v_readlane_b32 s35, v252, 15
	s_and_b64 vcc, exec, s[34:35]
	s_cbranch_vccz .LBB0_4904
	s_barrier
